# write-through (sc1) stores for P0 / P3 outputs (on top of XCD-local seams + epilogue rewrites)
# baseline (speedup 1.0000x reference)
.LBB0_46:
	s_cmpk_gt_i32 s49, 0x5ff
	s_mov_b64 s[10:11], -1
	s_cbranch_scc0 .LBB0_48
	s_lshl_b32 s0, s49, 1
	s_addk_i32 s0, 0xf400
	s_lshl_b32 s10, s27, 6
	s_andn2_b32 s0, s0, 63
	s_and_b32 s10, s10, 0xfffff800
	s_sub_i32 s10, s20, s10
	s_lshl_b64 s[50:51], s[0:1], 13
	s_add_u32 s21, s18, s50
	s_addc_u32 s52, s19, s51
	s_ashr_i32 s11, s10, 31
	s_lshl_b64 s[50:51], s[10:11], 2
	s_add_u32 s50, s21, s50
	s_addc_u32 s51, s52, s51
	v_lshl_add_u64 v[100:101], s[50:51], 0, v[0:1]
	v_mov_b32_e32 v3, v1
	v_mov_b32_e32 v5, v1
	v_lshl_add_u64 v[102:103], v[100:101], 0, v[2:3]
	v_lshl_add_u64 v[44:45], v[100:101], 0, v[4:5]
	global_load_dwordx4 v[40:43], v[102:103], off nt
	s_nop 0
	global_load_dwordx4 v[44:47], v[44:45], off nt
	v_add_co_u32_e32 v48, vcc, s28, v102
	v_mov_b32_e32 v7, v1
	s_nop 0
	v_addc_co_u32_e32 v49, vcc, 0, v103, vcc
	v_lshl_add_u64 v[52:53], v[100:101], 0, v[6:7]
	global_load_dwordx4 v[48:51], v[48:49], off nt
	s_nop 0
	global_load_dwordx4 v[52:55], v[52:53], off nt
	v_add_co_u32_e32 v56, vcc, s29, v102
	v_mov_b32_e32 v9, v1
	s_nop 0
	v_addc_co_u32_e32 v57, vcc, 0, v103, vcc
	v_lshl_add_u64 v[60:61], v[100:101], 0, v[8:9]
	global_load_dwordx4 v[56:59], v[56:57], off nt
	s_nop 0
	global_load_dwordx4 v[60:63], v[60:61], off nt
	v_add_co_u32_e32 v68, vcc, s30, v102
	v_mov_b32_e32 v11, v1
	s_nop 0
	v_addc_co_u32_e32 v69, vcc, 0, v103, vcc
	v_lshl_add_u64 v[72:73], v[100:101], 0, v[10:11]
	global_load_dwordx4 v[68:71], v[68:69], off nt
	s_nop 0
	global_load_dwordx4 v[72:75], v[72:73], off nt
	v_add_co_u32_e32 v76, vcc, s31, v102
	v_mov_b32_e32 v13, v1
	s_nop 0
	v_addc_co_u32_e32 v77, vcc, 0, v103, vcc
	v_lshl_add_u64 v[80:81], v[100:101], 0, v[12:13]
	global_load_dwordx4 v[76:79], v[76:77], off nt
	s_nop 0
	global_load_dwordx4 v[80:83], v[80:81], off nt
	v_add_co_u32_e32 v84, vcc, s33, v102
	v_mov_b32_e32 v15, v1
	s_nop 0
	v_addc_co_u32_e32 v85, vcc, 0, v103, vcc
	v_lshl_add_u64 v[88:89], v[100:101], 0, v[14:15]
	global_load_dwordx4 v[84:87], v[84:85], off nt
	s_nop 0
	global_load_dwordx4 v[88:91], v[88:89], off nt
	v_add_co_u32_e32 v92, vcc, s34, v102
	v_mov_b32_e32 v17, v1
	s_nop 0
	v_addc_co_u32_e32 v93, vcc, 0, v103, vcc
	v_lshl_add_u64 v[96:97], v[100:101], 0, v[16:17]
	global_load_dwordx4 v[92:95], v[92:93], off nt
	s_nop 0
	global_load_dwordx4 v[96:99], v[96:97], off nt
	v_add_co_u32_e32 v102, vcc, s35, v102
	v_mov_b32_e32 v19, v1
	s_nop 0
	v_addc_co_u32_e32 v103, vcc, 0, v103, vcc
	v_lshl_add_u64 v[104:105], v[100:101], 0, v[18:19]
	global_load_dwordx4 v[100:103], v[102:103], off nt
	s_nop 0
	global_load_dwordx4 v[104:107], v[104:105], off nt
	v_mov_b32_e32 v3, v38
	s_lshl_b64 s[50:51], s[0:1], 1
	v_lshlrev_b32_e32 v5, 9, v3
	v_ashrrev_i32_e32 v7, 2, v3
	v_lshlrev_b32_e32 v9, 4, v3
	v_and_b32_e32 v5, 0x1e00, v5
	v_and_b32_e32 v7, -4, v7
	v_and_b32_e32 v108, 0x70, v9
	v_add3_u32 v5, s25, v5, v7
	v_add_u32_e32 v7, v5, v108
	v_xad_u32 v9, v108, 16, v5
	s_add_u32 s50, s42, s50
	s_addc_u32 s51, s43, s51
	v_mov_b32_e32 v109, v1
	s_waitcnt vmcnt(14)
	v_cvt_pk_bf16_f32 v11, v40, v44
	ds_write_b32 v7, v11
	v_cvt_pk_bf16_f32 v11, v41, v45
	ds_write_b32 v7, v11 offset:128
	v_cvt_pk_bf16_f32 v11, v42, v46
	ds_write_b32 v7, v11 offset:256
	v_cvt_pk_bf16_f32 v11, v43, v47
	ds_write_b32 v7, v11 offset:384
	s_waitcnt vmcnt(12)
	v_cvt_pk_bf16_f32 v7, v48, v52
	ds_write_b32 v9, v7
	v_cvt_pk_bf16_f32 v7, v49, v53
	ds_write_b32 v9, v7 offset:128
	v_cvt_pk_bf16_f32 v7, v50, v54
	ds_write_b32 v9, v7 offset:256
	v_cvt_pk_bf16_f32 v7, v51, v55
	ds_write_b32 v9, v7 offset:384
	v_xad_u32 v7, v108, 32, v5
	s_waitcnt vmcnt(10)
	v_cvt_pk_bf16_f32 v9, v56, v60
	ds_write_b32 v7, v9
	v_cvt_pk_bf16_f32 v9, v57, v61
	ds_write_b32 v7, v9 offset:128
	v_cvt_pk_bf16_f32 v9, v58, v62
	ds_write_b32 v7, v9 offset:256
	v_cvt_pk_bf16_f32 v9, v59, v63
	ds_write_b32 v7, v9 offset:384
	v_xad_u32 v7, v108, 48, v5
	s_waitcnt vmcnt(8)
	v_cvt_pk_bf16_f32 v9, v68, v72
	ds_write_b32 v7, v9
	v_cvt_pk_bf16_f32 v9, v69, v73
	ds_write_b32 v7, v9 offset:128
	v_cvt_pk_bf16_f32 v9, v70, v74
	ds_write_b32 v7, v9 offset:256
	v_cvt_pk_bf16_f32 v9, v71, v75
	ds_write_b32 v7, v9 offset:384
	v_xad_u32 v7, v108, 64, v5
	s_waitcnt vmcnt(6)
	v_cvt_pk_bf16_f32 v9, v76, v80
	ds_write_b32 v7, v9
	v_cvt_pk_bf16_f32 v9, v77, v81
	ds_write_b32 v7, v9 offset:128
	v_cvt_pk_bf16_f32 v9, v78, v82
	ds_write_b32 v7, v9 offset:256
	v_cvt_pk_bf16_f32 v9, v79, v83
	ds_write_b32 v7, v9 offset:384
	v_xad_u32 v7, v108, s39, v5
	s_waitcnt vmcnt(4)
	v_cvt_pk_bf16_f32 v9, v84, v88
	ds_write_b32 v7, v9
	v_cvt_pk_bf16_f32 v9, v85, v89
	ds_write_b32 v7, v9 offset:128
	v_cvt_pk_bf16_f32 v9, v86, v90
	ds_write_b32 v7, v9 offset:256
	v_cvt_pk_bf16_f32 v9, v87, v91
	ds_write_b32 v7, v9 offset:384
	v_xad_u32 v7, v108, s40, v5
	s_waitcnt vmcnt(2)
	v_cvt_pk_bf16_f32 v9, v92, v96
	ds_write_b32 v7, v9
	v_cvt_pk_bf16_f32 v9, v93, v97
	ds_write_b32 v7, v9 offset:128
	v_cvt_pk_bf16_f32 v9, v94, v98
	ds_write_b32 v7, v9 offset:256
	v_cvt_pk_bf16_f32 v9, v95, v99
	ds_write_b32 v7, v9 offset:384
	v_xad_u32 v5, v108, s38, v5
	s_waitcnt vmcnt(0)
	v_cvt_pk_bf16_f32 v7, v100, v104
	ds_write_b32 v5, v7
	v_cvt_pk_bf16_f32 v7, v101, v105
	ds_write_b32 v5, v7 offset:128
	v_cvt_pk_bf16_f32 v7, v102, v106
	ds_write_b32 v5, v7 offset:256
	v_cvt_pk_bf16_f32 v7, v103, v107
	ds_write_b32 v5, v7 offset:384
	v_ashrrev_i32_e32 v5, 3, v3
	v_lshrrev_b32_e32 v9, 2, v5
	v_xor_b32_e32 v9, v9, v3
	v_lshlrev_b32_e32 v9, 4, v9
	v_add_u32_e32 v54, s10, v5
	s_waitcnt lgkmcnt(0)
	v_lshlrev_b32_e32 v7, 7, v5
	v_and_b32_e32 v9, 0x70, v9
	v_ashrrev_i32_e32 v55, 31, v54
	v_lshl_add_u64 v[52:53], s[50:51], 0, v[108:109]
	v_add3_u32 v7, s25, v7, v9
	v_lshlrev_b64 v[44:45], 12, v[54:55]
	ds_read_b128 v[40:43], v7
	v_lshl_add_u64 v[48:49], v[52:53], 0, v[44:45]
	ds_read_b128 v[44:47], v7 offset:4096
	v_add_u32_e32 v7, 8, v5
	v_lshlrev_b32_e32 v9, 7, v7
	v_lshrrev_b32_e32 v7, 2, v7
	v_xor_b32_e32 v7, v7, v3
	v_lshlrev_b32_e32 v7, 4, v7
	v_and_b32_e32 v7, 0x70, v7
	v_add3_u32 v7, s25, v9, v7
	s_waitcnt lgkmcnt(1)
	global_store_dwordx4 v[48:49], v[40:43], off sc1
	ds_read_b128 v[40:43], v7
	v_add_u32_e32 v7, 16, v5
	v_lshlrev_b32_e32 v9, 7, v7
	v_lshrrev_b32_e32 v7, 2, v7
	v_xor_b32_e32 v7, v7, v3
	v_add_u32_e32 v48, 8, v54
	v_lshlrev_b32_e32 v7, 4, v7
	v_ashrrev_i32_e32 v49, 31, v48
	v_and_b32_e32 v7, 0x70, v7
	v_lshlrev_b64 v[48:49], 12, v[48:49]
	v_add3_u32 v7, s25, v9, v7
	v_lshl_add_u64 v[56:57], v[52:53], 0, v[48:49]
	ds_read_b128 v[48:51], v7
	v_add_u32_e32 v7, 24, v5
	v_lshlrev_b32_e32 v9, 7, v7
	v_lshrrev_b32_e32 v7, 2, v7
	s_waitcnt lgkmcnt(1)
	global_store_dwordx4 v[56:57], v[40:43], off sc1
	v_xor_b32_e32 v7, v7, v3
	v_lshlrev_b32_e32 v7, 4, v7
	v_add_u32_e32 v40, 16, v54
	v_ashrrev_i32_e32 v41, 31, v40
	v_lshlrev_b64 v[40:41], 12, v[40:41]
	v_and_b32_e32 v7, 0x70, v7
	v_lshl_add_u64 v[40:41], v[52:53], 0, v[40:41]
	v_add3_u32 v7, s25, v9, v7
	s_waitcnt lgkmcnt(0)
	global_store_dwordx4 v[40:41], v[48:51], off sc1
	ds_read_b128 v[40:43], v7
	v_add_u32_e32 v7, 40, v5
	v_add_u32_e32 v48, 24, v54
	v_ashrrev_i32_e32 v49, 31, v48
	v_lshlrev_b32_e32 v9, 7, v7
	v_lshrrev_b32_e32 v7, 2, v7
	v_lshlrev_b64 v[48:49], 12, v[48:49]
	v_xor_b32_e32 v7, v7, v3
	v_lshl_add_u64 v[56:57], v[52:53], 0, v[48:49]
	v_lshlrev_b32_e32 v7, 4, v7
	v_and_b32_e32 v7, 0x70, v7
	s_waitcnt lgkmcnt(0)
	global_store_dwordx4 v[56:57], v[40:43], off sc1
	v_add3_u32 v7, s25, v9, v7
	ds_read_b128 v[48:51], v7
	v_add_u32_e32 v40, 32, v54
	v_ashrrev_i32_e32 v41, 31, v40
	v_lshlrev_b64 v[40:41], 12, v[40:41]
	v_add_u32_e32 v7, 48, v5
	v_lshl_add_u64 v[40:41], v[52:53], 0, v[40:41]
	v_lshlrev_b32_e32 v9, 7, v7
	v_lshrrev_b32_e32 v7, 2, v7
	global_store_dwordx4 v[40:41], v[44:47], off sc1
	v_add_u32_e32 v40, 40, v54
	v_xor_b32_e32 v7, v7, v3
	v_ashrrev_i32_e32 v41, 31, v40
	v_lshlrev_b32_e32 v7, 4, v7
	v_lshlrev_b64 v[40:41], 12, v[40:41]
	v_and_b32_e32 v7, 0x70, v7
	v_lshl_add_u64 v[40:41], v[52:53], 0, v[40:41]
	v_add3_u32 v7, s25, v9, v7
	v_add_u32_e32 v5, 56, v5
	s_waitcnt lgkmcnt(0)
	global_store_dwordx4 v[40:41], v[48:51], off sc1
	ds_read_b128 v[40:43], v7
	v_lshlrev_b32_e32 v7, 7, v5
	v_lshrrev_b32_e32 v5, 2, v5
	v_xor_b32_e32 v3, v5, v3
	v_add_u32_e32 v44, 48, v54
	v_lshlrev_b32_e32 v3, 4, v3
	v_ashrrev_i32_e32 v45, 31, v44
	v_and_b32_e32 v3, 0x70, v3
	v_lshlrev_b64 v[44:45], 12, v[44:45]
	v_add3_u32 v3, s25, v7, v3
	v_lshl_add_u64 v[48:49], v[52:53], 0, v[44:45]
	ds_read_b128 v[44:47], v3
	s_waitcnt lgkmcnt(1)
	global_store_dwordx4 v[48:49], v[40:43], off sc1
	s_mov_b64 s[10:11], 0
	s_nop 0
	v_add_u32_e32 v40, 56, v54
	v_ashrrev_i32_e32 v41, 31, v40
	v_lshlrev_b64 v[40:41], 12, v[40:41]
	v_lshl_add_u64 v[40:41], v[52:53], 0, v[40:41]
	s_waitcnt lgkmcnt(0)
	global_store_dwordx4 v[40:41], v[44:47], off sc1
	s_waitcnt lgkmcnt(0)
.LBB0_48:
	s_andn2_b64 vcc, exec, s[10:11]
	s_cbranch_vccnz .LBB0_45
	s_mul_hi_i32 s0, s49, 0x2aaaaaab
	s_lshr_b32 s10, s0, 31
	s_ashr_i32 s0, s0, 3
	s_add_i32 s0, s0, s10
	s_mul_i32 s11, s0, 0xfffff400
	s_lshl_b32 s10, s0, 6
	s_add_i32 s11, s20, s11
	s_add_i32 s50, s11, 0x18000
	s_ashr_i32 s11, s10, 31
	s_mul_i32 s21, s0, 0xc0000
	s_mul_hi_i32 s51, s10, 0x3000
	s_add_u32 s21, s8, s21
	s_addc_u32 s52, s9, s51
	s_ashr_i32 s51, s50, 31
	s_lshl_b64 s[50:51], s[50:51], 2
	s_add_u32 s50, s21, s50
	s_addc_u32 s51, s52, s51
	v_lshl_add_u64 v[100:101], s[50:51], 0, v[0:1]
	v_mov_b32_e32 v21, v1
	v_mov_b32_e32 v23, v1
	v_lshl_add_u64 v[102:103], v[100:101], 0, v[20:21]
	v_lshl_add_u64 v[44:45], v[100:101], 0, v[22:23]
	global_load_dwordx4 v[40:43], v[102:103], off nt
	s_nop 0
	global_load_dwordx4 v[44:47], v[44:45], off nt
	v_add_co_u32_e32 v48, vcc, s41, v102
	v_mov_b32_e32 v25, v1
	s_nop 0
	v_addc_co_u32_e32 v49, vcc, 0, v103, vcc
	v_lshl_add_u64 v[52:53], v[100:101], 0, v[24:25]
	global_load_dwordx4 v[48:51], v[48:49], off nt
	s_nop 0
	global_load_dwordx4 v[52:55], v[52:53], off nt
	v_add_co_u32_e32 v56, vcc, s30, v102
	v_mov_b32_e32 v27, v1
	s_nop 0
	v_addc_co_u32_e32 v57, vcc, 0, v103, vcc
	v_lshl_add_u64 v[60:61], v[100:101], 0, v[26:27]
	global_load_dwordx4 v[56:59], v[56:57], off nt
	s_nop 0
	global_load_dwordx4 v[60:63], v[60:61], off nt
	v_add_co_u32_e32 v68, vcc, s45, v102
	v_mov_b32_e32 v29, v1
	s_nop 0
	v_addc_co_u32_e32 v69, vcc, 0, v103, vcc
	v_lshl_add_u64 v[72:73], v[100:101], 0, v[28:29]
	global_load_dwordx4 v[68:71], v[68:69], off nt
	s_nop 0
	global_load_dwordx4 v[72:75], v[72:73], off nt
	v_add_co_u32_e32 v76, vcc, s34, v102
	v_mov_b32_e32 v31, v1
	s_nop 0
	v_addc_co_u32_e32 v77, vcc, 0, v103, vcc
	v_lshl_add_u64 v[80:81], v[100:101], 0, v[30:31]
	global_load_dwordx4 v[76:79], v[76:77], off nt
	s_nop 0
	global_load_dwordx4 v[80:83], v[80:81], off nt
	v_add_co_u32_e32 v84, vcc, s46, v102
	v_mov_b32_e32 v33, v1
	s_nop 0
	v_addc_co_u32_e32 v85, vcc, 0, v103, vcc
	v_lshl_add_u64 v[88:89], v[100:101], 0, v[32:33]
	global_load_dwordx4 v[84:87], v[84:85], off nt
	s_nop 0
	global_load_dwordx4 v[88:91], v[88:89], off nt
	v_add_co_u32_e32 v92, vcc, s47, v102
	v_mov_b32_e32 v35, v1
	s_nop 0
	v_addc_co_u32_e32 v93, vcc, 0, v103, vcc
	v_lshl_add_u64 v[96:97], v[100:101], 0, v[34:35]
	global_load_dwordx4 v[92:95], v[92:93], off nt
	s_nop 0
	global_load_dwordx4 v[96:99], v[96:97], off nt
	v_add_co_u32_e32 v102, vcc, s48, v102
	v_mov_b32_e32 v37, v1
	s_nop 0
	v_addc_co_u32_e32 v103, vcc, 0, v103, vcc
	v_lshl_add_u64 v[104:105], v[100:101], 0, v[36:37]
	global_load_dwordx4 v[100:103], v[102:103], off nt
	s_nop 0
	global_load_dwordx4 v[104:107], v[104:105], off nt
	v_mov_b32_e32 v3, v38
	s_mulk_i32 s0, 0xc00
	v_lshlrev_b32_e32 v5, 9, v3
	v_ashrrev_i32_e32 v7, 2, v3
	v_lshlrev_b32_e32 v9, 4, v3
	v_and_b32_e32 v5, 0x1e00, v5
	v_and_b32_e32 v7, -4, v7
	v_and_b32_e32 v108, 0x70, v9
	v_add3_u32 v5, s25, v5, v7
	v_add_u32_e32 v7, v5, v108
	s_lshl_b64 s[10:11], s[10:11], 1
	s_add_u32 s10, s76, s10
	s_addc_u32 s11, s77, s11
	v_mov_b32_e32 v109, v1
	s_waitcnt vmcnt(14)
	v_cvt_pk_bf16_f32 v9, v40, v44
	ds_write_b32 v7, v9
	v_cvt_pk_bf16_f32 v9, v41, v45
	ds_write_b32 v7, v9 offset:128
	v_cvt_pk_bf16_f32 v9, v42, v46
	ds_write_b32 v7, v9 offset:256
	v_cvt_pk_bf16_f32 v9, v43, v47
	ds_write_b32 v7, v9 offset:384
	v_xad_u32 v7, v108, 16, v5
	s_waitcnt vmcnt(12)
	v_cvt_pk_bf16_f32 v9, v48, v52
	ds_write_b32 v7, v9
	v_cvt_pk_bf16_f32 v9, v49, v53
	ds_write_b32 v7, v9 offset:128
	v_cvt_pk_bf16_f32 v9, v50, v54
	ds_write_b32 v7, v9 offset:256
	v_cvt_pk_bf16_f32 v9, v51, v55
	ds_write_b32 v7, v9 offset:384
	v_xad_u32 v7, v108, 32, v5
	s_waitcnt vmcnt(10)
	v_cvt_pk_bf16_f32 v9, v56, v60
	ds_write_b32 v7, v9
	v_cvt_pk_bf16_f32 v9, v57, v61
	ds_write_b32 v7, v9 offset:128
	v_cvt_pk_bf16_f32 v9, v58, v62
	ds_write_b32 v7, v9 offset:256
	v_cvt_pk_bf16_f32 v9, v59, v63
	ds_write_b32 v7, v9 offset:384
	v_xad_u32 v7, v108, 48, v5
	s_waitcnt vmcnt(8)
	v_cvt_pk_bf16_f32 v9, v68, v72
	ds_write_b32 v7, v9
	v_cvt_pk_bf16_f32 v9, v69, v73
	ds_write_b32 v7, v9 offset:128
	v_cvt_pk_bf16_f32 v9, v70, v74
	ds_write_b32 v7, v9 offset:256
	v_cvt_pk_bf16_f32 v9, v71, v75
	ds_write_b32 v7, v9 offset:384
	v_xad_u32 v7, v108, 64, v5
	s_waitcnt vmcnt(6)
	v_cvt_pk_bf16_f32 v9, v76, v80
	ds_write_b32 v7, v9
	v_cvt_pk_bf16_f32 v9, v77, v81
	ds_write_b32 v7, v9 offset:128
	v_cvt_pk_bf16_f32 v9, v78, v82
	ds_write_b32 v7, v9 offset:256
	v_cvt_pk_bf16_f32 v9, v79, v83
	ds_write_b32 v7, v9 offset:384
	v_xad_u32 v7, v108, s39, v5
	s_waitcnt vmcnt(4)
	v_cvt_pk_bf16_f32 v9, v84, v88
	ds_write_b32 v7, v9
	v_cvt_pk_bf16_f32 v9, v85, v89
	ds_write_b32 v7, v9 offset:128
	v_cvt_pk_bf16_f32 v9, v86, v90
	ds_write_b32 v7, v9 offset:256
	v_cvt_pk_bf16_f32 v9, v87, v91
	ds_write_b32 v7, v9 offset:384
	v_xad_u32 v7, v108, s40, v5
	s_waitcnt vmcnt(2)
	v_cvt_pk_bf16_f32 v9, v92, v96
	ds_write_b32 v7, v9
	v_cvt_pk_bf16_f32 v9, v93, v97
	ds_write_b32 v7, v9 offset:128
	v_cvt_pk_bf16_f32 v9, v94, v98
	ds_write_b32 v7, v9 offset:256
	v_cvt_pk_bf16_f32 v9, v95, v99
	ds_write_b32 v7, v9 offset:384
	v_xad_u32 v5, v108, s38, v5
	s_waitcnt vmcnt(0)
	v_cvt_pk_bf16_f32 v7, v100, v104
	ds_write_b32 v5, v7
	v_cvt_pk_bf16_f32 v7, v101, v105
	ds_write_b32 v5, v7 offset:128
	v_cvt_pk_bf16_f32 v7, v102, v106
	ds_write_b32 v5, v7 offset:256
	v_cvt_pk_bf16_f32 v7, v103, v107
	ds_write_b32 v5, v7 offset:384
	v_ashrrev_i32_e32 v5, 3, v3
	v_lshrrev_b32_e32 v9, 2, v5
	v_xor_b32_e32 v9, v9, v3
	v_lshlrev_b32_e32 v9, 4, v9
	v_lshlrev_b32_e32 v7, 7, v5
	v_and_b32_e32 v9, 0x70, v9
	v_add3_u32 v7, s25, v7, v9
	v_subrev_u32_e32 v9, s0, v5
	v_add_u32_e32 v9, s20, v9
	v_add_u32_e32 v44, 0x18000, v9
	s_waitcnt lgkmcnt(0)
	v_ashrrev_i32_e32 v45, 31, v44
	v_lshl_add_u64 v[52:53], s[10:11], 0, v[108:109]
	v_lshlrev_b64 v[44:45], 12, v[44:45]
	ds_read_b128 v[40:43], v7
	v_lshl_add_u64 v[48:49], v[52:53], 0, v[44:45]
	ds_read_b128 v[44:47], v7 offset:4096
	v_add_u32_e32 v7, 8, v5
	v_lshlrev_b32_e32 v11, 7, v7
	v_lshrrev_b32_e32 v7, 2, v7
	v_xor_b32_e32 v7, v7, v3
	v_lshlrev_b32_e32 v7, 4, v7
	v_and_b32_e32 v7, 0x70, v7
	v_add3_u32 v7, s25, v11, v7
	s_waitcnt lgkmcnt(1)
	global_store_dwordx4 v[48:49], v[40:43], off sc1
	ds_read_b128 v[40:43], v7
	v_add_u32_e32 v7, 16, v5
	v_lshlrev_b32_e32 v11, 7, v7
	v_lshrrev_b32_e32 v7, 2, v7
	v_xor_b32_e32 v7, v7, v3
	v_add_u32_e32 v48, 0x18008, v9
	v_lshlrev_b32_e32 v7, 4, v7
	v_ashrrev_i32_e32 v49, 31, v48
	v_and_b32_e32 v7, 0x70, v7
	v_lshlrev_b64 v[48:49], 12, v[48:49]
	v_add3_u32 v7, s25, v11, v7
	v_lshl_add_u64 v[54:55], v[52:53], 0, v[48:49]
	ds_read_b128 v[48:51], v7
	v_add_u32_e32 v7, 24, v5
	v_lshlrev_b32_e32 v11, 7, v7
	v_lshrrev_b32_e32 v7, 2, v7
	s_waitcnt lgkmcnt(1)
	global_store_dwordx4 v[54:55], v[40:43], off sc1
	v_xor_b32_e32 v7, v7, v3
	v_lshlrev_b32_e32 v7, 4, v7
	v_add_u32_e32 v40, 0x18010, v9
	v_ashrrev_i32_e32 v41, 31, v40
	v_lshlrev_b64 v[40:41], 12, v[40:41]
	v_and_b32_e32 v7, 0x70, v7
	v_lshl_add_u64 v[40:41], v[52:53], 0, v[40:41]
	v_add3_u32 v7, s25, v11, v7
	s_waitcnt lgkmcnt(0)
	global_store_dwordx4 v[40:41], v[48:51], off sc1
	ds_read_b128 v[40:43], v7
	v_add_u32_e32 v7, 40, v5
	v_add_u32_e32 v48, 0x18018, v9
	v_ashrrev_i32_e32 v49, 31, v48
	v_lshlrev_b32_e32 v11, 7, v7
	v_lshrrev_b32_e32 v7, 2, v7
	v_lshlrev_b64 v[48:49], 12, v[48:49]
	v_xor_b32_e32 v7, v7, v3
	v_lshl_add_u64 v[54:55], v[52:53], 0, v[48:49]
	v_lshlrev_b32_e32 v7, 4, v7
	v_and_b32_e32 v7, 0x70, v7
	s_waitcnt lgkmcnt(0)
	global_store_dwordx4 v[54:55], v[40:43], off sc1
	v_add3_u32 v7, s25, v11, v7
	ds_read_b128 v[48:51], v7
	v_add_u32_e32 v40, 0x18020, v9
	v_ashrrev_i32_e32 v41, 31, v40
	v_lshlrev_b64 v[40:41], 12, v[40:41]
	v_add_u32_e32 v7, 48, v5
	v_lshl_add_u64 v[40:41], v[52:53], 0, v[40:41]
	v_lshlrev_b32_e32 v11, 7, v7
	v_lshrrev_b32_e32 v7, 2, v7
	global_store_dwordx4 v[40:41], v[44:47], off sc1
	v_add_u32_e32 v40, 0x18028, v9
	v_xor_b32_e32 v7, v7, v3
	v_ashrrev_i32_e32 v41, 31, v40
	v_lshlrev_b32_e32 v7, 4, v7
	v_lshlrev_b64 v[40:41], 12, v[40:41]
	v_and_b32_e32 v7, 0x70, v7
	v_lshl_add_u64 v[40:41], v[52:53], 0, v[40:41]
	v_add3_u32 v7, s25, v11, v7
	v_add_u32_e32 v5, 56, v5
	s_waitcnt lgkmcnt(0)
	global_store_dwordx4 v[40:41], v[48:51], off sc1
	ds_read_b128 v[40:43], v7
	v_lshlrev_b32_e32 v7, 7, v5
	v_lshrrev_b32_e32 v5, 2, v5
	v_xor_b32_e32 v3, v5, v3
	v_add_u32_e32 v44, 0x18030, v9
	v_lshlrev_b32_e32 v3, 4, v3
	v_ashrrev_i32_e32 v45, 31, v44
	v_and_b32_e32 v3, 0x70, v3
	v_lshlrev_b64 v[44:45], 12, v[44:45]
	v_add3_u32 v3, s25, v7, v3
	v_lshl_add_u64 v[48:49], v[52:53], 0, v[44:45]
	ds_read_b128 v[44:47], v3
	s_waitcnt lgkmcnt(1)
	global_store_dwordx4 v[48:49], v[40:43], off sc1
	s_nop 1
	v_add_u32_e32 v40, 0x18038, v9
	v_ashrrev_i32_e32 v41, 31, v40
	v_lshlrev_b64 v[40:41], 12, v[40:41]
	v_lshl_add_u64 v[40:41], v[52:53], 0, v[40:41]
	s_waitcnt lgkmcnt(0)
	global_store_dwordx4 v[40:41], v[44:47], off sc1
	s_waitcnt lgkmcnt(0)
	s_branch .LBB0_45

.LBB0_52:
	s_or_b64 exec, exec, s[48:49]
	s_waitcnt lgkmcnt(0)
	global_load_dwordx4 v[90:93], v[70:71], off
	v_lshl_add_u64 v[94:95], s[66:67], 0, v[80:81]
	v_add_co_u32_e32 v96, vcc, s27, v94
	s_add_i32 s28, s28, s8
	s_nop 0
	v_addc_co_u32_e32 v97, vcc, 0, v95, vcc
	s_add_u32 s10, s10, s18
	s_addc_u32 s11, s11, s19
	v_lshl_add_u64 v[80:81], v[80:81], 0, s[34:35]
	s_cmpk_gt_i32 s28, 0x3fff
	v_lshl_add_u64 v[82:83], v[82:83], 0, s[46:47]
	s_waitcnt vmcnt(0)
	v_pk_mul_f32 v[56:57], v[90:91], v[56:57]
	v_pk_mul_f32 v[58:59], v[92:93], v[58:59]
	v_cvt_pk_bf16_f32 v56, v56, v57
	v_pk_mul_f32 v[62:63], v[92:93], v[62:63]
	v_cvt_pk_bf16_f32 v57, v58, v59
	v_pk_mul_f32 v[60:61], v[90:91], v[60:61]
	global_store_dwordx2 v[96:97], v[56:57], off offset:-4096 sc1
	v_cvt_pk_bf16_f32 v56, v60, v61
	v_cvt_pk_bf16_f32 v57, v62, v63
	global_store_dwordx2 v[96:97], v[56:57], off sc1
	global_load_dwordx4 v[56:59], v[70:71], off offset:1024
	v_add_co_u32_e32 v60, vcc, s20, v94
	s_waitcnt vmcnt(0)
	v_pk_mul_f32 v[48:49], v[56:57], v[48:49]
	v_addc_co_u32_e32 v61, vcc, 0, v95, vcc
	v_pk_mul_f32 v[50:51], v[58:59], v[50:51]
	v_cvt_pk_bf16_f32 v48, v48, v49
	v_pk_mul_f32 v[54:55], v[58:59], v[54:55]
	v_cvt_pk_bf16_f32 v49, v50, v51
	v_pk_mul_f32 v[52:53], v[56:57], v[52:53]
	global_store_dwordx2 v[60:61], v[48:49], off offset:512 sc1
	v_cvt_pk_bf16_f32 v48, v52, v53
	v_cvt_pk_bf16_f32 v49, v54, v55
	global_store_dwordx2 v[96:97], v[48:49], off offset:512 sc1
	global_load_dwordx4 v[48:51], v[70:71], off offset:2048
	s_waitcnt vmcnt(0)
	v_pk_mul_f32 v[40:41], v[48:49], v[40:41]
	v_pk_mul_f32 v[42:43], v[50:51], v[42:43]
	v_cvt_pk_bf16_f32 v40, v40, v41
	v_pk_mul_f32 v[46:47], v[50:51], v[46:47]
	v_cvt_pk_bf16_f32 v41, v42, v43
	v_pk_mul_f32 v[44:45], v[48:49], v[44:45]
	global_store_dwordx2 v[60:61], v[40:41], off offset:1024 sc1
	v_cvt_pk_bf16_f32 v40, v44, v45
	v_cvt_pk_bf16_f32 v41, v46, v47
	global_store_dwordx2 v[96:97], v[40:41], off offset:1024 sc1
	global_load_dwordx4 v[40:43], v[70:71], off offset:3072
	s_waitcnt vmcnt(0)
	v_pk_mul_f32 v[36:37], v[40:41], v[36:37]
	v_pk_mul_f32 v[28:29], v[40:41], v[28:29]
	v_pk_mul_f32 v[38:39], v[42:43], v[38:39]
	v_pk_mul_f32 v[30:31], v[42:43], v[30:31]
	v_cvt_pk_bf16_f32 v36, v36, v37
	v_cvt_pk_bf16_f32 v37, v38, v39
	global_store_dwordx2 v[60:61], v[36:37], off offset:1536 sc1
	v_cvt_pk_bf16_f32 v28, v28, v29
	v_cvt_pk_bf16_f32 v29, v30, v31
	global_store_dwordx2 v[96:97], v[28:29], off offset:1536 sc1
	global_load_dwordx4 v[28:31], v[72:73], off
	s_waitcnt vmcnt(0)
	v_pk_mul_f32 v[24:25], v[28:29], v[24:25]
	v_pk_mul_f32 v[34:35], v[30:31], v[34:35]
	v_pk_mul_f32 v[32:33], v[28:29], v[32:33]
	v_pk_mul_f32 v[26:27], v[30:31], v[26:27]
	v_cvt_pk_bf16_f32 v28, v32, v33
	v_cvt_pk_bf16_f32 v29, v34, v35
	global_store_dwordx2 v[60:61], v[28:29], off offset:2048 sc1
	v_cvt_pk_bf16_f32 v24, v24, v25
	v_cvt_pk_bf16_f32 v25, v26, v27
	global_store_dwordx2 v[96:97], v[24:25], off offset:2048 sc1
	global_load_dwordx4 v[24:27], v[74:75], off
	s_waitcnt vmcnt(0)
	v_pk_mul_f32 v[20:21], v[24:25], v[20:21]
	v_pk_mul_f32 v[16:17], v[24:25], v[16:17]
	v_pk_mul_f32 v[22:23], v[26:27], v[22:23]
	v_pk_mul_f32 v[18:19], v[26:27], v[18:19]
	v_cvt_pk_bf16_f32 v20, v20, v21
	v_cvt_pk_bf16_f32 v21, v22, v23
	global_store_dwordx2 v[60:61], v[20:21], off offset:2560 sc1
	v_cvt_pk_bf16_f32 v16, v16, v17
	v_cvt_pk_bf16_f32 v17, v18, v19
	global_store_dwordx2 v[96:97], v[16:17], off offset:2560 sc1
	global_load_dwordx4 v[16:19], v[76:77], off
	s_waitcnt vmcnt(0)
	v_pk_mul_f32 v[12:13], v[16:17], v[12:13]
	v_pk_mul_f32 v[8:9], v[16:17], v[8:9]
	v_pk_mul_f32 v[14:15], v[18:19], v[14:15]
	v_pk_mul_f32 v[10:11], v[18:19], v[10:11]
	v_cvt_pk_bf16_f32 v12, v12, v13
	v_cvt_pk_bf16_f32 v13, v14, v15
	global_store_dwordx2 v[60:61], v[12:13], off offset:3072 sc1
	v_cvt_pk_bf16_f32 v8, v8, v9
	v_cvt_pk_bf16_f32 v9, v10, v11
	global_store_dwordx2 v[96:97], v[8:9], off offset:3072 sc1
	global_load_dwordx4 v[8:11], v[78:79], off
	s_waitcnt vmcnt(0)
	v_pk_mul_f32 v[4:5], v[8:9], v[4:5]
	v_pk_mul_f32 v[0:1], v[8:9], v[0:1]
	v_pk_mul_f32 v[6:7], v[10:11], v[6:7]
	v_pk_mul_f32 v[2:3], v[10:11], v[2:3]
	v_cvt_pk_bf16_f32 v4, v4, v5
	v_cvt_pk_bf16_f32 v5, v6, v7
	global_store_dwordx2 v[60:61], v[4:5], off offset:3584 sc1
	v_cvt_pk_bf16_f32 v0, v0, v1
	v_cvt_pk_bf16_f32 v1, v2, v3
	global_store_dwordx2 v[96:97], v[0:1], off offset:3584 sc1
	s_cbranch_scc1 .LBB0_55
.LBB0_53:
	v_add_co_u32_e32 v0, vcc, 0xffffd000, v82
	global_load_dwordx4 v[28:31], v[82:83], off offset:-4096 nt
	global_load_dwordx4 v[24:27], v[82:83], off offset:-3072 nt
	v_addc_co_u32_e32 v1, vcc, -1, v83, vcc
	global_load_dwordx4 v[56:59], v[0:1], off offset:-3072 nt
	global_load_dwordx4 v[48:51], v[0:1], off offset:-2048 nt
	global_load_dwordx4 v[40:43], v[0:1], off offset:-1024 nt
	global_load_dwordx4 v[36:39], v[0:1], off nt
	v_add_co_u32_e32 v0, vcc, 0xfffff000, v82
	s_waitcnt vmcnt(5)
	v_mul_f32_e32 v90, v29, v29
	v_addc_co_u32_e32 v1, vcc, -1, v83, vcc
	global_load_dwordx4 v[60:63], v[0:1], off offset:-3072 nt
	global_load_dwordx4 v[52:55], v[0:1], off offset:-2048 nt
	global_load_dwordx4 v[44:47], v[0:1], off offset:-1024 nt
	v_add_co_u32_e32 v4, vcc, 0xffffe000, v82
	v_mul_f32_e32 v91, v31, v31
	s_nop 0
	v_addc_co_u32_e32 v5, vcc, -1, v83, vcc
	global_load_dwordx4 v[32:35], v[4:5], off offset:-3072 nt
	global_load_dwordx4 v[20:23], v[4:5], off offset:-2048 nt
	global_load_dwordx4 v[16:19], v[82:83], off offset:-2048 nt
	global_load_dwordx4 v[12:15], v[4:5], off offset:-1024 nt
	global_load_dwordx4 v[8:11], v[82:83], off offset:-1024 nt
	global_load_dwordx4 v[0:3], v[82:83], off nt
	s_nop 0
	global_load_dwordx4 v[4:7], v[4:5], off nt
	s_waitcnt vmcnt(14)
	v_mul_f32_e32 v92, v25, v25
	v_mul_f32_e32 v93, v27, v27
	v_fmac_f32_e32 v90, v28, v28
	v_fmac_f32_e32 v91, v30, v30
	v_fmac_f32_e32 v92, v24, v24
	v_fmac_f32_e32 v93, v26, v26
	s_waitcnt vmcnt(13)
	v_mul_f32_e32 v94, v57, v57
	v_mul_f32_e32 v95, v59, v59
	s_waitcnt vmcnt(12)
	v_mul_f32_e32 v96, v49, v49
	v_mul_f32_e32 v97, v51, v51
	v_add_f32_e32 v90, v90, v91
	v_add_f32_e32 v91, v92, v93
	v_fmac_f32_e32 v94, v56, v56
	v_fmac_f32_e32 v95, v58, v58
	v_fmac_f32_e32 v96, v48, v48
	v_fmac_f32_e32 v97, v50, v50
	v_add_f32_e32 v94, v94, v95
	v_add_f32_e32 v95, v96, v97
	s_waitcnt vmcnt(11)
	v_mul_f32_e32 v98, v41, v41
	v_mul_f32_e32 v99, v43, v43
	s_waitcnt vmcnt(10)
	v_mul_f32_e32 v100, v37, v37
	v_mul_f32_e32 v101, v39, v39
	v_fmac_f32_e32 v98, v40, v40
	v_fmac_f32_e32 v99, v42, v42
	v_fmac_f32_e32 v100, v36, v36
	v_fmac_f32_e32 v101, v38, v38
	v_add_f32_e32 v96, v98, v99
	v_add_f32_e32 v97, v100, v101
	s_waitcnt vmcnt(9)
	v_mul_f32_e32 v92, v61, v61
	v_mul_f32_e32 v93, v63, v63
	s_waitcnt vmcnt(8)
	v_mul_f32_e32 v102, v53, v53
	v_mul_f32_e32 v103, v55, v55
	s_waitcnt vmcnt(7)
	v_mul_f32_e32 v104, v45, v45
	v_mul_f32_e32 v105, v47, v47
	v_fmac_f32_e32 v92, v60, v60
	v_fmac_f32_e32 v93, v62, v62
	v_fmac_f32_e32 v102, v52, v52
	v_fmac_f32_e32 v103, v54, v54
	v_fmac_f32_e32 v104, v44, v44
	v_fmac_f32_e32 v105, v46, v46
	v_add_f32_e32 v92, v92, v93
	v_add_f32_e32 v93, v94, v95
	v_add_f32_e32 v94, v102, v103
	v_add_f32_e32 v95, v104, v105
	v_add_f32_e32 v92, v92, v94
	v_add_f32_e32 v92, v92, v95
	s_waitcnt vmcnt(6)
	v_mul_f32_e32 v98, v33, v33
	v_mul_f32_e32 v99, v35, v35
	v_add_f32_e32 v90, v92, v90
	s_waitcnt vmcnt(5)
	v_mul_f32_e32 v100, v21, v21
	v_fmac_f32_e32 v98, v32, v32
	v_fmac_f32_e32 v99, v34, v34
	v_add_f32_e32 v93, v93, v96
	v_add_f32_e32 v90, v90, v91
	v_mul_f32_e32 v91, v23, v23
	v_add_f32_e32 v94, v98, v99
	v_add_f32_e32 v93, v93, v97
	v_fmac_f32_e32 v100, v20, v20
	v_fmac_f32_e32 v91, v22, v22
	v_add_f32_e32 v92, v93, v94
	v_add_f32_e32 v91, v100, v91
	v_add_f32_e32 v91, v92, v91
	s_waitcnt vmcnt(4)
	v_mul_f32_e32 v92, v17, v17
	v_mul_f32_e32 v93, v19, v19
	v_fmac_f32_e32 v92, v16, v16
	v_fmac_f32_e32 v93, v18, v18
	v_add_f32_e32 v92, v92, v93
	v_add_f32_e32 v90, v90, v92
	s_waitcnt vmcnt(3)
	v_mul_f32_e32 v92, v13, v13
	v_mul_f32_e32 v93, v15, v15
	v_fmac_f32_e32 v92, v12, v12
	v_fmac_f32_e32 v93, v14, v14
	v_add_f32_e32 v92, v92, v93
	v_add_f32_e32 v91, v91, v92
	s_waitcnt vmcnt(2)
	v_mul_f32_e32 v92, v9, v9
	v_mul_f32_e32 v93, v11, v11
	v_fmac_f32_e32 v92, v8, v8
	v_fmac_f32_e32 v93, v10, v10
	v_add_f32_e32 v92, v92, v93
	v_add_f32_e32 v90, v90, v92
	s_waitcnt vmcnt(0)
	v_mul_f32_e32 v92, v5, v5
	v_mul_f32_e32 v93, v7, v7
	v_fmac_f32_e32 v92, v4, v4
	v_fmac_f32_e32 v93, v6, v6
	v_add_f32_e32 v92, v92, v93
	v_add_f32_e32 v91, v91, v92
	v_mul_f32_e32 v92, v1, v1
	v_mul_f32_e32 v93, v3, v3
	v_fmac_f32_e32 v92, v0, v0
	v_fmac_f32_e32 v93, v2, v2
	v_add_f32_e32 v92, v92, v93
	v_add_f32_e32 v90, v90, v92
	ds_bpermute_b32 v93, v67, v91
	ds_bpermute_b32 v92, v67, v90
	s_waitcnt lgkmcnt(1)
	v_add_f32_e32 v91, v91, v93
	s_waitcnt lgkmcnt(0)
	v_add_f32_e32 v90, v90, v92
	ds_bpermute_b32 v93, v84, v91
	ds_bpermute_b32 v92, v84, v90
	s_waitcnt lgkmcnt(1)
	v_add_f32_e32 v91, v91, v93
	s_waitcnt lgkmcnt(0)
	v_add_f32_e32 v90, v90, v92
	ds_bpermute_b32 v93, v85, v91
	ds_bpermute_b32 v92, v85, v90
	s_waitcnt lgkmcnt(1)
	v_add_f32_e32 v91, v91, v93
	s_waitcnt lgkmcnt(0)
	v_add_f32_e32 v90, v90, v92
	ds_bpermute_b32 v93, v86, v91
	ds_bpermute_b32 v92, v86, v90
	s_waitcnt lgkmcnt(1)
	v_add_f32_e32 v91, v91, v93
	s_waitcnt lgkmcnt(0)
	v_add_f32_e32 v90, v90, v92
	ds_bpermute_b32 v93, v87, v91
	ds_bpermute_b32 v94, v87, v90
	s_waitcnt lgkmcnt(1)
	v_add_f32_e32 v92, v91, v93
	s_waitcnt lgkmcnt(0)
	v_add_f32_e32 v90, v90, v94
	ds_bpermute_b32 v93, v88, v92
	ds_bpermute_b32 v91, v88, v90
	s_and_saveexec_b64 s[48:49], s[0:1]
	s_cbranch_execz .LBB0_52
	s_waitcnt lgkmcnt(1)
	v_add_f32_e32 v92, v92, v93
	v_fmamk_f32 v92, v92, 0x3a000000, v68
	v_mul_f32_e32 v93, 0x4f800000, v92
	v_cmp_gt_f32_e32 vcc, s9, v92
	s_waitcnt lgkmcnt(0)
	v_add_f32_e32 v90, v90, v91
	v_fmamk_f32 v90, v90, 0x3a000000, v68
	v_cndmask_b32_e32 v92, v92, v93, vcc
	v_sqrt_f32_e32 v93, v92
	v_mul_f32_e32 v95, 0x4f800000, v90
	v_add_u32_e32 v91, -1, v93
	v_fma_f32 v94, -v91, v93, v92
	v_cmp_ge_f32_e64 s[4:5], 0, v94
	v_add_u32_e32 v94, 1, v93
	s_nop 0
	v_cndmask_b32_e64 v91, v93, v91, s[4:5]
	v_cmp_gt_f32_e64 s[4:5], s9, v90
	v_fma_f32 v93, -v94, v93, v92
	v_cmp_lt_f32_e64 s[6:7], 0, v93
	v_cndmask_b32_e64 v90, v90, v95, s[4:5]
	v_sqrt_f32_e32 v95, v90
	v_cndmask_b32_e64 v91, v91, v94, s[6:7]
	v_mul_f32_e32 v93, 0x37800000, v91
	v_cndmask_b32_e32 v91, v91, v93, vcc
	v_add_u32_e32 v93, -1, v95
	v_fma_f32 v94, -v93, v95, v90
	v_cmp_ge_f32_e32 vcc, 0, v94
	v_add_u32_e32 v94, 1, v95
	s_nop 0
	v_cndmask_b32_e32 v93, v95, v93, vcc
	v_fma_f32 v95, -v94, v95, v90
	v_cmp_lt_f32_e32 vcc, 0, v95
	s_nop 1
	v_cndmask_b32_e32 v93, v93, v94, vcc
	v_mul_f32_e32 v94, 0x37800000, v93
	v_cndmask_b32_e64 v93, v93, v94, s[4:5]
	v_cmp_class_f32_e32 vcc, v90, v89
	s_nop 1
	v_cndmask_b32_e32 v90, v93, v90, vcc
	v_div_scale_f32 v93, s[4:5], v90, v90, 1.0
	v_rcp_f32_e32 v94, v93
	v_cmp_class_f32_e32 vcc, v92, v89
	s_add_u32 s4, s66, s10
	s_addc_u32 s5, s67, s11
	v_cndmask_b32_e32 v92, v91, v92, vcc
	v_fma_f32 v91, -v93, v94, 1.0
	v_fmac_f32_e32 v94, v91, v94
	v_div_scale_f32 v91, vcc, 1.0, v90, 1.0
	v_mul_f32_e32 v95, v91, v94
	v_fma_f32 v96, -v93, v95, v91
	v_fmac_f32_e32 v95, v96, v94
	v_fma_f32 v91, -v93, v95, v91
	v_div_scale_f32 v93, s[6:7], v92, v92, 1.0
	v_rcp_f32_e32 v96, v93
	v_div_fmas_f32 v91, v91, v94, v95
	v_div_fixup_f32 v91, v91, v90, 1.0
	v_fma_f32 v90, -v93, v96, 1.0
	v_fmac_f32_e32 v96, v90, v96
	v_div_scale_f32 v90, vcc, 1.0, v92, 1.0
	v_mul_f32_e32 v94, v90, v96
	v_fma_f32 v95, -v93, v94, v90
	v_fmac_f32_e32 v94, v95, v96
	v_fma_f32 v90, -v93, v94, v90
	v_div_fmas_f32 v90, v90, v96, v94
	v_div_fixup_f32 v90, v90, v92, 1.0
	global_store_dwordx2 v69, v[90:91], s[4:5] sc1
	s_branch .LBB0_52

.LBB0_57:
	v_ashrrev_i32_e32 v4, 8, v64
	v_add_u32_e32 v64, s44, v64
	v_lshlrev_b32_e32 v9, 1, v4
	v_cmp_lt_i32_e32 vcc, s11, v64
	v_ashrrev_i32_e32 v5, 31, v4
	v_add_u32_e32 v10, 0x401, v9
	s_or_b64 s[4:5], vcc, s[4:5]
	v_cmp_gt_i32_e32 vcc, s7, v4
	v_and_b32_e32 v3, 0x7f8, v2
	v_and_b32_e32 v8, 0x3f8, v2
	v_lshlrev_b64 v[6:7], 12, v[4:5]
	v_cndmask_b32_e32 v10, v10, v9, vcc
	v_lshlrev_b32_e32 v0, 1, v3
	v_lshl_add_u64 v[4:5], s[8:9], 0, v[6:7]
	v_mul_lo_u32 v6, v8, v10
	v_lshl_add_u64 v[8:9], v[4:5], 0, v[0:1]
	v_add_u32_e32 v4, v6, v10
	v_and_b32_e32 v5, 0x7ff, v4
	v_add_u32_e32 v4, v4, v10
	v_and_b32_e32 v0, 0x7f8, v6
	v_cvt_f32_u32_e32 v5, v5
	v_and_b32_e32 v6, 0x7fe, v4
	v_add_u32_e32 v4, v4, v10
	v_cvt_f32_u32_e32 v0, v0
	v_cvt_f32_u32_e32 v6, v6
	v_and_b32_e32 v7, 0x7ff, v4
	v_add_u32_e32 v4, v4, v10
	v_cvt_f32_u32_e32 v7, v7
	v_and_b32_e32 v11, 0x7fc, v4
	v_add_u32_e32 v4, v4, v10
	v_and_b32_e32 v12, 0x7ff, v4
	v_add_u32_e32 v4, v4, v10
	v_cmp_gt_u32_e32 vcc, s10, v3
	v_mul_f32_e32 v3, 0x3a000000, v5
	v_cvt_f32_u32_e32 v5, v12
	v_and_b32_e32 v12, 0x7fe, v4
	v_add_u32_e32 v4, v4, v10
	v_mul_f32_e32 v0, 0x3a000000, v0
	v_sin_f32_e32 v10, v3
	v_cos_f32_e32 v3, v3
	v_mul_f32_e32 v6, 0x3a000000, v6
	v_cvt_f32_u32_e32 v12, v12
	v_and_b32_e32 v4, 0x7ff, v4
	v_cvt_f32_u32_e32 v11, v11
	v_sin_f32_e32 v13, v0
	v_cos_f32_e32 v0, v0
	v_sin_f32_e32 v14, v6
	v_cos_f32_e32 v6, v6
	v_mul_f32_e32 v7, 0x3a000000, v7
	v_cvt_f32_u32_e32 v4, v4
	v_sin_f32_e32 v15, v7
	v_cos_f32_e32 v7, v7
	v_mul_f32_e32 v5, 0x3a000000, v5
	v_cndmask_b32_e32 v3, v10, v3, vcc
	v_sin_f32_e32 v10, v5
	v_cos_f32_e32 v16, v5
	v_mul_f32_e32 v5, 0x3a000000, v12
	v_mul_f32_e32 v11, 0x3a000000, v11
	v_cndmask_b32_e32 v0, v13, v0, vcc
	v_cndmask_b32_e32 v6, v14, v6, vcc
	v_sin_f32_e32 v12, v5
	v_cos_f32_e32 v14, v5
	v_mul_f32_e32 v5, 0x3a000000, v4
	v_sin_f32_e32 v13, v11
	v_cos_f32_e32 v11, v11
	v_cvt_pk_bf16_f32 v4, v0, v3
	v_cndmask_b32_e32 v0, v15, v7, vcc
	v_sin_f32_e32 v3, v5
	v_cos_f32_e32 v7, v5
	v_add_u32_e32 v2, s6, v2
	v_cvt_pk_bf16_f32 v5, v6, v0
	v_cndmask_b32_e32 v0, v10, v16, vcc
	v_cndmask_b32_e32 v11, v13, v11, vcc
	v_cndmask_b32_e32 v10, v12, v14, vcc
	v_cvt_pk_bf16_f32 v6, v11, v0
	v_cndmask_b32_e32 v0, v3, v7, vcc
	v_cvt_pk_bf16_f32 v7, v10, v0
	global_store_dwordx4 v[8:9], v[4:7], off sc1
	s_andn2_b64 exec, exec, s[4:5]
	s_cbranch_execnz .LBB0_57

.LBB0_277:
	s_bfe_u32 s0, s51, 0x40003
	s_lshl_b32 s60, s0, 7
	s_and_b32 s20, s51, 0x1ffff80
	s_lshl_b32 s0, s0, 3
	s_and_b32 s64, s51, 7
	s_or_b32 s0, s0, s20
	s_or_b32 s0, s0, s64
	s_lshl_b32 s20, s0, 7
	s_ashr_i32 s21, s20, 31
	s_lshl_b64 s[20:21], s[20:21], 8
	s_add_u32 s20, s23, s20
	v_mbcnt_lo_u32_b32 v64, -1, 0
	v_mbcnt_hi_u32_b32 v64, -1, v64
	s_addc_u32 s21, s45, s21
	v_lshlrev_b32_e32 v128, 4, v64
	global_load_dwordx4 v[0:3], v128, s[20:21]
	global_load_dwordx4 v[4:7], v128, s[20:21] offset:1024
	s_waitcnt lgkmcnt(0)
	global_load_dwordx4 v[8:11], v128, s[20:21] offset:2048
	global_load_dwordx4 v[12:15], v128, s[20:21] offset:3072
	v_lshl_add_u64 v[140:141], s[20:21], 0, v[128:129]
	s_movk_i32 s0, 0x1000
	v_add_co_u32_e32 v16, vcc, s0, v140
	s_movk_i32 s0, 0x2000
	s_nop 0
	v_addc_co_u32_e32 v17, vcc, 0, v141, vcc
	v_add_co_u32_e32 v28, vcc, s0, v140
	s_movk_i32 s0, 0x3000
	s_nop 0
	v_addc_co_u32_e32 v29, vcc, 0, v141, vcc
	global_load_dwordx4 v[48:51], v[28:29], off offset:-4096
	global_load_dwordx4 v[52:55], v[16:17], off offset:1024
	global_load_dwordx4 v[56:59], v[16:17], off offset:2048
	global_load_dwordx4 v[60:63], v[16:17], off offset:3072
	s_nop 0
	global_load_dwordx4 v[16:19], v[28:29], off
	global_load_dwordx4 v[20:23], v[28:29], off offset:1024
	global_load_dwordx4 v[24:27], v[28:29], off offset:2048
	s_nop 0
	global_load_dwordx4 v[28:31], v[28:29], off offset:3072
	v_add_co_u32_e32 v44, vcc, s0, v140
	s_movk_i32 s0, 0x4000
	s_nop 0
	v_addc_co_u32_e32 v45, vcc, 0, v141, vcc
	v_and_b32_e32 v144, 15, v64
	v_add_co_u32_e32 v146, vcc, s0, v140
	s_and_b32 s0, s59, 0xfffff800
	v_ashrrev_i32_e32 v64, 1, v64
	s_or_b32 s20, s60, s0
	s_lshl_b32 s0, s64, 16
	v_and_b32_e32 v134, -8, v64
	s_add_u32 s60, s14, s0
	v_ashrrev_i32_e32 v135, 31, v134
	s_addc_u32 s61, s15, 0
	v_or_b32_e32 v143, s39, v144
	v_lshlrev_b64 v[132:133], 2, v[134:135]
	v_lshl_add_u64 v[72:73], s[60:61], 0, v[132:133]
	v_lshlrev_b32_e32 v128, 9, v143
	v_addc_co_u32_e32 v147, vcc, 0, v141, vcc
	v_lshl_add_u64 v[136:137], v[72:73], 0, v[128:129]
	global_load_dwordx4 v[32:35], v[146:147], off offset:-4096
	global_load_dwordx4 v[36:39], v[44:45], off offset:1024
	global_load_dwordx4 v[40:43], v[44:45], off offset:2048
	s_nop 0
	global_load_dwordx4 v[44:47], v[44:45], off offset:3072
	s_nop 0
	global_load_dwordx4 v[64:67], v[136:137], off offset:16
	global_load_dwordx4 v[68:71], v[136:137], off
	v_or_b32_e32 v128, 0x2000, v128
	v_lshl_add_u64 v[138:139], v[72:73], 0, v[128:129]
	global_load_dwordx4 v[72:75], v[138:139], off offset:16
	global_load_dwordx4 v[76:79], v[138:139], off
	s_movk_i32 s0, 0x5000
	s_waitcnt vmcnt(19)
	v_lshlrev_b32_e32 v80, 16, v0
	s_waitcnt vmcnt(18)
	v_lshlrev_b32_e32 v88, 16, v4
	v_mul_f32_e32 v88, v88, v88
	v_fmac_f32_e32 v88, v80, v80
	v_and_b32_e32 v80, 0xffff0000, v4
	v_mul_f32_e32 v89, v80, v80
	v_lshlrev_b32_e32 v80, 16, v5
	v_lshlrev_b32_e32 v82, 16, v1
	v_mul_f32_e32 v90, v80, v80
	v_and_b32_e32 v80, 0xffff0000, v5
	v_and_b32_e32 v83, 0xffff0000, v1
	v_fmac_f32_e32 v90, v82, v82
	v_mul_f32_e32 v82, v80, v80
	v_lshlrev_b32_e32 v80, 16, v6
	v_lshlrev_b32_e32 v84, 16, v2
	v_fmac_f32_e32 v82, v83, v83
	v_mul_f32_e32 v83, v80, v80
	v_and_b32_e32 v80, 0xffff0000, v6
	v_and_b32_e32 v85, 0xffff0000, v2
	v_fmac_f32_e32 v83, v84, v84
	v_mul_f32_e32 v84, v80, v80
	v_lshlrev_b32_e32 v80, 16, v7
	v_lshlrev_b32_e32 v86, 16, v3
	v_fmac_f32_e32 v84, v85, v85
	v_mul_f32_e32 v85, v80, v80
	v_and_b32_e32 v80, 0xffff0000, v7
	v_and_b32_e32 v81, 0xffff0000, v0
	v_fmac_f32_e32 v85, v86, v86
	v_mul_f32_e32 v86, v80, v80
	s_waitcnt vmcnt(17)
	v_lshlrev_b32_e32 v80, 16, v8
	v_fmac_f32_e32 v89, v81, v81
	v_fmac_f32_e32 v88, v80, v80
	v_and_b32_e32 v80, 0xffff0000, v8
	v_fmac_f32_e32 v89, v80, v80
	v_lshlrev_b32_e32 v80, 16, v9
	v_fmac_f32_e32 v90, v80, v80
	v_and_b32_e32 v80, 0xffff0000, v9
	v_fmac_f32_e32 v82, v80, v80
	v_lshlrev_b32_e32 v80, 16, v10
	v_fmac_f32_e32 v83, v80, v80
	v_and_b32_e32 v80, 0xffff0000, v10
	v_and_b32_e32 v87, 0xffff0000, v3
	v_fmac_f32_e32 v84, v80, v80
	v_lshlrev_b32_e32 v80, 16, v11
	v_fmac_f32_e32 v86, v87, v87
	v_fmac_f32_e32 v85, v80, v80
	v_and_b32_e32 v80, 0xffff0000, v11
	v_fmac_f32_e32 v86, v80, v80
	s_waitcnt vmcnt(16)
	v_lshlrev_b32_e32 v80, 16, v12
	v_fmac_f32_e32 v88, v80, v80
	v_and_b32_e32 v80, 0xffff0000, v12
	v_fmac_f32_e32 v89, v80, v80
	v_lshlrev_b32_e32 v80, 16, v13
	v_fmac_f32_e32 v90, v80, v80
	v_and_b32_e32 v80, 0xffff0000, v13
	v_fmac_f32_e32 v82, v80, v80
	v_lshlrev_b32_e32 v80, 16, v14
	v_fmac_f32_e32 v83, v80, v80
	v_and_b32_e32 v80, 0xffff0000, v14
	v_fmac_f32_e32 v84, v80, v80
	v_lshlrev_b32_e32 v80, 16, v15
	v_fmac_f32_e32 v85, v80, v80
	v_and_b32_e32 v80, 0xffff0000, v15
	v_fmac_f32_e32 v86, v80, v80
	s_waitcnt vmcnt(15)
	v_lshlrev_b32_e32 v80, 16, v48
	v_fmac_f32_e32 v88, v80, v80
	v_and_b32_e32 v80, 0xffff0000, v48
	v_fmac_f32_e32 v89, v80, v80
	v_lshlrev_b32_e32 v80, 16, v49
	v_fmac_f32_e32 v90, v80, v80
	v_and_b32_e32 v80, 0xffff0000, v49
	v_fmac_f32_e32 v82, v80, v80
	v_lshlrev_b32_e32 v80, 16, v50
	v_fmac_f32_e32 v83, v80, v80
	v_and_b32_e32 v80, 0xffff0000, v50
	v_fmac_f32_e32 v84, v80, v80
	v_lshlrev_b32_e32 v80, 16, v51
	v_fmac_f32_e32 v85, v80, v80
	v_and_b32_e32 v80, 0xffff0000, v51
	v_fmac_f32_e32 v86, v80, v80
	s_waitcnt vmcnt(14)
	v_lshlrev_b32_e32 v80, 16, v52
	v_fmac_f32_e32 v88, v80, v80
	v_and_b32_e32 v80, 0xffff0000, v52
	v_fmac_f32_e32 v89, v80, v80
	v_lshlrev_b32_e32 v80, 16, v53
	v_fmac_f32_e32 v90, v80, v80
	v_and_b32_e32 v80, 0xffff0000, v53
	v_fmac_f32_e32 v82, v80, v80
	v_lshlrev_b32_e32 v80, 16, v54
	v_fmac_f32_e32 v83, v80, v80
	v_and_b32_e32 v80, 0xffff0000, v54
	v_fmac_f32_e32 v84, v80, v80
	v_lshlrev_b32_e32 v80, 16, v55
	v_fmac_f32_e32 v85, v80, v80
	v_and_b32_e32 v80, 0xffff0000, v55
	v_fmac_f32_e32 v86, v80, v80
	s_waitcnt vmcnt(12)
	v_lshlrev_b32_e32 v81, 16, v60
	v_lshlrev_b32_e32 v80, 16, v56
	v_pk_mul_f32 v[80:81], v[80:81], v[80:81]
	s_waitcnt vmcnt(10)
	v_lshlrev_b32_e32 v171, 16, v20
	v_add_f32_e32 v80, v88, v80
	v_add_f32_e32 v87, v80, v81
	v_and_b32_e32 v81, 0xffff0000, v60
	v_and_b32_e32 v80, 0xffff0000, v56
	v_pk_mul_f32 v[80:81], v[80:81], v[80:81]
	v_lshlrev_b32_e32 v128, 16, v16
	v_add_f32_e32 v80, v89, v80
	v_add_f32_e32 v88, v80, v81
	v_lshlrev_b32_e32 v81, 16, v61
	v_lshlrev_b32_e32 v80, 16, v57
	v_pk_mul_f32 v[80:81], v[80:81], v[80:81]
	v_mul_f32_e32 v171, v171, v171
	v_add_f32_e32 v80, v90, v80
	v_add_f32_e32 v89, v80, v81
	v_and_b32_e32 v81, 0xffff0000, v61
	v_and_b32_e32 v80, 0xffff0000, v57
	v_pk_mul_f32 v[80:81], v[80:81], v[80:81]
	v_fmac_f32_e32 v171, v128, v128
	v_add_f32_e32 v80, v82, v80
	v_add_f32_e32 v82, v80, v81
	v_lshlrev_b32_e32 v81, 16, v62
	v_lshlrev_b32_e32 v80, 16, v58
	v_pk_mul_f32 v[80:81], v[80:81], v[80:81]
	v_add_f32_dpp v82, v82, v82 row_ror:8 row_mask:0xf bank_mask:0xf bound_ctrl:1
	v_add_f32_e32 v80, v83, v80
	v_add_f32_e32 v83, v80, v81
	v_and_b32_e32 v81, 0xffff0000, v62
	v_and_b32_e32 v80, 0xffff0000, v58
	v_pk_mul_f32 v[80:81], v[80:81], v[80:81]
	v_add_f32_dpp v83, v83, v83 row_ror:8 row_mask:0xf bank_mask:0xf bound_ctrl:1
	v_add_f32_e32 v80, v84, v80
	v_add_f32_e32 v84, v80, v81
	v_lshlrev_b32_e32 v81, 16, v63
	v_lshlrev_b32_e32 v80, 16, v59
	v_pk_mul_f32 v[80:81], v[80:81], v[80:81]
	v_add_f32_dpp v84, v84, v84 row_ror:8 row_mask:0xf bank_mask:0xf bound_ctrl:1
	v_add_f32_e32 v80, v85, v80
	v_add_f32_e32 v85, v80, v81
	v_and_b32_e32 v81, 0xffff0000, v63
	v_and_b32_e32 v80, 0xffff0000, v59
	v_pk_mul_f32 v[80:81], v[80:81], v[80:81]
	v_add_f32_dpp v83, v83, v83 row_ror:4 row_mask:0xf bank_mask:0xf bound_ctrl:1
	v_add_f32_e32 v80, v86, v80
	v_add_f32_e32 v80, v80, v81
	v_add_f32_dpp v81, v87, v87 row_ror:8 row_mask:0xf bank_mask:0xf bound_ctrl:1
	v_add_f32_dpp v86, v88, v88 row_ror:8 row_mask:0xf bank_mask:0xf bound_ctrl:1
	v_add_f32_dpp v87, v89, v89 row_ror:8 row_mask:0xf bank_mask:0xf bound_ctrl:1
	v_add_f32_dpp v81, v81, v81 row_ror:4 row_mask:0xf bank_mask:0xf bound_ctrl:1
	v_add_f32_dpp v86, v86, v86 row_ror:4 row_mask:0xf bank_mask:0xf bound_ctrl:1
	v_add_f32_dpp v84, v84, v84 row_ror:4 row_mask:0xf bank_mask:0xf bound_ctrl:1
	v_add_f32_dpp v85, v85, v85 row_ror:8 row_mask:0xf bank_mask:0xf bound_ctrl:1
	v_add_f32_dpp v80, v80, v80 row_ror:8 row_mask:0xf bank_mask:0xf bound_ctrl:1
	v_add_f32_dpp v81, v81, v81 row_ror:2 row_mask:0xf bank_mask:0xf bound_ctrl:1
	v_add_f32_dpp v86, v86, v86 row_ror:2 row_mask:0xf bank_mask:0xf bound_ctrl:1
	v_add_f32_dpp v87, v87, v87 row_ror:4 row_mask:0xf bank_mask:0xf bound_ctrl:1
	v_add_f32_dpp v82, v82, v82 row_ror:4 row_mask:0xf bank_mask:0xf bound_ctrl:1
	v_add_f32_dpp v83, v83, v83 row_ror:2 row_mask:0xf bank_mask:0xf bound_ctrl:1
	v_add_f32_dpp v84, v84, v84 row_ror:2 row_mask:0xf bank_mask:0xf bound_ctrl:1
	v_add_f32_dpp v85, v85, v85 row_ror:4 row_mask:0xf bank_mask:0xf bound_ctrl:1
	v_add_f32_dpp v80, v80, v80 row_ror:4 row_mask:0xf bank_mask:0xf bound_ctrl:1
	v_add_f32_dpp v81, v81, v81 row_ror:1 row_mask:0xf bank_mask:0xf bound_ctrl:1
	v_add_f32_dpp v86, v86, v86 row_ror:1 row_mask:0xf bank_mask:0xf bound_ctrl:1
	v_add_f32_dpp v87, v87, v87 row_ror:2 row_mask:0xf bank_mask:0xf bound_ctrl:1
	v_add_f32_dpp v82, v82, v82 row_ror:2 row_mask:0xf bank_mask:0xf bound_ctrl:1
	v_add_f32_dpp v83, v83, v83 row_ror:1 row_mask:0xf bank_mask:0xf bound_ctrl:1
	v_add_f32_dpp v84, v84, v84 row_ror:1 row_mask:0xf bank_mask:0xf bound_ctrl:1
	v_add_f32_dpp v85, v85, v85 row_ror:2 row_mask:0xf bank_mask:0xf bound_ctrl:1
	v_add_f32_dpp v80, v80, v80 row_ror:2 row_mask:0xf bank_mask:0xf bound_ctrl:1
	v_fmamk_f32 v81, v81, 0x3c000000, v142
	v_fmamk_f32 v86, v86, 0x3c000000, v142
	v_add_f32_dpp v87, v87, v87 row_ror:1 row_mask:0xf bank_mask:0xf bound_ctrl:1
	v_add_f32_dpp v82, v82, v82 row_ror:1 row_mask:0xf bank_mask:0xf bound_ctrl:1
	v_fmamk_f32 v83, v83, 0x3c000000, v142
	v_fmamk_f32 v84, v84, 0x3c000000, v142
	v_add_f32_dpp v85, v85, v85 row_ror:1 row_mask:0xf bank_mask:0xf bound_ctrl:1
	v_add_f32_dpp v80, v80, v80 row_ror:1 row_mask:0xf bank_mask:0xf bound_ctrl:1
	v_rsq_f32_e32 v81, v81
	v_rsq_f32_e32 v86, v86
	v_fmamk_f32 v87, v87, 0x3c000000, v142
	v_fmamk_f32 v82, v82, 0x3c000000, v142
	v_rsq_f32_e32 v83, v83
	v_rsq_f32_e32 v84, v84
	v_fmamk_f32 v85, v85, 0x3c000000, v142
	v_fmamk_f32 v80, v80, 0x3c000000, v142
	v_rsq_f32_e32 v87, v87
	v_rsq_f32_e32 v82, v82
	v_rsq_f32_e32 v85, v85
	v_rsq_f32_e32 v80, v80
	s_waitcnt vmcnt(2)
	v_mul_f32_e32 v68, v81, v68
	v_mul_f32_e32 v69, v86, v69
	v_mul_f32_e32 v64, v83, v64
	v_mul_f32_e32 v65, v84, v65
	v_cvt_pk_bf16_f32 v92, v68, v69
	v_mul_f32_e32 v68, v87, v70
	v_mul_f32_e32 v69, v82, v71
	v_cvt_pk_bf16_f32 v93, v68, v69
	v_cvt_pk_bf16_f32 v94, v64, v65
	v_mul_f32_e32 v64, v85, v66
	v_mul_f32_e32 v65, v80, v67
	v_cvt_pk_bf16_f32 v95, v64, v65
	s_waitcnt vmcnt(0)
	v_mul_f32_e32 v64, v81, v76
	v_mul_f32_e32 v65, v86, v77
	v_cvt_pk_bf16_f32 v124, v64, v65
	v_mul_f32_e32 v64, v87, v78
	v_mul_f32_e32 v65, v82, v79
	v_cvt_pk_bf16_f32 v125, v64, v65
	v_mul_f32_e32 v64, v83, v72
	v_mul_f32_e32 v65, v84, v73
	v_cvt_pk_bf16_f32 v126, v64, v65
	v_mul_f32_e32 v64, v85, v74
	v_mul_f32_e32 v65, v80, v75
	v_cvt_pk_bf16_f32 v127, v64, v65
	v_mfma_f32_16x16x32_bf16 v[64:67], v[0:3], v[92:95], 0
	v_and_b32_e32 v128, 0xffff0000, v20
	v_and_b32_e32 v145, 0xffff0000, v16
	v_mfma_f32_16x16x32_bf16 v[68:71], v[4:7], v[92:95], 0
	v_mul_f32_e32 v128, v128, v128
	v_fmac_f32_e32 v128, v145, v145
	v_lshlrev_b32_e32 v145, 16, v21
	v_mfma_f32_16x16x32_bf16 v[72:75], v[8:11], v[92:95], 0
	v_lshlrev_b32_e32 v164, 16, v17
	v_mul_f32_e32 v145, v145, v145
	v_fmac_f32_e32 v145, v164, v164
	v_mfma_f32_16x16x32_bf16 v[76:79], v[12:15], v[92:95], 0
	v_and_b32_e32 v164, 0xffff0000, v21
	v_mul_f32_e32 v172, v164, v164
	v_lshlrev_b32_e32 v164, 16, v22
	v_mfma_f32_16x16x32_bf16 v[80:83], v[48:51], v[92:95], 0
	v_lshlrev_b32_e32 v167, 16, v18
	v_mul_f32_e32 v173, v164, v164
	v_and_b32_e32 v164, 0xffff0000, v22
	v_mfma_f32_16x16x32_bf16 v[84:87], v[52:55], v[92:95], 0
	v_and_b32_e32 v168, 0xffff0000, v18
	v_fmac_f32_e32 v173, v167, v167
	v_mul_f32_e32 v167, v164, v164
	v_mfma_f32_16x16x32_bf16 v[88:91], v[56:59], v[92:95], 0
	v_lshlrev_b32_e32 v164, 16, v23
	v_lshlrev_b32_e32 v169, 16, v19
	v_fmac_f32_e32 v167, v168, v168
	v_mfma_f32_16x16x32_bf16 v[92:95], v[60:63], v[92:95], 0
	v_mul_f32_e32 v168, v164, v164
	v_and_b32_e32 v164, 0xffff0000, v23
	v_fmac_f32_e32 v168, v169, v169
	v_mfma_f32_16x16x32_bf16 v[96:99], v[0:3], v[124:127], 0
	v_mul_f32_e32 v169, v164, v164
	v_lshlrev_b32_e32 v164, 16, v24
	v_fmac_f32_e32 v171, v164, v164
	v_mfma_f32_16x16x32_bf16 v[100:103], v[4:7], v[124:127], 0
	v_and_b32_e32 v164, 0xffff0000, v24
	v_and_b32_e32 v165, 0xffff0000, v17
	v_fmac_f32_e32 v128, v164, v164
	v_mfma_f32_16x16x32_bf16 v[104:107], v[8:11], v[124:127], 0
	v_lshlrev_b32_e32 v164, 16, v25
	v_fmac_f32_e32 v172, v165, v165
	v_fmac_f32_e32 v145, v164, v164
	v_mfma_f32_16x16x32_bf16 v[108:111], v[12:15], v[124:127], 0
	global_load_dwordx4 v[0:3], v[146:147], off
	global_load_dwordx4 v[4:7], v[146:147], off offset:1024
	global_load_dwordx4 v[8:11], v[146:147], off offset:2048
	global_load_dwordx4 v[12:15], v[146:147], off offset:3072
	v_and_b32_e32 v164, 0xffff0000, v25
	v_fmac_f32_e32 v172, v164, v164
	v_mfma_f32_16x16x32_bf16 v[112:115], v[48:51], v[124:127], 0
	v_lshlrev_b32_e32 v164, 16, v26
	v_fmac_f32_e32 v173, v164, v164
	v_and_b32_e32 v164, 0xffff0000, v26
	v_mfma_f32_16x16x32_bf16 v[116:119], v[52:55], v[124:127], 0
	v_and_b32_e32 v170, 0xffff0000, v19
	v_fmac_f32_e32 v167, v164, v164
	v_lshlrev_b32_e32 v164, 16, v27
	v_mfma_f32_16x16x32_bf16 v[120:123], v[56:59], v[124:127], 0
	v_fmac_f32_e32 v169, v170, v170
	v_fmac_f32_e32 v168, v164, v164
	v_and_b32_e32 v164, 0xffff0000, v27
	v_mfma_f32_16x16x32_bf16 v[124:127], v[60:63], v[124:127], 0
	v_add_co_u32_e32 v60, vcc, s0, v140
	s_movk_i32 s0, 0x6000
	s_nop 0
	v_addc_co_u32_e32 v61, vcc, 0, v141, vcc
	v_add_co_u32_e32 v162, vcc, s0, v140
	v_fmac_f32_e32 v169, v164, v164
	s_nop 0
	v_addc_co_u32_e32 v163, vcc, 0, v141, vcc
	global_load_dwordx4 v[48:51], v[162:163], off offset:-4096
	global_load_dwordx4 v[52:55], v[60:61], off offset:1024
	global_load_dwordx4 v[56:59], v[60:61], off offset:2048
	s_nop 0
	global_load_dwordx4 v[60:63], v[60:61], off offset:3072
	s_nop 0
	global_load_dwordx4 v[146:149], v[136:137], off offset:144
	global_load_dwordx4 v[150:153], v[136:137], off offset:128
	global_load_dwordx4 v[154:157], v[138:139], off offset:144
	global_load_dwordx4 v[158:161], v[138:139], off offset:128
	v_lshlrev_b32_e32 v164, 16, v28
	v_fmac_f32_e32 v171, v164, v164
	v_and_b32_e32 v164, 0xffff0000, v28
	v_fmac_f32_e32 v128, v164, v164
	v_lshlrev_b32_e32 v164, 16, v29
	v_fmac_f32_e32 v145, v164, v164
	v_and_b32_e32 v164, 0xffff0000, v29
	v_fmac_f32_e32 v172, v164, v164
	v_lshlrev_b32_e32 v164, 16, v30
	v_fmac_f32_e32 v173, v164, v164
	v_and_b32_e32 v164, 0xffff0000, v30
	v_fmac_f32_e32 v167, v164, v164
	v_lshlrev_b32_e32 v164, 16, v31
	v_fmac_f32_e32 v168, v164, v164
	v_and_b32_e32 v164, 0xffff0000, v31
	v_fmac_f32_e32 v169, v164, v164
	v_lshlrev_b32_e32 v164, 16, v32
	v_fmac_f32_e32 v171, v164, v164
	v_and_b32_e32 v164, 0xffff0000, v32
	v_fmac_f32_e32 v128, v164, v164
	v_lshlrev_b32_e32 v164, 16, v33
	v_fmac_f32_e32 v145, v164, v164
	v_and_b32_e32 v164, 0xffff0000, v33
	v_fmac_f32_e32 v172, v164, v164
	v_lshlrev_b32_e32 v164, 16, v34
	v_fmac_f32_e32 v173, v164, v164
	v_and_b32_e32 v164, 0xffff0000, v34
	v_fmac_f32_e32 v167, v164, v164
	v_lshlrev_b32_e32 v164, 16, v35
	v_fmac_f32_e32 v168, v164, v164
	v_and_b32_e32 v164, 0xffff0000, v35
	v_fmac_f32_e32 v169, v164, v164
	v_lshlrev_b32_e32 v164, 16, v36
	v_fmac_f32_e32 v171, v164, v164
	v_and_b32_e32 v164, 0xffff0000, v36
	v_fmac_f32_e32 v128, v164, v164
	v_lshlrev_b32_e32 v164, 16, v37
	v_fmac_f32_e32 v145, v164, v164
	v_and_b32_e32 v164, 0xffff0000, v37
	v_fmac_f32_e32 v172, v164, v164
	v_lshlrev_b32_e32 v164, 16, v38
	v_fmac_f32_e32 v173, v164, v164
	v_and_b32_e32 v164, 0xffff0000, v38
	v_fmac_f32_e32 v167, v164, v164
	v_lshlrev_b32_e32 v164, 16, v39
	v_fmac_f32_e32 v168, v164, v164
	v_and_b32_e32 v164, 0xffff0000, v39
	v_fmac_f32_e32 v169, v164, v164
	v_lshlrev_b32_e32 v165, 16, v44
	v_lshlrev_b32_e32 v164, 16, v40
	v_pk_mul_f32 v[164:165], v[164:165], v[164:165]
	s_movk_i32 s0, 0x7000
	v_add_f32_e32 v164, v171, v164
	v_add_f32_e32 v170, v164, v165
	v_and_b32_e32 v165, 0xffff0000, v44
	v_and_b32_e32 v164, 0xffff0000, v40
	v_pk_mul_f32 v[164:165], v[164:165], v[164:165]
	s_nop 0
	v_add_f32_e32 v128, v128, v164
	v_add_f32_e32 v128, v128, v165
	v_lshlrev_b32_e32 v165, 16, v45
	v_lshlrev_b32_e32 v164, 16, v41
	v_pk_mul_f32 v[164:165], v[164:165], v[164:165]
	v_add_f32_dpp v128, v128, v128 row_ror:8 row_mask:0xf bank_mask:0xf bound_ctrl:1
	v_add_f32_e32 v145, v145, v164
	v_add_f32_e32 v145, v145, v165
	v_and_b32_e32 v165, 0xffff0000, v45
	v_and_b32_e32 v164, 0xffff0000, v41
	v_pk_mul_f32 v[164:165], v[164:165], v[164:165]
	v_add_f32_dpp v128, v128, v128 row_ror:4 row_mask:0xf bank_mask:0xf bound_ctrl:1
	v_add_f32_e32 v164, v172, v164
	v_add_f32_e32 v171, v164, v165
	v_lshlrev_b32_e32 v165, 16, v46
	v_lshlrev_b32_e32 v164, 16, v42
	v_pk_mul_f32 v[164:165], v[164:165], v[164:165]
	v_add_f32_dpp v145, v145, v145 row_ror:8 row_mask:0xf bank_mask:0xf bound_ctrl:1
	v_add_f32_e32 v164, v173, v164
	v_add_f32_e32 v172, v164, v165
	v_and_b32_e32 v165, 0xffff0000, v46
	v_and_b32_e32 v164, 0xffff0000, v42
	v_pk_mul_f32 v[164:165], v[164:165], v[164:165]
	v_add_f32_dpp v128, v128, v128 row_ror:2 row_mask:0xf bank_mask:0xf bound_ctrl:1
	v_add_f32_e32 v164, v167, v164
	v_add_f32_e32 v167, v164, v165
	v_lshlrev_b32_e32 v165, 16, v47
	v_lshlrev_b32_e32 v164, 16, v43
	v_pk_mul_f32 v[164:165], v[164:165], v[164:165]
	v_add_f32_dpp v145, v145, v145 row_ror:4 row_mask:0xf bank_mask:0xf bound_ctrl:1
	v_add_f32_e32 v164, v168, v164
	v_add_f32_e32 v168, v164, v165
	v_and_b32_e32 v165, 0xffff0000, v47
	v_and_b32_e32 v164, 0xffff0000, v43
	v_pk_mul_f32 v[164:165], v[164:165], v[164:165]
	v_add_f32_dpp v167, v167, v167 row_ror:8 row_mask:0xf bank_mask:0xf bound_ctrl:1
	v_add_f32_e32 v164, v169, v164
	v_add_f32_e32 v164, v164, v165
	v_add_f32_dpp v165, v170, v170 row_ror:8 row_mask:0xf bank_mask:0xf bound_ctrl:1
	v_add_f32_dpp v169, v171, v171 row_ror:8 row_mask:0xf bank_mask:0xf bound_ctrl:1
	v_add_f32_dpp v170, v172, v172 row_ror:8 row_mask:0xf bank_mask:0xf bound_ctrl:1
	v_add_f32_dpp v165, v165, v165 row_ror:4 row_mask:0xf bank_mask:0xf bound_ctrl:1
	v_add_f32_dpp v169, v169, v169 row_ror:4 row_mask:0xf bank_mask:0xf bound_ctrl:1
	v_add_f32_dpp v170, v170, v170 row_ror:4 row_mask:0xf bank_mask:0xf bound_ctrl:1
	v_add_f32_dpp v165, v165, v165 row_ror:2 row_mask:0xf bank_mask:0xf bound_ctrl:1
	v_add_f32_dpp v168, v168, v168 row_ror:8 row_mask:0xf bank_mask:0xf bound_ctrl:1
	v_add_f32_dpp v128, v128, v128 row_ror:1 row_mask:0xf bank_mask:0xf bound_ctrl:1
	v_add_f32_dpp v165, v165, v165 row_ror:1 row_mask:0xf bank_mask:0xf bound_ctrl:1
	v_add_f32_dpp v145, v145, v145 row_ror:2 row_mask:0xf bank_mask:0xf bound_ctrl:1
	v_add_f32_dpp v169, v169, v169 row_ror:2 row_mask:0xf bank_mask:0xf bound_ctrl:1
	v_add_f32_dpp v170, v170, v170 row_ror:2 row_mask:0xf bank_mask:0xf bound_ctrl:1
	v_add_f32_dpp v167, v167, v167 row_ror:4 row_mask:0xf bank_mask:0xf bound_ctrl:1
	v_add_f32_dpp v168, v168, v168 row_ror:4 row_mask:0xf bank_mask:0xf bound_ctrl:1
	v_add_f32_dpp v164, v164, v164 row_ror:8 row_mask:0xf bank_mask:0xf bound_ctrl:1
	v_fmamk_f32 v165, v165, 0x3c000000, v142
	v_fmamk_f32 v128, v128, 0x3c000000, v142
	v_add_f32_dpp v145, v145, v145 row_ror:1 row_mask:0xf bank_mask:0xf bound_ctrl:1
	v_add_f32_dpp v169, v169, v169 row_ror:1 row_mask:0xf bank_mask:0xf bound_ctrl:1
	v_add_f32_dpp v170, v170, v170 row_ror:1 row_mask:0xf bank_mask:0xf bound_ctrl:1
	v_add_f32_dpp v167, v167, v167 row_ror:2 row_mask:0xf bank_mask:0xf bound_ctrl:1
	v_add_f32_dpp v168, v168, v168 row_ror:2 row_mask:0xf bank_mask:0xf bound_ctrl:1
	v_add_f32_dpp v164, v164, v164 row_ror:4 row_mask:0xf bank_mask:0xf bound_ctrl:1
	v_rsq_f32_e32 v165, v165
	v_rsq_f32_e32 v128, v128
	v_fmamk_f32 v145, v145, 0x3c000000, v142
	v_fmamk_f32 v169, v169, 0x3c000000, v142
	v_fmamk_f32 v170, v170, 0x3c000000, v142
	v_add_f32_dpp v167, v167, v167 row_ror:1 row_mask:0xf bank_mask:0xf bound_ctrl:1
	v_add_f32_dpp v168, v168, v168 row_ror:1 row_mask:0xf bank_mask:0xf bound_ctrl:1
	v_add_f32_dpp v164, v164, v164 row_ror:2 row_mask:0xf bank_mask:0xf bound_ctrl:1
	v_rsq_f32_e32 v145, v145
	v_rsq_f32_e32 v169, v169
	v_rsq_f32_e32 v170, v170
	v_fmamk_f32 v167, v167, 0x3c000000, v142
	v_fmamk_f32 v168, v168, 0x3c000000, v142
	v_add_f32_dpp v164, v164, v164 row_ror:1 row_mask:0xf bank_mask:0xf bound_ctrl:1
	v_rsq_f32_e32 v167, v167
	v_rsq_f32_e32 v168, v168
	v_fmamk_f32 v164, v164, 0x3c000000, v142
	v_rsq_f32_e32 v164, v164
	s_waitcnt vmcnt(2)
	v_mul_f32_e32 v150, v165, v150
	v_mul_f32_e32 v151, v128, v151
	v_cvt_pk_bf16_f32 v150, v150, v151
	v_mul_f32_e32 v151, v145, v152
	v_mul_f32_e32 v152, v169, v153
	v_mul_f32_e32 v146, v170, v146
	v_cvt_pk_bf16_f32 v151, v151, v152
	v_mul_f32_e32 v147, v167, v147
	v_cvt_pk_bf16_f32 v152, v146, v147
	v_mul_f32_e32 v146, v168, v148
	v_mul_f32_e32 v147, v164, v149
	v_cvt_pk_bf16_f32 v153, v146, v147
	s_waitcnt vmcnt(0)
	v_mul_f32_e32 v146, v165, v158
	v_mul_f32_e32 v128, v128, v159
	v_cvt_pk_bf16_f32 v146, v146, v128
	v_mul_f32_e32 v128, v145, v160
	v_mul_f32_e32 v145, v169, v161
	v_cvt_pk_bf16_f32 v147, v128, v145
	v_mul_f32_e32 v128, v170, v154
	v_mul_f32_e32 v145, v167, v155
	v_cvt_pk_bf16_f32 v148, v128, v145
	v_mul_f32_e32 v128, v168, v156
	v_mul_f32_e32 v145, v164, v157
	v_cvt_pk_bf16_f32 v149, v128, v145
	v_mfma_f32_16x16x32_bf16 v[92:95], v[44:47], v[150:153], v[92:95]
	v_lshlrev_b32_e32 v167, 16, v4
	v_lshlrev_b32_e32 v128, 16, v0
	v_mfma_f32_16x16x32_bf16 v[44:47], v[44:47], v[146:149], v[124:127]
	v_mul_f32_e32 v167, v167, v167
	v_fmac_f32_e32 v167, v128, v128
	v_and_b32_e32 v128, 0xffff0000, v4
	v_add_co_u32_e32 v124, vcc, s0, v140
	v_mfma_f32_16x16x32_bf16 v[64:67], v[16:19], v[150:153], v[64:67]
	s_nop 0
	v_addc_co_u32_e32 v125, vcc, 0, v141, vcc
	v_and_b32_e32 v140, 0xffff0000, v0
	v_mfma_f32_16x16x32_bf16 v[68:71], v[20:23], v[150:153], v[68:71]
	v_mul_f32_e32 v128, v128, v128
	v_fmac_f32_e32 v128, v140, v140
	v_lshlrev_b32_e32 v140, 16, v5
	v_mfma_f32_16x16x32_bf16 v[72:75], v[24:27], v[150:153], v[72:75]
	v_mul_f32_e32 v168, v140, v140
	v_and_b32_e32 v140, 0xffff0000, v5
	v_and_b32_e32 v145, 0xffff0000, v1
	v_mfma_f32_16x16x32_bf16 v[76:79], v[28:31], v[150:153], v[76:79]
	v_mul_f32_e32 v169, v140, v140
	v_lshlrev_b32_e32 v140, 16, v6
	v_fmac_f32_e32 v169, v145, v145
	v_mfma_f32_16x16x32_bf16 v[80:83], v[32:35], v[150:153], v[80:83]
	v_mul_f32_e32 v145, v140, v140
	v_and_b32_e32 v140, 0xffff0000, v6
	v_lshlrev_b32_e32 v164, 16, v3
	v_mfma_f32_16x16x32_bf16 v[84:87], v[36:39], v[150:153], v[84:87]
	v_lshlrev_b32_e32 v141, 16, v1
	v_fmac_f32_e32 v168, v141, v141
	v_and_b32_e32 v165, 0xffff0000, v3
	v_mfma_f32_16x16x32_bf16 v[88:91], v[40:43], v[150:153], v[88:91]
	v_lshlrev_b32_e32 v141, 16, v60
	s_or_b32 s0, s39, s20
	v_mfma_f32_16x16x32_bf16 v[96:99], v[16:19], v[146:149], v[96:99]
	v_mfma_f32_16x16x32_bf16 v[100:103], v[20:23], v[146:149], v[100:103]
	v_mfma_f32_16x16x32_bf16 v[24:27], v[24:27], v[146:149], v[104:107]
	v_mfma_f32_16x16x32_bf16 v[28:31], v[28:31], v[146:149], v[108:111]
	v_mfma_f32_16x16x32_bf16 v[104:107], v[32:35], v[146:149], v[112:115]
	v_mfma_f32_16x16x32_bf16 v[108:111], v[36:39], v[146:149], v[116:119]
	global_load_dwordx4 v[16:19], v[162:163], off
	global_load_dwordx4 v[20:23], v[162:163], off offset:1024
	global_load_dwordx4 v[32:35], v[162:163], off offset:2048
	global_load_dwordx4 v[36:39], v[162:163], off offset:3072
	v_lshlrev_b32_e32 v162, 16, v2
	v_and_b32_e32 v163, 0xffff0000, v2
	v_mfma_f32_16x16x32_bf16 v[40:43], v[40:43], v[146:149], v[120:123]
	global_load_dwordx4 v[112:115], v[124:125], off
	global_load_dwordx4 v[116:119], v[124:125], off offset:1024
	s_nop 0
	global_load_dwordx4 v[120:123], v[124:125], off offset:2048
	s_nop 0
	global_load_dwordx4 v[124:127], v[124:125], off offset:3072
	s_nop 0
	global_load_dwordx4 v[146:149], v[136:137], off offset:272
	global_load_dwordx4 v[150:153], v[136:137], off offset:256
	global_load_dwordx4 v[154:157], v[138:139], off offset:272
	global_load_dwordx4 v[158:161], v[138:139], off offset:256
	v_fmac_f32_e32 v145, v162, v162
	v_mul_f32_e32 v162, v140, v140
	v_lshlrev_b32_e32 v140, 16, v7
	v_fmac_f32_e32 v162, v163, v163
	v_mul_f32_e32 v163, v140, v140
	v_and_b32_e32 v140, 0xffff0000, v7
	v_fmac_f32_e32 v163, v164, v164
	v_mul_f32_e32 v164, v140, v140
	v_lshlrev_b32_e32 v140, 16, v8
	v_fmac_f32_e32 v167, v140, v140
	v_and_b32_e32 v140, 0xffff0000, v8
	v_fmac_f32_e32 v128, v140, v140
	v_lshlrev_b32_e32 v140, 16, v9
	v_fmac_f32_e32 v168, v140, v140
	v_and_b32_e32 v140, 0xffff0000, v9
	v_fmac_f32_e32 v169, v140, v140
	v_lshlrev_b32_e32 v140, 16, v10
	v_fmac_f32_e32 v145, v140, v140
	v_and_b32_e32 v140, 0xffff0000, v10
	v_fmac_f32_e32 v162, v140, v140
	v_lshlrev_b32_e32 v140, 16, v11
	v_fmac_f32_e32 v164, v165, v165
	v_fmac_f32_e32 v163, v140, v140
	v_and_b32_e32 v140, 0xffff0000, v11
	v_fmac_f32_e32 v164, v140, v140
	v_lshlrev_b32_e32 v140, 16, v12
	v_fmac_f32_e32 v167, v140, v140
	v_and_b32_e32 v140, 0xffff0000, v12
	v_fmac_f32_e32 v128, v140, v140
	v_lshlrev_b32_e32 v140, 16, v13
	v_fmac_f32_e32 v168, v140, v140
	v_and_b32_e32 v140, 0xffff0000, v13
	v_fmac_f32_e32 v169, v140, v140
	v_lshlrev_b32_e32 v140, 16, v14
	v_fmac_f32_e32 v145, v140, v140
	v_and_b32_e32 v140, 0xffff0000, v14
	v_fmac_f32_e32 v162, v140, v140
	v_lshlrev_b32_e32 v140, 16, v15
	v_fmac_f32_e32 v163, v140, v140
	v_and_b32_e32 v140, 0xffff0000, v15
	v_fmac_f32_e32 v164, v140, v140
	v_lshlrev_b32_e32 v140, 16, v48
	v_fmac_f32_e32 v167, v140, v140
	v_and_b32_e32 v140, 0xffff0000, v48
	v_fmac_f32_e32 v128, v140, v140
	v_lshlrev_b32_e32 v140, 16, v49
	v_fmac_f32_e32 v168, v140, v140
	v_and_b32_e32 v140, 0xffff0000, v49
	v_fmac_f32_e32 v169, v140, v140
	v_lshlrev_b32_e32 v140, 16, v50
	v_fmac_f32_e32 v145, v140, v140
	v_and_b32_e32 v140, 0xffff0000, v50
	v_fmac_f32_e32 v162, v140, v140
	v_lshlrev_b32_e32 v140, 16, v51
	v_fmac_f32_e32 v163, v140, v140
	v_and_b32_e32 v140, 0xffff0000, v51
	v_fmac_f32_e32 v164, v140, v140
	v_lshlrev_b32_e32 v140, 16, v52
	v_fmac_f32_e32 v167, v140, v140
	v_and_b32_e32 v140, 0xffff0000, v52
	v_fmac_f32_e32 v128, v140, v140
	v_lshlrev_b32_e32 v140, 16, v53
	v_fmac_f32_e32 v168, v140, v140
	v_and_b32_e32 v140, 0xffff0000, v53
	v_fmac_f32_e32 v169, v140, v140
	v_lshlrev_b32_e32 v140, 16, v54
	v_fmac_f32_e32 v145, v140, v140
	v_and_b32_e32 v140, 0xffff0000, v54
	v_fmac_f32_e32 v162, v140, v140
	v_lshlrev_b32_e32 v140, 16, v55
	v_fmac_f32_e32 v163, v140, v140
	v_and_b32_e32 v140, 0xffff0000, v55
	v_fmac_f32_e32 v164, v140, v140
	v_lshlrev_b32_e32 v140, 16, v56
	v_pk_mul_f32 v[140:141], v[140:141], v[140:141]
	s_nop 0
	v_add_f32_e32 v140, v167, v140
	v_add_f32_e32 v165, v140, v141
	v_and_b32_e32 v141, 0xffff0000, v60
	v_and_b32_e32 v140, 0xffff0000, v56
	v_pk_mul_f32 v[140:141], v[140:141], v[140:141]
	s_nop 0
	v_add_f32_e32 v128, v128, v140
	v_add_f32_e32 v128, v128, v141
	v_lshlrev_b32_e32 v141, 16, v61
	v_lshlrev_b32_e32 v140, 16, v57
	v_pk_mul_f32 v[140:141], v[140:141], v[140:141]
	v_add_f32_dpp v128, v128, v128 row_ror:8 row_mask:0xf bank_mask:0xf bound_ctrl:1
	v_add_f32_e32 v140, v168, v140
	v_add_f32_e32 v167, v140, v141
	v_and_b32_e32 v141, 0xffff0000, v61
	v_and_b32_e32 v140, 0xffff0000, v57
	v_pk_mul_f32 v[140:141], v[140:141], v[140:141]
	v_add_f32_dpp v128, v128, v128 row_ror:4 row_mask:0xf bank_mask:0xf bound_ctrl:1
	v_add_f32_e32 v140, v169, v140
	v_add_f32_e32 v168, v140, v141
	v_lshlrev_b32_e32 v141, 16, v62
	v_lshlrev_b32_e32 v140, 16, v58
	v_pk_mul_f32 v[140:141], v[140:141], v[140:141]
	v_add_f32_dpp v128, v128, v128 row_ror:2 row_mask:0xf bank_mask:0xf bound_ctrl:1
	v_add_f32_e32 v140, v145, v140
	v_add_f32_e32 v145, v140, v141
	v_and_b32_e32 v141, 0xffff0000, v62
	v_and_b32_e32 v140, 0xffff0000, v58
	v_pk_mul_f32 v[140:141], v[140:141], v[140:141]
	v_add_f32_dpp v145, v145, v145 row_ror:8 row_mask:0xf bank_mask:0xf bound_ctrl:1
	v_add_f32_e32 v140, v162, v140
	v_add_f32_e32 v162, v140, v141
	v_lshlrev_b32_e32 v141, 16, v63
	v_lshlrev_b32_e32 v140, 16, v59
	v_pk_mul_f32 v[140:141], v[140:141], v[140:141]
	v_add_f32_dpp v145, v145, v145 row_ror:4 row_mask:0xf bank_mask:0xf bound_ctrl:1
	v_add_f32_e32 v140, v163, v140
	v_add_f32_e32 v163, v140, v141
	v_and_b32_e32 v141, 0xffff0000, v63
	v_and_b32_e32 v140, 0xffff0000, v59
	v_pk_mul_f32 v[140:141], v[140:141], v[140:141]
	v_add_f32_dpp v162, v162, v162 row_ror:8 row_mask:0xf bank_mask:0xf bound_ctrl:1
	v_add_f32_e32 v140, v164, v140
	v_add_f32_e32 v140, v140, v141
	v_add_f32_dpp v141, v165, v165 row_ror:8 row_mask:0xf bank_mask:0xf bound_ctrl:1
	v_add_f32_dpp v164, v167, v167 row_ror:8 row_mask:0xf bank_mask:0xf bound_ctrl:1
	v_add_f32_dpp v165, v168, v168 row_ror:8 row_mask:0xf bank_mask:0xf bound_ctrl:1
	v_add_f32_dpp v141, v141, v141 row_ror:4 row_mask:0xf bank_mask:0xf bound_ctrl:1
	v_add_f32_dpp v164, v164, v164 row_ror:4 row_mask:0xf bank_mask:0xf bound_ctrl:1
	v_add_f32_dpp v165, v165, v165 row_ror:4 row_mask:0xf bank_mask:0xf bound_ctrl:1
	v_add_f32_dpp v141, v141, v141 row_ror:2 row_mask:0xf bank_mask:0xf bound_ctrl:1
	v_add_f32_dpp v163, v163, v163 row_ror:8 row_mask:0xf bank_mask:0xf bound_ctrl:1
	v_add_f32_dpp v128, v128, v128 row_ror:1 row_mask:0xf bank_mask:0xf bound_ctrl:1
	v_add_f32_dpp v141, v141, v141 row_ror:1 row_mask:0xf bank_mask:0xf bound_ctrl:1
	v_add_f32_dpp v164, v164, v164 row_ror:2 row_mask:0xf bank_mask:0xf bound_ctrl:1
	v_add_f32_dpp v165, v165, v165 row_ror:2 row_mask:0xf bank_mask:0xf bound_ctrl:1
	v_add_f32_dpp v145, v145, v145 row_ror:2 row_mask:0xf bank_mask:0xf bound_ctrl:1
	v_add_f32_dpp v162, v162, v162 row_ror:4 row_mask:0xf bank_mask:0xf bound_ctrl:1
	v_add_f32_dpp v163, v163, v163 row_ror:4 row_mask:0xf bank_mask:0xf bound_ctrl:1
	v_add_f32_dpp v140, v140, v140 row_ror:8 row_mask:0xf bank_mask:0xf bound_ctrl:1
	v_fmamk_f32 v141, v141, 0x3c000000, v142
	v_fmamk_f32 v128, v128, 0x3c000000, v142
	v_add_f32_dpp v164, v164, v164 row_ror:1 row_mask:0xf bank_mask:0xf bound_ctrl:1
	v_add_f32_dpp v165, v165, v165 row_ror:1 row_mask:0xf bank_mask:0xf bound_ctrl:1
	v_add_f32_dpp v145, v145, v145 row_ror:1 row_mask:0xf bank_mask:0xf bound_ctrl:1
	v_add_f32_dpp v162, v162, v162 row_ror:2 row_mask:0xf bank_mask:0xf bound_ctrl:1
	v_add_f32_dpp v163, v163, v163 row_ror:2 row_mask:0xf bank_mask:0xf bound_ctrl:1
	v_add_f32_dpp v140, v140, v140 row_ror:4 row_mask:0xf bank_mask:0xf bound_ctrl:1
	v_rsq_f32_e32 v141, v141
	v_rsq_f32_e32 v128, v128
	v_fmamk_f32 v164, v164, 0x3c000000, v142
	v_fmamk_f32 v165, v165, 0x3c000000, v142
	v_fmamk_f32 v145, v145, 0x3c000000, v142
	v_add_f32_dpp v162, v162, v162 row_ror:1 row_mask:0xf bank_mask:0xf bound_ctrl:1
	v_add_f32_dpp v163, v163, v163 row_ror:1 row_mask:0xf bank_mask:0xf bound_ctrl:1
	v_add_f32_dpp v140, v140, v140 row_ror:2 row_mask:0xf bank_mask:0xf bound_ctrl:1
	v_rsq_f32_e32 v164, v164
	v_rsq_f32_e32 v165, v165
	v_rsq_f32_e32 v145, v145
	v_fmamk_f32 v162, v162, 0x3c000000, v142
	v_fmamk_f32 v163, v163, 0x3c000000, v142
	v_add_f32_dpp v140, v140, v140 row_ror:1 row_mask:0xf bank_mask:0xf bound_ctrl:1
	v_rsq_f32_e32 v162, v162
	v_rsq_f32_e32 v163, v163
	v_fmamk_f32 v140, v140, 0x3c000000, v142
	v_rsq_f32_e32 v140, v140
	s_waitcnt vmcnt(2)
	v_mul_f32_e32 v150, v141, v150
	v_mul_f32_e32 v151, v128, v151
	v_cvt_pk_bf16_f32 v150, v150, v151
	v_mul_f32_e32 v151, v164, v152
	v_mul_f32_e32 v152, v165, v153
	v_mul_f32_e32 v146, v145, v146
	v_cvt_pk_bf16_f32 v151, v151, v152
	v_mul_f32_e32 v147, v162, v147
	v_cvt_pk_bf16_f32 v152, v146, v147
	v_mul_f32_e32 v146, v163, v148
	s_waitcnt vmcnt(0)
	v_mul_f32_e32 v128, v128, v159
	v_mul_f32_e32 v147, v140, v149
	v_cvt_pk_bf16_f32 v153, v146, v147
	v_mul_f32_e32 v141, v141, v158
	v_cvt_pk_bf16_f32 v146, v141, v128
	v_mul_f32_e32 v128, v164, v160
	v_mul_f32_e32 v141, v165, v161
	v_cvt_pk_bf16_f32 v147, v128, v141
	v_mul_f32_e32 v128, v145, v154
	v_mul_f32_e32 v141, v162, v155
	v_cvt_pk_bf16_f32 v148, v128, v141
	v_mul_f32_e32 v128, v163, v156
	v_mul_f32_e32 v140, v140, v157
	v_cvt_pk_bf16_f32 v149, v128, v140
	v_mfma_f32_16x16x32_bf16 v[64:67], v[0:3], v[150:153], v[64:67]
	v_mfma_f32_16x16x32_bf16 v[68:71], v[4:7], v[150:153], v[68:71]
	v_mfma_f32_16x16x32_bf16 v[154:157], v[8:11], v[150:153], v[72:75]
	v_mfma_f32_16x16x32_bf16 v[158:161], v[12:15], v[150:153], v[76:79]
	s_nop 1
	v_lshlrev_b32_e32 v72, 16, v20
	v_mul_f32_e32 v72, v72, v72
	v_mfma_f32_16x16x32_bf16 v[80:83], v[48:51], v[150:153], v[80:83]
	v_mfma_f32_16x16x32_bf16 v[84:87], v[52:55], v[150:153], v[84:87]
	v_mfma_f32_16x16x32_bf16 v[0:3], v[0:3], v[146:149], v[96:99]
	v_mfma_f32_16x16x32_bf16 v[4:7], v[4:7], v[146:149], v[100:103]
	v_mfma_f32_16x16x32_bf16 v[8:11], v[8:11], v[146:149], v[24:27]
	v_mfma_f32_16x16x32_bf16 v[12:15], v[12:15], v[146:149], v[28:31]
	v_mfma_f32_16x16x32_bf16 v[96:99], v[48:51], v[146:149], v[104:107]
	v_mfma_f32_16x16x32_bf16 v[100:103], v[52:55], v[146:149], v[108:111]
	global_load_dwordx4 v[24:27], v[138:139], off offset:400
	global_load_dwordx4 v[28:31], v[138:139], off offset:384
	global_load_dwordx4 v[48:51], v[136:137], off offset:400
	global_load_dwordx4 v[52:55], v[136:137], off offset:384
	v_mfma_f32_16x16x32_bf16 v[88:91], v[56:59], v[150:153], v[88:91]
	v_mfma_f32_16x16x32_bf16 v[40:43], v[56:59], v[146:149], v[40:43]
	v_lshlrev_b32_e32 v56, 16, v16
	v_fmac_f32_e32 v72, v56, v56
	v_and_b32_e32 v56, 0xffff0000, v20
	v_mul_f32_e32 v73, v56, v56
	v_lshlrev_b32_e32 v56, 16, v21
	v_lshlrev_b32_e32 v58, 16, v17
	v_mul_f32_e32 v74, v56, v56
	v_and_b32_e32 v56, 0xffff0000, v21
	v_and_b32_e32 v59, 0xffff0000, v17
	v_fmac_f32_e32 v74, v58, v58
	v_mul_f32_e32 v58, v56, v56
	v_lshlrev_b32_e32 v56, 16, v22
	v_mfma_f32_16x16x32_bf16 v[92:95], v[60:63], v[150:153], v[92:95]
	v_fmac_f32_e32 v58, v59, v59
	v_mul_f32_e32 v59, v56, v56
	v_and_b32_e32 v56, 0xffff0000, v22
	v_mfma_f32_16x16x32_bf16 v[44:47], v[60:63], v[146:149], v[44:47]
	v_lshlrev_b32_e32 v60, 16, v18
	v_and_b32_e32 v61, 0xffff0000, v18
	v_fmac_f32_e32 v59, v60, v60
	v_mul_f32_e32 v60, v56, v56
	v_lshlrev_b32_e32 v56, 16, v23
	v_lshlrev_b32_e32 v62, 16, v19
	v_fmac_f32_e32 v60, v61, v61
	v_mul_f32_e32 v61, v56, v56
	v_and_b32_e32 v56, 0xffff0000, v23
	v_and_b32_e32 v57, 0xffff0000, v16
	v_fmac_f32_e32 v61, v62, v62
	v_mul_f32_e32 v62, v56, v56
	v_lshlrev_b32_e32 v56, 16, v32
	v_fmac_f32_e32 v73, v57, v57
	v_fmac_f32_e32 v72, v56, v56
	v_and_b32_e32 v56, 0xffff0000, v32
	v_fmac_f32_e32 v73, v56, v56
	v_lshlrev_b32_e32 v56, 16, v33
	v_fmac_f32_e32 v74, v56, v56
	v_and_b32_e32 v56, 0xffff0000, v33
	v_fmac_f32_e32 v58, v56, v56
	v_lshlrev_b32_e32 v56, 16, v34
	v_fmac_f32_e32 v59, v56, v56
	v_and_b32_e32 v56, 0xffff0000, v34
	v_and_b32_e32 v63, 0xffff0000, v19
	v_fmac_f32_e32 v60, v56, v56
	v_lshlrev_b32_e32 v56, 16, v35
	v_fmac_f32_e32 v62, v63, v63
	v_fmac_f32_e32 v61, v56, v56
	v_and_b32_e32 v56, 0xffff0000, v35
	v_fmac_f32_e32 v62, v56, v56
	v_lshlrev_b32_e32 v56, 16, v36
	v_fmac_f32_e32 v72, v56, v56
	v_and_b32_e32 v56, 0xffff0000, v36
	v_fmac_f32_e32 v73, v56, v56
	v_lshlrev_b32_e32 v56, 16, v37
	v_fmac_f32_e32 v74, v56, v56
	v_and_b32_e32 v56, 0xffff0000, v37
	v_fmac_f32_e32 v58, v56, v56
	v_lshlrev_b32_e32 v56, 16, v38
	v_fmac_f32_e32 v59, v56, v56
	v_and_b32_e32 v56, 0xffff0000, v38
	v_fmac_f32_e32 v60, v56, v56
	v_lshlrev_b32_e32 v56, 16, v39
	v_fmac_f32_e32 v61, v56, v56
	v_and_b32_e32 v56, 0xffff0000, v39
	v_fmac_f32_e32 v62, v56, v56
	v_lshlrev_b32_e32 v56, 16, v112
	v_fmac_f32_e32 v72, v56, v56
	v_and_b32_e32 v56, 0xffff0000, v112
	v_fmac_f32_e32 v73, v56, v56
	v_lshlrev_b32_e32 v56, 16, v113
	v_fmac_f32_e32 v74, v56, v56
	v_and_b32_e32 v56, 0xffff0000, v113
	v_fmac_f32_e32 v58, v56, v56
	v_lshlrev_b32_e32 v56, 16, v114
	v_fmac_f32_e32 v59, v56, v56
	v_and_b32_e32 v56, 0xffff0000, v114
	v_fmac_f32_e32 v60, v56, v56
	v_lshlrev_b32_e32 v56, 16, v115
	v_fmac_f32_e32 v61, v56, v56
	v_and_b32_e32 v56, 0xffff0000, v115
	v_fmac_f32_e32 v62, v56, v56
	v_lshlrev_b32_e32 v56, 16, v116
	v_fmac_f32_e32 v72, v56, v56
	v_and_b32_e32 v56, 0xffff0000, v116
	v_fmac_f32_e32 v73, v56, v56
	v_lshlrev_b32_e32 v56, 16, v117
	v_fmac_f32_e32 v74, v56, v56
	v_and_b32_e32 v56, 0xffff0000, v117
	v_fmac_f32_e32 v58, v56, v56
	v_lshlrev_b32_e32 v56, 16, v118
	v_fmac_f32_e32 v59, v56, v56
	v_and_b32_e32 v56, 0xffff0000, v118
	v_fmac_f32_e32 v60, v56, v56
	v_lshlrev_b32_e32 v56, 16, v119
	v_fmac_f32_e32 v61, v56, v56
	v_and_b32_e32 v56, 0xffff0000, v119
	v_fmac_f32_e32 v62, v56, v56
	v_lshlrev_b32_e32 v57, 16, v124
	v_lshlrev_b32_e32 v56, 16, v120
	v_pk_mul_f32 v[56:57], v[56:57], v[56:57]
	s_nop 0
	v_add_f32_e32 v56, v72, v56
	v_add_f32_e32 v63, v56, v57
	v_and_b32_e32 v57, 0xffff0000, v124
	v_and_b32_e32 v56, 0xffff0000, v120
	v_pk_mul_f32 v[56:57], v[56:57], v[56:57]
	s_nop 0
	v_add_f32_e32 v56, v73, v56
	v_add_f32_e32 v72, v56, v57
	v_lshlrev_b32_e32 v57, 16, v125
	v_lshlrev_b32_e32 v56, 16, v121
	v_pk_mul_f32 v[56:57], v[56:57], v[56:57]
	s_nop 0
	v_add_f32_e32 v56, v74, v56
	v_add_f32_e32 v73, v56, v57
	v_and_b32_e32 v57, 0xffff0000, v125
	v_and_b32_e32 v56, 0xffff0000, v121
	v_pk_mul_f32 v[56:57], v[56:57], v[56:57]
	s_nop 0
	v_add_f32_e32 v56, v58, v56
	v_add_f32_e32 v58, v56, v57
	v_lshlrev_b32_e32 v57, 16, v126
	v_lshlrev_b32_e32 v56, 16, v122
	v_pk_mul_f32 v[56:57], v[56:57], v[56:57]
	v_add_f32_dpp v58, v58, v58 row_ror:8 row_mask:0xf bank_mask:0xf bound_ctrl:1
	v_add_f32_e32 v56, v59, v56
	v_add_f32_e32 v59, v56, v57
	v_and_b32_e32 v57, 0xffff0000, v126
	v_and_b32_e32 v56, 0xffff0000, v122
	v_pk_mul_f32 v[56:57], v[56:57], v[56:57]
	v_add_f32_dpp v59, v59, v59 row_ror:8 row_mask:0xf bank_mask:0xf bound_ctrl:1
	v_add_f32_e32 v56, v60, v56
	v_add_f32_e32 v60, v56, v57
	v_lshlrev_b32_e32 v57, 16, v127
	v_lshlrev_b32_e32 v56, 16, v123
	v_pk_mul_f32 v[56:57], v[56:57], v[56:57]
	v_add_f32_dpp v60, v60, v60 row_ror:8 row_mask:0xf bank_mask:0xf bound_ctrl:1
	v_add_f32_e32 v56, v61, v56
	v_add_f32_e32 v61, v56, v57
	v_and_b32_e32 v57, 0xffff0000, v127
	v_and_b32_e32 v56, 0xffff0000, v123
	v_pk_mul_f32 v[56:57], v[56:57], v[56:57]
	v_add_f32_dpp v59, v59, v59 row_ror:4 row_mask:0xf bank_mask:0xf bound_ctrl:1
	v_add_f32_e32 v56, v62, v56
	v_add_f32_e32 v56, v56, v57
	v_add_f32_dpp v57, v63, v63 row_ror:8 row_mask:0xf bank_mask:0xf bound_ctrl:1
	v_add_f32_dpp v62, v72, v72 row_ror:8 row_mask:0xf bank_mask:0xf bound_ctrl:1
	v_add_f32_dpp v63, v73, v73 row_ror:8 row_mask:0xf bank_mask:0xf bound_ctrl:1
	v_add_f32_dpp v57, v57, v57 row_ror:4 row_mask:0xf bank_mask:0xf bound_ctrl:1
	v_add_f32_dpp v62, v62, v62 row_ror:4 row_mask:0xf bank_mask:0xf bound_ctrl:1
	v_add_f32_dpp v60, v60, v60 row_ror:4 row_mask:0xf bank_mask:0xf bound_ctrl:1
	v_add_f32_dpp v61, v61, v61 row_ror:8 row_mask:0xf bank_mask:0xf bound_ctrl:1
	v_add_f32_dpp v56, v56, v56 row_ror:8 row_mask:0xf bank_mask:0xf bound_ctrl:1
	v_add_f32_dpp v57, v57, v57 row_ror:2 row_mask:0xf bank_mask:0xf bound_ctrl:1
	v_add_f32_dpp v62, v62, v62 row_ror:2 row_mask:0xf bank_mask:0xf bound_ctrl:1
	v_add_f32_dpp v63, v63, v63 row_ror:4 row_mask:0xf bank_mask:0xf bound_ctrl:1
	v_add_f32_dpp v58, v58, v58 row_ror:4 row_mask:0xf bank_mask:0xf bound_ctrl:1
	v_add_f32_dpp v59, v59, v59 row_ror:2 row_mask:0xf bank_mask:0xf bound_ctrl:1
	v_add_f32_dpp v60, v60, v60 row_ror:2 row_mask:0xf bank_mask:0xf bound_ctrl:1
	v_add_f32_dpp v61, v61, v61 row_ror:4 row_mask:0xf bank_mask:0xf bound_ctrl:1
	v_add_f32_dpp v56, v56, v56 row_ror:4 row_mask:0xf bank_mask:0xf bound_ctrl:1
	v_add_f32_dpp v57, v57, v57 row_ror:1 row_mask:0xf bank_mask:0xf bound_ctrl:1
	v_add_f32_dpp v62, v62, v62 row_ror:1 row_mask:0xf bank_mask:0xf bound_ctrl:1
	v_add_f32_dpp v63, v63, v63 row_ror:2 row_mask:0xf bank_mask:0xf bound_ctrl:1
	v_add_f32_dpp v58, v58, v58 row_ror:2 row_mask:0xf bank_mask:0xf bound_ctrl:1
	v_add_f32_dpp v59, v59, v59 row_ror:1 row_mask:0xf bank_mask:0xf bound_ctrl:1
	v_add_f32_dpp v60, v60, v60 row_ror:1 row_mask:0xf bank_mask:0xf bound_ctrl:1
	v_add_f32_dpp v61, v61, v61 row_ror:2 row_mask:0xf bank_mask:0xf bound_ctrl:1
	v_add_f32_dpp v56, v56, v56 row_ror:2 row_mask:0xf bank_mask:0xf bound_ctrl:1
	v_fmamk_f32 v57, v57, 0x3c000000, v142
	v_fmamk_f32 v62, v62, 0x3c000000, v142
	v_add_f32_dpp v63, v63, v63 row_ror:1 row_mask:0xf bank_mask:0xf bound_ctrl:1
	v_add_f32_dpp v58, v58, v58 row_ror:1 row_mask:0xf bank_mask:0xf bound_ctrl:1
	v_fmamk_f32 v59, v59, 0x3c000000, v142
	v_fmamk_f32 v60, v60, 0x3c000000, v142
	v_add_f32_dpp v61, v61, v61 row_ror:1 row_mask:0xf bank_mask:0xf bound_ctrl:1
	v_add_f32_dpp v56, v56, v56 row_ror:1 row_mask:0xf bank_mask:0xf bound_ctrl:1
	v_rsq_f32_e32 v57, v57
	v_rsq_f32_e32 v62, v62
	v_fmamk_f32 v63, v63, 0x3c000000, v142
	v_fmamk_f32 v58, v58, 0x3c000000, v142
	v_rsq_f32_e32 v59, v59
	v_rsq_f32_e32 v60, v60
	v_fmamk_f32 v61, v61, 0x3c000000, v142
	v_fmamk_f32 v56, v56, 0x3c000000, v142
	v_rsq_f32_e32 v63, v63
	v_rsq_f32_e32 v58, v58
	v_rsq_f32_e32 v61, v61
	v_rsq_f32_e32 v56, v56
	s_waitcnt vmcnt(0)
	v_mul_f32_e32 v52, v57, v52
	v_mul_f32_e32 v53, v62, v53
	v_mul_f32_e32 v48, v59, v48
	v_mul_f32_e32 v49, v60, v49
	v_mul_f32_e32 v28, v57, v28
	v_mul_f32_e32 v29, v62, v29
	v_mul_f32_e32 v24, v59, v24
	v_mul_f32_e32 v25, v60, v25
	v_cvt_pk_bf16_f32 v104, v52, v53
	v_mul_f32_e32 v52, v63, v54
	v_mul_f32_e32 v53, v58, v55
	v_cvt_pk_bf16_f32 v105, v52, v53
	v_cvt_pk_bf16_f32 v106, v48, v49
	v_mul_f32_e32 v48, v61, v50
	v_mul_f32_e32 v49, v56, v51
	v_cvt_pk_bf16_f32 v107, v48, v49
	v_cvt_pk_bf16_f32 v108, v28, v29
	v_mul_f32_e32 v28, v63, v30
	v_mul_f32_e32 v29, v58, v31
	v_cvt_pk_bf16_f32 v109, v28, v29
	v_cvt_pk_bf16_f32 v110, v24, v25
	v_mul_f32_e32 v24, v61, v26
	v_mul_f32_e32 v25, v56, v27
	v_cvt_pk_bf16_f32 v111, v24, v25
	v_mfma_f32_16x16x32_bf16 v[72:75], v[20:23], v[104:107], v[68:71]
	v_mfma_f32_16x16x32_bf16 v[68:71], v[32:35], v[104:107], v[154:157]
	v_mfma_f32_16x16x32_bf16 v[24:27], v[20:23], v[108:111], v[4:7]
	v_mfma_f32_16x16x32_bf16 v[20:23], v[32:35], v[108:111], v[8:11]
	v_or_b32_e32 v32, s0, v144
	s_lshl_b32 s0, s64, 8
	s_add_u32 s60, s46, s0
	v_mfma_f32_16x16x32_bf16 v[76:79], v[16:19], v[104:107], v[64:67]
	s_addc_u32 s61, s47, 0
	v_ashrrev_i32_e32 v33, 31, v32
	s_lshl_b32 s21, s64, 9
	v_mfma_f32_16x16x32_bf16 v[28:31], v[16:19], v[108:111], v[0:3]
	v_mfma_f32_16x16x32_bf16 v[16:19], v[36:39], v[108:111], v[12:15]
	v_mfma_f32_16x16x32_bf16 v[12:15], v[112:115], v[108:111], v[96:99]
	s_nop 2
	v_lshlrev_b64 v[98:99], 1, v[134:135]
	v_mfma_f32_16x16x32_bf16 v[64:67], v[36:39], v[104:107], v[158:161]
	v_lshl_add_u64 v[34:35], s[60:61], 0, v[98:99]
	v_lshlrev_b64 v[36:37], 11, v[32:33]
	v_lshl_add_u64 v[36:37], v[34:35], 0, v[36:37]
	v_mfma_f32_16x16x32_bf16 v[60:63], v[112:115], v[104:107], v[80:83]
	v_or_b32_e32 v32, 16, v32
	v_ashrrev_i32_e32 v33, 31, v32
	v_lshlrev_b64 v[32:33], 11, v[32:33]
	v_mfma_f32_16x16x32_bf16 v[56:59], v[116:119], v[104:107], v[84:87]
	s_add_u32 s60, s12, s21
	v_lshl_add_u64 v[32:33], v[34:35], 0, v[32:33]
	s_addc_u32 s61, s13, 0
	v_mfma_f32_16x16x32_bf16 v[52:55], v[120:123], v[104:107], v[88:91]
	v_mfma_f32_16x16x32_bf16 v[48:51], v[124:127], v[104:107], v[92:95]
	s_nop 2
	global_load_dwordx4 v[92:95], v[36:37], off
	global_load_dwordx4 v[88:91], v[36:37], off offset:64
	global_load_dwordx4 v[84:87], v[36:37], off offset:128
	global_load_dwordx4 v[80:83], v[36:37], off offset:192
	s_waitcnt vmcnt(3)
	v_and_b32_e32 v115, 0xffff0000, v92
	v_mfma_f32_16x16x32_bf16 v[8:11], v[116:119], v[108:111], v[100:103]
	v_lshlrev_b32_e32 v114, 16, v92
	v_and_b32_e32 v117, 0xffff0000, v94
	v_lshlrev_b32_e32 v116, 16, v94
	v_or_b32_e32 v100, s20, v143
	v_ashrrev_i32_e32 v101, 31, v100
	v_lshlrev_b64 v[96:97], 12, v[100:101]
	v_lshl_or_b32 v102, v143, 2, s21
	v_lshl_add_u64 v[96:97], s[48:49], 0, v[96:97]
	v_mfma_f32_16x16x32_bf16 v[4:7], v[120:123], v[108:111], v[40:43]
	v_lshl_add_u64 v[112:113], v[96:97], 0, s[0:1]
	v_lshl_add_u64 v[96:97], s[60:61], 0, v[132:133]
	v_and_b32_e32 v119, 0xffff0000, v93
	v_mfma_f32_16x16x32_bf16 v[0:3], v[124:127], v[108:111], v[44:47]
	s_nop 2
	global_load_dwordx4 v[44:47], v[32:33], off
	global_load_dwordx4 v[40:43], v[32:33], off offset:64
	global_load_dwordx4 v[36:39], v[32:33], off offset:128
	s_nop 0
	global_load_dwordx4 v[32:35], v[32:33], off offset:192
	v_lshlrev_b32_e32 v118, 16, v93
	global_load_dword v103, v102, s[16:17]
	global_load_dwordx4 v[104:107], v[96:97], off offset:16
	global_load_dwordx4 v[108:111], v[96:97], off
	v_and_b32_e32 v93, 0xffff0000, v95
	v_lshlrev_b32_e32 v92, 16, v95
	v_and_b32_e32 v95, 0x7fffffff, v115
	v_and_b32_e32 v94, 0x7fffffff, v114
	v_pk_fma_f32 v[94:95], v[94:95], s[4:5], 1.0 op_sel_hi:[1,0,0]
	v_pk_mul_f32 v[122:123], v[114:115], v[114:115]
	v_rcp_f32_e32 v94, v94
	v_rcp_f32_e32 v95, v95
	v_pk_mul_f32 v[122:123], v[122:123], s[58:59] op_sel_hi:[1,0]
	v_cmp_gt_f32_e32 vcc, 0, v114
	v_exp_f32_e32 v122, v122
	v_pk_fma_f32 v[120:121], v[94:95], s[50:51], v[130:131] op_sel_hi:[1,0,0]
	v_exp_f32_e32 v123, v123
	v_pk_fma_f32 v[120:121], v[94:95], v[120:121], s[52:53] op_sel_hi:[1,1,0]
	s_waitcnt vmcnt(1)
	v_fma_f32 v74, v106, v74, v103
	v_pk_fma_f32 v[120:121], v[94:95], v[120:121], s[54:55] op_sel_hi:[1,1,0]
	s_waitcnt vmcnt(0)
	v_fma_f32 v76, v108, v76, v103
	v_pk_fma_f32 v[120:121], v[94:95], v[120:121], s[56:57] op_sel_hi:[1,1,0]
	v_fma_f32 v72, v104, v72, v103
	v_pk_mul_f32 v[94:95], v[94:95], v[120:121]
	v_pk_mul_f32 v[120:121], v[118:119], v[118:119]
	v_pk_mul_f32 v[94:95], v[122:123], v[94:95]
	v_fma_f32 v73, v105, v73, v103
	v_pk_mul_f32 v[122:123], v[94:95], v[114:115]
	v_pk_fma_f32 v[94:95], v[94:95], v[114:115], v[114:115] neg_lo:[1,0,0] neg_hi:[1,0,0]
	v_fma_f32 v77, v109, v77, v103
	v_cndmask_b32_e32 v101, v94, v122, vcc
	v_cmp_gt_f32_e32 vcc, 0, v115
	v_and_b32_e32 v94, 0x7fffffff, v118
	v_mul_f32_e32 v76, v101, v76
	v_cndmask_b32_e32 v122, v95, v123, vcc
	v_and_b32_e32 v95, 0x7fffffff, v119
	v_pk_fma_f32 v[94:95], v[94:95], s[4:5], 1.0 op_sel_hi:[1,0,0]
	v_cmp_gt_f32_e32 vcc, 0, v118
	v_rcp_f32_e32 v94, v94
	v_rcp_f32_e32 v95, v95
	v_fma_f32 v78, v110, v78, v103
	v_mul_f32_e32 v77, v122, v77
	v_and_b32_e32 v105, 0xffff0000, v90
	v_pk_fma_f32 v[114:115], v[94:95], s[50:51], v[130:131] op_sel_hi:[1,0,0]
	v_lshlrev_b32_e32 v104, 16, v90
	v_pk_fma_f32 v[114:115], v[94:95], v[114:115], s[52:53] op_sel_hi:[1,1,0]
	v_lshlrev_b32_e32 v106, 16, v89
	v_pk_fma_f32 v[114:115], v[94:95], v[114:115], s[54:55] op_sel_hi:[1,1,0]
	s_nop 0
	v_pk_fma_f32 v[114:115], v[94:95], v[114:115], s[56:57] op_sel_hi:[1,1,0]
	s_nop 0
	v_pk_mul_f32 v[94:95], v[94:95], v[114:115]
	v_pk_mul_f32 v[114:115], v[120:121], s[58:59] op_sel_hi:[1,0]
	s_nop 0
	v_exp_f32_e32 v114, v114
	v_exp_f32_e32 v115, v115
	s_nop 0
	v_pk_mul_f32 v[94:95], v[114:115], v[94:95]
	s_nop 0
	v_pk_mul_f32 v[114:115], v[94:95], v[118:119]
	v_pk_fma_f32 v[94:95], v[94:95], v[118:119], v[118:119] neg_lo:[1,0,0] neg_hi:[1,0,0]
	s_nop 0
	v_cndmask_b32_e32 v120, v94, v114, vcc
	v_cmp_gt_f32_e32 vcc, 0, v119
	v_and_b32_e32 v94, 0x7fffffff, v116
	v_pk_mul_f32 v[118:119], v[116:117], v[116:117]
	v_cndmask_b32_e32 v121, v95, v115, vcc
	v_and_b32_e32 v95, 0x7fffffff, v117
	v_pk_fma_f32 v[94:95], v[94:95], s[4:5], 1.0 op_sel_hi:[1,0,0]
	v_pk_mul_f32 v[118:119], v[118:119], s[58:59] op_sel_hi:[1,0]
	v_rcp_f32_e32 v94, v94
	v_rcp_f32_e32 v95, v95
	v_exp_f32_e32 v118, v118
	v_exp_f32_e32 v119, v119
	v_cmp_gt_f32_e32 vcc, 0, v116
	v_pk_fma_f32 v[114:115], v[94:95], s[50:51], v[130:131] op_sel_hi:[1,0,0]
	v_mul_f32_e32 v78, v120, v78
	v_pk_fma_f32 v[114:115], v[94:95], v[114:115], s[52:53] op_sel_hi:[1,1,0]
	s_nop 0
	v_pk_fma_f32 v[114:115], v[94:95], v[114:115], s[54:55] op_sel_hi:[1,1,0]
	s_nop 0
	v_pk_fma_f32 v[114:115], v[94:95], v[114:115], s[56:57] op_sel_hi:[1,1,0]
	s_nop 0
	v_pk_mul_f32 v[94:95], v[94:95], v[114:115]
	v_pk_mul_f32 v[114:115], v[92:93], v[92:93]
	v_pk_mul_f32 v[94:95], v[118:119], v[94:95]
	v_pk_mul_f32 v[114:115], v[114:115], s[58:59] op_sel_hi:[1,0]
	v_pk_mul_f32 v[118:119], v[94:95], v[116:117]
	v_pk_fma_f32 v[94:95], v[94:95], v[116:117], v[116:117] neg_lo:[1,0,0] neg_hi:[1,0,0]
	v_exp_f32_e32 v114, v114
	v_cndmask_b32_e32 v118, v94, v118, vcc
	v_cmp_gt_f32_e32 vcc, 0, v117
	v_and_b32_e32 v94, 0x7fffffff, v92
	v_exp_f32_e32 v115, v115
	v_cndmask_b32_e32 v119, v95, v119, vcc
	v_and_b32_e32 v95, 0x7fffffff, v93
	v_pk_fma_f32 v[94:95], v[94:95], s[4:5], 1.0 op_sel_hi:[1,0,0]
	v_cmp_gt_f32_e32 vcc, 0, v92
	v_rcp_f32_e32 v94, v94
	v_rcp_f32_e32 v95, v95
	v_mul_f32_e32 v72, v118, v72
	v_mul_f32_e32 v73, v119, v73
	v_pk_fma_f32 v[116:117], v[94:95], s[50:51], v[130:131] op_sel_hi:[1,0,0]
	s_nop 0
	v_pk_fma_f32 v[116:117], v[94:95], v[116:117], s[52:53] op_sel_hi:[1,1,0]
	s_nop 0
	v_pk_fma_f32 v[116:117], v[94:95], v[116:117], s[54:55] op_sel_hi:[1,1,0]
	s_nop 0
	v_pk_fma_f32 v[116:117], v[94:95], v[116:117], s[56:57] op_sel_hi:[1,1,0]
	s_nop 0
	v_pk_mul_f32 v[94:95], v[94:95], v[116:117]
	s_nop 0
	v_pk_mul_f32 v[94:95], v[114:115], v[94:95]
	s_nop 0
	v_pk_mul_f32 v[114:115], v[94:95], v[92:93]
	v_pk_fma_f32 v[94:95], v[94:95], v[92:93], v[92:93] neg_lo:[1,0,0] neg_hi:[1,0,0]
	s_nop 0
	v_cndmask_b32_e32 v92, v94, v114, vcc
	v_cmp_gt_f32_e32 vcc, 0, v93
	v_mul_f32_e32 v92, v92, v74
	v_fma_f32 v74, v111, v79, v103
	v_cndmask_b32_e32 v93, v95, v115, vcc
	v_mul_f32_e32 v79, v121, v74
	v_fma_f32 v74, v107, v75, v103
	v_mul_f32_e32 v93, v93, v74
	v_cvt_pk_bf16_f32 v74, v76, v77
	v_cvt_pk_bf16_f32 v75, v78, v79
	v_cvt_pk_bf16_f32 v76, v72, v73
	v_lshl_add_u64 v[72:73], v[112:113], 0, v[98:99]
	v_cvt_pk_bf16_f32 v77, v92, v93
	global_store_dwordx4 v[72:73], v[74:77], off offset:2048 sc1
	global_load_dwordx4 v[74:77], v[96:97], off offset:144
	s_nop 0
	global_load_dwordx4 v[92:95], v[96:97], off offset:128
	v_and_b32_e32 v79, 0xffff0000, v88
	v_lshlrev_b32_e32 v78, 16, v88
	v_and_b32_e32 v107, 0xffff0000, v89
	v_and_b32_e32 v89, 0xffff0000, v91
	v_lshlrev_b32_e32 v88, 16, v91
	v_and_b32_e32 v91, 0x7fffffff, v79
	v_and_b32_e32 v90, 0x7fffffff, v78
	v_pk_fma_f32 v[90:91], v[90:91], s[4:5], 1.0 op_sel_hi:[1,0,0]
	v_pk_mul_f32 v[110:111], v[78:79], v[78:79]
	v_rcp_f32_e32 v90, v90
	v_rcp_f32_e32 v91, v91
	v_pk_mul_f32 v[110:111], v[110:111], s[58:59] op_sel_hi:[1,0]
	v_cmp_gt_f32_e32 vcc, 0, v78
	v_exp_f32_e32 v110, v110
	v_pk_fma_f32 v[108:109], v[90:91], s[50:51], v[130:131] op_sel_hi:[1,0,0]
	v_exp_f32_e32 v111, v111
	v_pk_fma_f32 v[108:109], v[90:91], v[108:109], s[52:53] op_sel_hi:[1,1,0]
	s_waitcnt vmcnt(1)
	v_fma_f32 v64, v74, v64, v103
	v_pk_fma_f32 v[108:109], v[90:91], v[108:109], s[54:55] op_sel_hi:[1,1,0]
	v_fma_f32 v65, v75, v65, v103
	v_pk_fma_f32 v[108:109], v[90:91], v[108:109], s[56:57] op_sel_hi:[1,1,0]
	v_fma_f32 v66, v76, v66, v103
	v_pk_mul_f32 v[90:91], v[90:91], v[108:109]
	v_pk_mul_f32 v[108:109], v[106:107], v[106:107]
	v_pk_mul_f32 v[90:91], v[110:111], v[90:91]
	v_fma_f32 v67, v77, v67, v103
	v_pk_mul_f32 v[110:111], v[90:91], v[78:79]
	v_pk_fma_f32 v[90:91], v[90:91], v[78:79], v[78:79] neg_lo:[1,0,0] neg_hi:[1,0,0]
	v_and_b32_e32 v78, 0x7fffffff, v106
	v_cndmask_b32_e32 v101, v90, v110, vcc
	v_cmp_gt_f32_e32 vcc, 0, v79
	v_and_b32_e32 v79, 0x7fffffff, v107
	v_pk_fma_f32 v[78:79], v[78:79], s[4:5], 1.0 op_sel_hi:[1,0,0]
	v_cndmask_b32_e32 v110, v91, v111, vcc
	v_rcp_f32_e32 v78, v78
	v_rcp_f32_e32 v79, v79
	v_cmp_gt_f32_e32 vcc, 0, v106
	s_waitcnt vmcnt(0)
	v_fma_f32 v68, v92, v68, v103
	v_mul_f32_e32 v68, v101, v68
	v_pk_fma_f32 v[90:91], v[78:79], s[50:51], v[130:131] op_sel_hi:[1,0,0]
	v_and_b32_e32 v75, 0xffff0000, v84
	v_pk_fma_f32 v[90:91], v[78:79], v[90:91], s[52:53] op_sel_hi:[1,1,0]
	v_and_b32_e32 v77, 0xffff0000, v86
	v_pk_fma_f32 v[90:91], v[78:79], v[90:91], s[54:55] op_sel_hi:[1,1,0]
	v_lshlrev_b32_e32 v76, 16, v86
	v_pk_fma_f32 v[90:91], v[78:79], v[90:91], s[56:57] op_sel_hi:[1,1,0]
	s_nop 0
	v_pk_mul_f32 v[78:79], v[78:79], v[90:91]
	v_pk_mul_f32 v[90:91], v[108:109], s[58:59] op_sel_hi:[1,0]
	s_nop 0
	v_exp_f32_e32 v90, v90
	v_exp_f32_e32 v91, v91
	s_nop 0
	v_pk_mul_f32 v[78:79], v[90:91], v[78:79]
	s_nop 0
	v_pk_mul_f32 v[90:91], v[78:79], v[106:107]
	v_pk_fma_f32 v[78:79], v[78:79], v[106:107], v[106:107] neg_lo:[1,0,0] neg_hi:[1,0,0]
	s_nop 0
	v_cndmask_b32_e32 v108, v78, v90, vcc
	v_cmp_gt_f32_e32 vcc, 0, v107
	v_and_b32_e32 v78, 0x7fffffff, v104
	v_pk_mul_f32 v[106:107], v[104:105], v[104:105]
	v_cndmask_b32_e32 v109, v79, v91, vcc
	v_and_b32_e32 v79, 0x7fffffff, v105
	v_pk_fma_f32 v[78:79], v[78:79], s[4:5], 1.0 op_sel_hi:[1,0,0]
	v_pk_mul_f32 v[106:107], v[106:107], s[58:59] op_sel_hi:[1,0]
	v_rcp_f32_e32 v78, v78
	v_rcp_f32_e32 v79, v79
	v_exp_f32_e32 v106, v106
	v_exp_f32_e32 v107, v107
	v_cmp_gt_f32_e32 vcc, 0, v104
	v_pk_fma_f32 v[90:91], v[78:79], s[50:51], v[130:131] op_sel_hi:[1,0,0]
	s_nop 0
	v_pk_fma_f32 v[90:91], v[78:79], v[90:91], s[52:53] op_sel_hi:[1,1,0]
	s_nop 0
	v_pk_fma_f32 v[90:91], v[78:79], v[90:91], s[54:55] op_sel_hi:[1,1,0]
	s_nop 0
	v_pk_fma_f32 v[90:91], v[78:79], v[90:91], s[56:57] op_sel_hi:[1,1,0]
	s_nop 0
	v_pk_mul_f32 v[78:79], v[78:79], v[90:91]
	v_pk_mul_f32 v[90:91], v[88:89], v[88:89]
	v_pk_mul_f32 v[78:79], v[106:107], v[78:79]
	v_pk_mul_f32 v[90:91], v[90:91], s[58:59] op_sel_hi:[1,0]
	v_pk_mul_f32 v[106:107], v[78:79], v[104:105]
	v_pk_fma_f32 v[78:79], v[78:79], v[104:105], v[104:105] neg_lo:[1,0,0] neg_hi:[1,0,0]
	v_exp_f32_e32 v90, v90
	v_cndmask_b32_e32 v106, v78, v106, vcc
	v_cmp_gt_f32_e32 vcc, 0, v105
	v_and_b32_e32 v78, 0x7fffffff, v88
	v_exp_f32_e32 v91, v91
	v_cndmask_b32_e32 v107, v79, v107, vcc
	v_and_b32_e32 v79, 0x7fffffff, v89
	v_pk_fma_f32 v[78:79], v[78:79], s[4:5], 1.0 op_sel_hi:[1,0,0]
	v_cmp_gt_f32_e32 vcc, 0, v88
	v_rcp_f32_e32 v78, v78
	v_rcp_f32_e32 v79, v79
	v_mul_f32_e32 v74, v106, v64
	v_fma_f32 v64, v93, v69, v103
	v_mul_f32_e32 v69, v107, v65
	v_pk_fma_f32 v[104:105], v[78:79], s[50:51], v[130:131] op_sel_hi:[1,0,0]
	v_fma_f32 v65, v94, v70, v103
	v_pk_fma_f32 v[104:105], v[78:79], v[104:105], s[52:53] op_sel_hi:[1,1,0]
	v_mul_f32_e32 v64, v110, v64
	v_pk_fma_f32 v[104:105], v[78:79], v[104:105], s[54:55] op_sel_hi:[1,1,0]
	v_mul_f32_e32 v65, v108, v65
	v_pk_fma_f32 v[104:105], v[78:79], v[104:105], s[56:57] op_sel_hi:[1,1,0]
	v_cvt_pk_bf16_f32 v64, v68, v64
	s_nop 0
	v_pk_mul_f32 v[78:79], v[78:79], v[104:105]
	s_nop 0
	v_pk_mul_f32 v[78:79], v[90:91], v[78:79]
	s_nop 0
	v_pk_mul_f32 v[90:91], v[78:79], v[88:89]
	v_pk_fma_f32 v[78:79], v[78:79], v[88:89], v[88:89] neg_lo:[1,0,0] neg_hi:[1,0,0]
	s_nop 0
	v_cndmask_b32_e32 v78, v78, v90, vcc
	v_cmp_gt_f32_e32 vcc, 0, v89
	v_mul_f32_e32 v70, v78, v66
	v_fma_f32 v66, v95, v71, v103
	v_cndmask_b32_e32 v79, v79, v91, vcc
	v_mul_f32_e32 v66, v109, v66
	v_mul_f32_e32 v67, v79, v67
	v_cvt_pk_bf16_f32 v65, v65, v66
	v_cvt_pk_bf16_f32 v66, v74, v69
	v_cvt_pk_bf16_f32 v67, v70, v67
	global_store_dwordx4 v[72:73], v[64:67], off offset:2112 sc1
	global_load_dwordx4 v[64:67], v[96:97], off offset:272
	s_nop 0
	global_load_dwordx4 v[68:71], v[96:97], off offset:256
	v_lshlrev_b32_e32 v74, 16, v84
	v_and_b32_e32 v79, 0xffff0000, v85
	v_lshlrev_b32_e32 v78, 16, v85
	v_and_b32_e32 v85, 0xffff0000, v87
	v_lshlrev_b32_e32 v84, 16, v87
	v_and_b32_e32 v87, 0x7fffffff, v75
	v_and_b32_e32 v86, 0x7fffffff, v74
	v_pk_fma_f32 v[86:87], v[86:87], s[4:5], 1.0 op_sel_hi:[1,0,0]
	v_pk_mul_f32 v[90:91], v[74:75], v[74:75]
	v_rcp_f32_e32 v86, v86
	v_rcp_f32_e32 v87, v87
	v_pk_mul_f32 v[90:91], v[90:91], s[58:59] op_sel_hi:[1,0]
	v_cmp_gt_f32_e32 vcc, 0, v74
	v_exp_f32_e32 v90, v90
	v_pk_fma_f32 v[88:89], v[86:87], s[50:51], v[130:131] op_sel_hi:[1,0,0]
	v_exp_f32_e32 v91, v91
	v_pk_fma_f32 v[88:89], v[86:87], v[88:89], s[52:53] op_sel_hi:[1,1,0]
	s_waitcnt vmcnt(1)
	v_fma_f32 v56, v64, v56, v103
	v_pk_fma_f32 v[88:89], v[86:87], v[88:89], s[54:55] op_sel_hi:[1,1,0]
	v_fma_f32 v57, v65, v57, v103
	v_pk_fma_f32 v[88:89], v[86:87], v[88:89], s[56:57] op_sel_hi:[1,1,0]
	v_fma_f32 v58, v66, v58, v103
	v_pk_mul_f32 v[86:87], v[86:87], v[88:89]
	v_pk_mul_f32 v[88:89], v[78:79], v[78:79]
	v_pk_mul_f32 v[86:87], v[90:91], v[86:87]
	v_fma_f32 v59, v67, v59, v103
	v_pk_mul_f32 v[90:91], v[86:87], v[74:75]
	v_pk_fma_f32 v[86:87], v[86:87], v[74:75], v[74:75] neg_lo:[1,0,0] neg_hi:[1,0,0]
	v_and_b32_e32 v74, 0x7fffffff, v78
	v_cndmask_b32_e32 v90, v86, v90, vcc
	v_cmp_gt_f32_e32 vcc, 0, v75
	v_and_b32_e32 v75, 0x7fffffff, v79
	v_pk_fma_f32 v[74:75], v[74:75], s[4:5], 1.0 op_sel_hi:[1,0,0]
	v_cndmask_b32_e32 v91, v87, v91, vcc
	v_rcp_f32_e32 v74, v74
	v_rcp_f32_e32 v75, v75
	v_cmp_gt_f32_e32 vcc, 0, v78
	s_waitcnt vmcnt(0)
	v_fma_f32 v60, v68, v60, v103
	v_mul_f32_e32 v60, v90, v60
	v_pk_fma_f32 v[86:87], v[74:75], s[50:51], v[130:131] op_sel_hi:[1,0,0]
	v_and_b32_e32 v65, 0xffff0000, v80
	v_pk_fma_f32 v[86:87], v[74:75], v[86:87], s[52:53] op_sel_hi:[1,1,0]
	v_lshlrev_b32_e32 v68, 16, v81
	v_pk_fma_f32 v[86:87], v[74:75], v[86:87], s[54:55] op_sel_hi:[1,1,0]
	v_and_b32_e32 v67, 0xffff0000, v82
	v_pk_fma_f32 v[86:87], v[74:75], v[86:87], s[56:57] op_sel_hi:[1,1,0]
	v_lshlrev_b32_e32 v66, 16, v82
	v_pk_mul_f32 v[74:75], v[74:75], v[86:87]
	v_pk_mul_f32 v[86:87], v[88:89], s[58:59] op_sel_hi:[1,0]
	s_nop 0
	v_exp_f32_e32 v86, v86
	v_exp_f32_e32 v87, v87
	s_nop 0
	v_pk_mul_f32 v[74:75], v[86:87], v[74:75]
	s_nop 0
	v_pk_mul_f32 v[86:87], v[74:75], v[78:79]
	v_pk_fma_f32 v[74:75], v[74:75], v[78:79], v[78:79] neg_lo:[1,0,0] neg_hi:[1,0,0]
	s_nop 0
	v_cndmask_b32_e32 v88, v74, v86, vcc
	v_cmp_gt_f32_e32 vcc, 0, v79
	v_and_b32_e32 v74, 0x7fffffff, v76
	s_nop 0
	v_cndmask_b32_e32 v89, v75, v87, vcc
	v_and_b32_e32 v75, 0x7fffffff, v77
	v_pk_fma_f32 v[74:75], v[74:75], s[4:5], 1.0 op_sel_hi:[1,0,0]
	v_pk_mul_f32 v[86:87], v[76:77], v[76:77]
	v_rcp_f32_e32 v74, v74
	v_rcp_f32_e32 v75, v75
	v_pk_mul_f32 v[86:87], v[86:87], s[58:59] op_sel_hi:[1,0]
	v_cmp_gt_f32_e32 vcc, 0, v76
	v_exp_f32_e32 v86, v86
	v_pk_fma_f32 v[78:79], v[74:75], s[50:51], v[130:131] op_sel_hi:[1,0,0]
	v_exp_f32_e32 v87, v87
	v_pk_fma_f32 v[78:79], v[74:75], v[78:79], s[52:53] op_sel_hi:[1,1,0]
	s_nop 0
	v_pk_fma_f32 v[78:79], v[74:75], v[78:79], s[54:55] op_sel_hi:[1,1,0]
	s_nop 0
	v_pk_fma_f32 v[78:79], v[74:75], v[78:79], s[56:57] op_sel_hi:[1,1,0]
	s_nop 0
	v_pk_mul_f32 v[74:75], v[74:75], v[78:79]
	v_pk_mul_f32 v[78:79], v[84:85], v[84:85]
	v_pk_mul_f32 v[74:75], v[86:87], v[74:75]
	s_nop 0
	v_pk_mul_f32 v[86:87], v[74:75], v[76:77]
	v_pk_fma_f32 v[74:75], v[74:75], v[76:77], v[76:77] neg_lo:[1,0,0] neg_hi:[1,0,0]
	s_nop 0
	v_cndmask_b32_e32 v86, v74, v86, vcc
	v_cmp_gt_f32_e32 vcc, 0, v77
	v_and_b32_e32 v74, 0x7fffffff, v84
	v_mul_f32_e32 v64, v86, v56
	v_cndmask_b32_e32 v87, v75, v87, vcc
	v_and_b32_e32 v75, 0x7fffffff, v85
	v_pk_fma_f32 v[74:75], v[74:75], s[4:5], 1.0 op_sel_hi:[1,0,0]
	v_cmp_gt_f32_e32 vcc, 0, v84
	v_rcp_f32_e32 v74, v74
	v_rcp_f32_e32 v75, v75
	v_fma_f32 v56, v69, v61, v103
	v_mul_f32_e32 v61, v87, v57
	v_fma_f32 v57, v70, v62, v103
	v_pk_fma_f32 v[76:77], v[74:75], s[50:51], v[130:131] op_sel_hi:[1,0,0]
	v_mul_f32_e32 v56, v91, v56
	v_pk_fma_f32 v[76:77], v[74:75], v[76:77], s[52:53] op_sel_hi:[1,1,0]
	v_mul_f32_e32 v57, v88, v57
	v_pk_fma_f32 v[76:77], v[74:75], v[76:77], s[54:55] op_sel_hi:[1,1,0]
	v_cvt_pk_bf16_f32 v56, v60, v56
	v_and_b32_e32 v69, 0xffff0000, v81
	v_pk_fma_f32 v[76:77], v[74:75], v[76:77], s[56:57] op_sel_hi:[1,1,0]
	v_lshlrev_b32_e32 v70, 16, v83
	v_pk_mul_f32 v[74:75], v[74:75], v[76:77]
	v_pk_mul_f32 v[76:77], v[78:79], s[58:59] op_sel_hi:[1,0]
	s_nop 0
	v_exp_f32_e32 v76, v76
	v_exp_f32_e32 v77, v77
	s_nop 0
	v_pk_mul_f32 v[74:75], v[76:77], v[74:75]
	s_nop 0
	v_pk_mul_f32 v[76:77], v[74:75], v[84:85]
	v_pk_fma_f32 v[74:75], v[74:75], v[84:85], v[84:85] neg_lo:[1,0,0] neg_hi:[1,0,0]
	s_nop 0
	v_cndmask_b32_e32 v74, v74, v76, vcc
	v_cmp_gt_f32_e32 vcc, 0, v85
	v_mul_f32_e32 v62, v74, v58
	v_fma_f32 v58, v71, v63, v103
	v_cndmask_b32_e32 v75, v75, v77, vcc
	v_mul_f32_e32 v58, v89, v58
	v_mul_f32_e32 v59, v75, v59
	v_cvt_pk_bf16_f32 v57, v57, v58
	v_cvt_pk_bf16_f32 v58, v64, v61
	v_cvt_pk_bf16_f32 v59, v62, v59
	global_store_dwordx4 v[72:73], v[56:59], off offset:2176 sc1
	global_load_dwordx4 v[56:59], v[96:97], off offset:400
	s_nop 0
	global_load_dwordx4 v[60:63], v[96:97], off offset:384
	v_lshlrev_b32_e32 v64, 16, v80
	v_and_b32_e32 v75, 0x7fffffff, v65
	v_and_b32_e32 v74, 0x7fffffff, v64
	v_pk_fma_f32 v[74:75], v[74:75], s[4:5], 1.0 op_sel_hi:[1,0,0]
	v_pk_mul_f32 v[78:79], v[64:65], v[64:65]
	v_rcp_f32_e32 v74, v74
	v_rcp_f32_e32 v75, v75
	v_pk_mul_f32 v[78:79], v[78:79], s[58:59] op_sel_hi:[1,0]
	v_cmp_gt_f32_e32 vcc, 0, v64
	v_exp_f32_e32 v78, v78
	v_pk_fma_f32 v[76:77], v[74:75], s[50:51], v[130:131] op_sel_hi:[1,0,0]
	v_exp_f32_e32 v79, v79
	v_pk_fma_f32 v[76:77], v[74:75], v[76:77], s[52:53] op_sel_hi:[1,1,0]
	v_and_b32_e32 v71, 0xffff0000, v83
	v_pk_fma_f32 v[76:77], v[74:75], v[76:77], s[54:55] op_sel_hi:[1,1,0]
	s_waitcnt vmcnt(1)
	v_fma_f32 v48, v56, v48, v103
	v_pk_fma_f32 v[76:77], v[74:75], v[76:77], s[56:57] op_sel_hi:[1,1,0]
	v_fma_f32 v49, v57, v49, v103
	v_pk_mul_f32 v[74:75], v[74:75], v[76:77]
	v_pk_mul_f32 v[76:77], v[68:69], v[68:69]
	v_pk_mul_f32 v[74:75], v[78:79], v[74:75]
	v_fma_f32 v50, v58, v50, v103
	v_pk_mul_f32 v[78:79], v[74:75], v[64:65]
	v_pk_fma_f32 v[74:75], v[74:75], v[64:65], v[64:65] neg_lo:[1,0,0] neg_hi:[1,0,0]
	v_and_b32_e32 v64, 0x7fffffff, v68
	v_cndmask_b32_e32 v78, v74, v78, vcc
	v_cmp_gt_f32_e32 vcc, 0, v65
	v_and_b32_e32 v65, 0x7fffffff, v69
	v_pk_fma_f32 v[64:65], v[64:65], s[4:5], 1.0 op_sel_hi:[1,0,0]
	v_cndmask_b32_e32 v79, v75, v79, vcc
	v_rcp_f32_e32 v64, v64
	v_rcp_f32_e32 v65, v65
	v_cmp_gt_f32_e32 vcc, 0, v68
	s_waitcnt vmcnt(0)
	v_fma_f32 v52, v60, v52, v103
	v_mul_f32_e32 v52, v78, v52
	v_pk_fma_f32 v[74:75], v[64:65], s[50:51], v[130:131] op_sel_hi:[1,0,0]
	v_lshlrev_b32_e32 v60, 16, v44
	v_pk_fma_f32 v[74:75], v[64:65], v[74:75], s[52:53] op_sel_hi:[1,1,0]
	s_nop 0
	v_pk_fma_f32 v[74:75], v[64:65], v[74:75], s[54:55] op_sel_hi:[1,1,0]
	s_nop 0
	v_pk_fma_f32 v[74:75], v[64:65], v[74:75], s[56:57] op_sel_hi:[1,1,0]
	s_nop 0
	v_pk_mul_f32 v[64:65], v[64:65], v[74:75]
	v_pk_mul_f32 v[74:75], v[76:77], s[58:59] op_sel_hi:[1,0]
	s_nop 0
	v_exp_f32_e32 v74, v74
	v_exp_f32_e32 v75, v75
	s_nop 0
	v_pk_mul_f32 v[64:65], v[74:75], v[64:65]
	s_nop 0
	v_pk_mul_f32 v[74:75], v[64:65], v[68:69]
	v_pk_fma_f32 v[64:65], v[64:65], v[68:69], v[68:69] neg_lo:[1,0,0] neg_hi:[1,0,0]
	s_nop 0
	v_cndmask_b32_e32 v76, v64, v74, vcc
	v_cmp_gt_f32_e32 vcc, 0, v69
	v_and_b32_e32 v64, 0x7fffffff, v66
	s_nop 0
	v_cndmask_b32_e32 v77, v65, v75, vcc
	v_and_b32_e32 v65, 0x7fffffff, v67
	v_pk_fma_f32 v[64:65], v[64:65], s[4:5], 1.0 op_sel_hi:[1,0,0]
	v_pk_mul_f32 v[74:75], v[66:67], v[66:67]
	v_rcp_f32_e32 v64, v64
	v_rcp_f32_e32 v65, v65
	v_pk_mul_f32 v[74:75], v[74:75], s[58:59] op_sel_hi:[1,0]
	v_cmp_gt_f32_e32 vcc, 0, v66
	v_exp_f32_e32 v74, v74
	v_pk_fma_f32 v[68:69], v[64:65], s[50:51], v[130:131] op_sel_hi:[1,0,0]
	v_exp_f32_e32 v75, v75
	v_pk_fma_f32 v[68:69], v[64:65], v[68:69], s[52:53] op_sel_hi:[1,1,0]
	s_nop 0
	v_pk_fma_f32 v[68:69], v[64:65], v[68:69], s[54:55] op_sel_hi:[1,1,0]
	s_nop 0
	v_pk_fma_f32 v[68:69], v[64:65], v[68:69], s[56:57] op_sel_hi:[1,1,0]
	s_nop 0
	v_pk_mul_f32 v[64:65], v[64:65], v[68:69]
	v_pk_mul_f32 v[68:69], v[70:71], v[70:71]
	v_pk_mul_f32 v[64:65], v[74:75], v[64:65]
	s_nop 0
	v_pk_mul_f32 v[74:75], v[64:65], v[66:67]
	v_pk_fma_f32 v[64:65], v[64:65], v[66:67], v[66:67] neg_lo:[1,0,0] neg_hi:[1,0,0]
	s_nop 0
	v_cndmask_b32_e32 v74, v64, v74, vcc
	v_cmp_gt_f32_e32 vcc, 0, v67
	v_and_b32_e32 v64, 0x7fffffff, v70
	v_mul_f32_e32 v56, v74, v48
	v_cndmask_b32_e32 v75, v65, v75, vcc
	v_and_b32_e32 v65, 0x7fffffff, v71
	v_pk_fma_f32 v[64:65], v[64:65], s[4:5], 1.0 op_sel_hi:[1,0,0]
	v_cmp_gt_f32_e32 vcc, 0, v70
	v_rcp_f32_e32 v64, v64
	v_rcp_f32_e32 v65, v65
	v_fma_f32 v48, v61, v53, v103
	v_mul_f32_e32 v53, v75, v49
	v_fma_f32 v49, v62, v54, v103
	v_pk_fma_f32 v[66:67], v[64:65], s[50:51], v[130:131] op_sel_hi:[1,0,0]
	v_mul_f32_e32 v48, v79, v48
	v_pk_fma_f32 v[66:67], v[64:65], v[66:67], s[52:53] op_sel_hi:[1,1,0]
	v_mul_f32_e32 v49, v76, v49
	v_pk_fma_f32 v[66:67], v[64:65], v[66:67], s[54:55] op_sel_hi:[1,1,0]
	v_cvt_pk_bf16_f32 v48, v52, v48
	v_and_b32_e32 v61, 0xffff0000, v44
	v_pk_fma_f32 v[66:67], v[64:65], v[66:67], s[56:57] op_sel_hi:[1,1,0]
	v_lshlrev_b32_e32 v62, 16, v46
	v_pk_mul_f32 v[64:65], v[64:65], v[66:67]
	v_pk_mul_f32 v[66:67], v[68:69], s[58:59] op_sel_hi:[1,0]
	v_lshlrev_b32_e32 v44, 16, v47
	v_exp_f32_e32 v66, v66
	v_exp_f32_e32 v67, v67
	v_pk_mul_f32 v[68:69], v[60:61], v[60:61]
	v_pk_mul_f32 v[64:65], v[66:67], v[64:65]
	s_nop 0
	v_pk_mul_f32 v[66:67], v[64:65], v[70:71]
	v_pk_fma_f32 v[64:65], v[64:65], v[70:71], v[70:71] neg_lo:[1,0,0] neg_hi:[1,0,0]
	v_pk_mul_f32 v[68:69], v[68:69], s[58:59] op_sel_hi:[1,0]
	v_cndmask_b32_e32 v64, v64, v66, vcc
	v_cmp_gt_f32_e32 vcc, 0, v71
	v_mul_f32_e32 v54, v64, v50
	v_fma_f32 v50, v63, v55, v103
	v_cndmask_b32_e32 v65, v65, v67, vcc
	v_fmac_f32_e32 v103, v59, v51
	v_mul_f32_e32 v50, v77, v50
	v_mul_f32_e32 v51, v65, v103
	v_cvt_pk_bf16_f32 v49, v49, v50
	v_cvt_pk_bf16_f32 v50, v56, v53
	v_cvt_pk_bf16_f32 v51, v54, v51
	global_store_dwordx4 v[72:73], v[48:51], off offset:2240 sc1
	global_load_dword v50, v102, s[16:17] offset:64
	s_nop 0
	global_load_dwordx4 v[52:55], v[96:97], off offset:16
	global_load_dwordx4 v[56:59], v[96:97], off
	v_and_b32_e32 v63, 0xffff0000, v46
	v_and_b32_e32 v65, 0xffff0000, v45
	v_lshlrev_b32_e32 v64, 16, v45
	v_and_b32_e32 v45, 0xffff0000, v47
	v_and_b32_e32 v47, 0x7fffffff, v61
	v_and_b32_e32 v46, 0x7fffffff, v60
	v_pk_fma_f32 v[46:47], v[46:47], s[4:5], 1.0 op_sel_hi:[1,0,0]
	v_exp_f32_e32 v68, v68
	v_rcp_f32_e32 v46, v46
	v_rcp_f32_e32 v47, v47
	v_exp_f32_e32 v69, v69
	v_cmp_gt_f32_e32 vcc, 0, v60
	v_or_b32_e32 v48, 16, v100
	v_pk_fma_f32 v[66:67], v[46:47], s[50:51], v[130:131] op_sel_hi:[1,0,0]
	v_ashrrev_i32_e32 v49, 31, v48
	v_pk_fma_f32 v[66:67], v[46:47], v[66:67], s[52:53] op_sel_hi:[1,1,0]
	v_lshlrev_b64 v[48:49], 12, v[48:49]
	v_pk_fma_f32 v[66:67], v[46:47], v[66:67], s[54:55] op_sel_hi:[1,1,0]
	v_lshl_add_u64 v[48:49], s[48:49], 0, v[48:49]
	v_pk_fma_f32 v[66:67], v[46:47], v[66:67], s[56:57] op_sel_hi:[1,1,0]
	v_lshl_add_u64 v[48:49], v[48:49], 0, s[0:1]
	v_pk_mul_f32 v[46:47], v[46:47], v[66:67]
	v_pk_mul_f32 v[66:67], v[64:65], v[64:65]
	v_pk_mul_f32 v[46:47], v[68:69], v[46:47]
	s_waitcnt vmcnt(1)
	v_fma_f32 v24, v52, v24, v50
	v_pk_mul_f32 v[68:69], v[46:47], v[60:61]
	v_pk_fma_f32 v[46:47], v[46:47], v[60:61], v[60:61] neg_lo:[1,0,0] neg_hi:[1,0,0]
	v_fma_f32 v25, v53, v25, v50
	v_cndmask_b32_e32 v51, v46, v68, vcc
	v_cmp_gt_f32_e32 vcc, 0, v61
	v_and_b32_e32 v46, 0x7fffffff, v64
	v_fma_f32 v26, v54, v26, v50
	v_cndmask_b32_e32 v68, v47, v69, vcc
	v_and_b32_e32 v47, 0x7fffffff, v65
	v_pk_fma_f32 v[46:47], v[46:47], s[4:5], 1.0 op_sel_hi:[1,0,0]
	v_cmp_gt_f32_e32 vcc, 0, v64
	v_rcp_f32_e32 v46, v46
	v_rcp_f32_e32 v47, v47
	v_fma_f32 v27, v55, v27, v50
	s_waitcnt vmcnt(0)
	v_fma_f32 v28, v56, v28, v50
	v_mul_f32_e32 v28, v51, v28
	v_pk_fma_f32 v[60:61], v[46:47], s[50:51], v[130:131] op_sel_hi:[1,0,0]
	v_and_b32_e32 v53, 0xffff0000, v41
	v_pk_fma_f32 v[60:61], v[46:47], v[60:61], s[52:53] op_sel_hi:[1,1,0]
	v_lshlrev_b32_e32 v52, 16, v41
	v_pk_fma_f32 v[60:61], v[46:47], v[60:61], s[54:55] op_sel_hi:[1,1,0]
	v_and_b32_e32 v41, 0xffff0000, v43
	v_pk_fma_f32 v[60:61], v[46:47], v[60:61], s[56:57] op_sel_hi:[1,1,0]
	s_nop 0
	v_pk_mul_f32 v[46:47], v[46:47], v[60:61]
	v_pk_mul_f32 v[60:61], v[66:67], s[58:59] op_sel_hi:[1,0]
	s_nop 0
	v_exp_f32_e32 v60, v60
	v_exp_f32_e32 v61, v61
	s_nop 0
	v_pk_mul_f32 v[46:47], v[60:61], v[46:47]
	s_nop 0
	v_pk_mul_f32 v[60:61], v[46:47], v[64:65]
	v_pk_fma_f32 v[46:47], v[46:47], v[64:65], v[64:65] neg_lo:[1,0,0] neg_hi:[1,0,0]
	s_nop 0
	v_cndmask_b32_e32 v66, v46, v60, vcc
	v_cmp_gt_f32_e32 vcc, 0, v65
	v_and_b32_e32 v46, 0x7fffffff, v62
	v_pk_mul_f32 v[64:65], v[62:63], v[62:63]
	v_cndmask_b32_e32 v67, v47, v61, vcc
	v_and_b32_e32 v47, 0x7fffffff, v63
	v_pk_fma_f32 v[46:47], v[46:47], s[4:5], 1.0 op_sel_hi:[1,0,0]
	v_pk_mul_f32 v[64:65], v[64:65], s[58:59] op_sel_hi:[1,0]
	v_rcp_f32_e32 v46, v46
	v_rcp_f32_e32 v47, v47
	v_exp_f32_e32 v64, v64
	v_exp_f32_e32 v65, v65
	v_cmp_gt_f32_e32 vcc, 0, v62
	v_pk_fma_f32 v[60:61], v[46:47], s[50:51], v[130:131] op_sel_hi:[1,0,0]
	s_nop 0
	v_pk_fma_f32 v[60:61], v[46:47], v[60:61], s[52:53] op_sel_hi:[1,1,0]
	s_nop 0
	v_pk_fma_f32 v[60:61], v[46:47], v[60:61], s[54:55] op_sel_hi:[1,1,0]
	s_nop 0
	v_pk_fma_f32 v[60:61], v[46:47], v[60:61], s[56:57] op_sel_hi:[1,1,0]
	s_nop 0
	v_pk_mul_f32 v[46:47], v[46:47], v[60:61]
	v_pk_mul_f32 v[60:61], v[44:45], v[44:45]
	v_pk_mul_f32 v[46:47], v[64:65], v[46:47]
	v_pk_mul_f32 v[60:61], v[60:61], s[58:59] op_sel_hi:[1,0]
	v_pk_mul_f32 v[64:65], v[46:47], v[62:63]
	v_pk_fma_f32 v[46:47], v[46:47], v[62:63], v[62:63] neg_lo:[1,0,0] neg_hi:[1,0,0]
	v_exp_f32_e32 v60, v60
	v_cndmask_b32_e32 v64, v46, v64, vcc
	v_cmp_gt_f32_e32 vcc, 0, v63
	v_and_b32_e32 v46, 0x7fffffff, v44
	v_exp_f32_e32 v61, v61
	v_cndmask_b32_e32 v65, v47, v65, vcc
	v_and_b32_e32 v47, 0x7fffffff, v45
	v_pk_fma_f32 v[46:47], v[46:47], s[4:5], 1.0 op_sel_hi:[1,0,0]
	v_cmp_gt_f32_e32 vcc, 0, v44
	v_rcp_f32_e32 v46, v46
	v_rcp_f32_e32 v47, v47
	s_nop 0
	v_pk_fma_f32 v[62:63], v[46:47], s[50:51], v[130:131] op_sel_hi:[1,0,0]
	s_nop 0
	v_pk_fma_f32 v[62:63], v[46:47], v[62:63], s[52:53] op_sel_hi:[1,1,0]
	s_nop 0
	v_pk_fma_f32 v[62:63], v[46:47], v[62:63], s[54:55] op_sel_hi:[1,1,0]
	s_nop 0
	v_pk_fma_f32 v[62:63], v[46:47], v[62:63], s[56:57] op_sel_hi:[1,1,0]
	s_nop 0
	v_pk_mul_f32 v[46:47], v[46:47], v[62:63]
	s_nop 0
	v_pk_mul_f32 v[46:47], v[60:61], v[46:47]
	s_nop 0
	v_pk_mul_f32 v[60:61], v[46:47], v[44:45]
	v_pk_fma_f32 v[46:47], v[46:47], v[44:45], v[44:45] neg_lo:[1,0,0] neg_hi:[1,0,0]
	s_nop 0
	v_cndmask_b32_e32 v44, v46, v60, vcc
	v_cmp_gt_f32_e32 vcc, 0, v45
	v_mul_f32_e32 v46, v64, v24
	v_fma_f32 v24, v57, v29, v50
	v_cndmask_b32_e32 v45, v47, v61, vcc
	v_mul_f32_e32 v29, v65, v25
	v_fma_f32 v25, v58, v30, v50
	v_mul_f32_e32 v30, v44, v26
	v_fma_f32 v26, v59, v31, v50
	v_mul_f32_e32 v24, v68, v24
	v_mul_f32_e32 v25, v66, v25
	v_mul_f32_e32 v26, v67, v26
	v_mul_f32_e32 v27, v45, v27
	v_lshl_add_u64 v[44:45], v[48:49], 0, v[98:99]
	v_cvt_pk_bf16_f32 v24, v28, v24
	v_cvt_pk_bf16_f32 v25, v25, v26
	v_cvt_pk_bf16_f32 v26, v46, v29
	v_cvt_pk_bf16_f32 v27, v30, v27
	global_store_dwordx4 v[44:45], v[24:27], off offset:2048 sc1
	global_load_dwordx4 v[24:27], v[96:97], off offset:144
	s_nop 0
	global_load_dwordx4 v[28:31], v[96:97], off offset:128
	v_and_b32_e32 v47, 0xffff0000, v40
	v_lshlrev_b32_e32 v46, 16, v40
	v_and_b32_e32 v49, 0xffff0000, v42
	v_lshlrev_b32_e32 v48, 16, v42
	v_lshlrev_b32_e32 v40, 16, v43
	v_and_b32_e32 v43, 0x7fffffff, v47
	v_and_b32_e32 v42, 0x7fffffff, v46
	v_pk_fma_f32 v[42:43], v[42:43], s[4:5], 1.0 op_sel_hi:[1,0,0]
	v_pk_mul_f32 v[56:57], v[46:47], v[46:47]
	v_rcp_f32_e32 v42, v42
	v_rcp_f32_e32 v43, v43
	v_pk_mul_f32 v[56:57], v[56:57], s[58:59] op_sel_hi:[1,0]
	v_cmp_gt_f32_e32 vcc, 0, v46
	v_exp_f32_e32 v56, v56
	v_pk_fma_f32 v[54:55], v[42:43], s[50:51], v[130:131] op_sel_hi:[1,0,0]
	v_exp_f32_e32 v57, v57
	v_pk_fma_f32 v[54:55], v[42:43], v[54:55], s[52:53] op_sel_hi:[1,1,0]
	s_waitcnt vmcnt(1)
	v_fma_f32 v16, v24, v16, v50
	v_pk_fma_f32 v[54:55], v[42:43], v[54:55], s[54:55] op_sel_hi:[1,1,0]
	v_fma_f32 v17, v25, v17, v50
	v_pk_fma_f32 v[54:55], v[42:43], v[54:55], s[56:57] op_sel_hi:[1,1,0]
	v_fma_f32 v18, v26, v18, v50
	v_pk_mul_f32 v[42:43], v[42:43], v[54:55]
	v_pk_mul_f32 v[54:55], v[52:53], v[52:53]
	v_pk_mul_f32 v[42:43], v[56:57], v[42:43]
	v_fma_f32 v19, v27, v19, v50
	v_pk_mul_f32 v[56:57], v[42:43], v[46:47]
	v_pk_fma_f32 v[42:43], v[42:43], v[46:47], v[46:47] neg_lo:[1,0,0] neg_hi:[1,0,0]
	s_waitcnt vmcnt(0)
	v_fma_f32 v20, v28, v20, v50
	v_cndmask_b32_e32 v51, v42, v56, vcc
	v_cmp_gt_f32_e32 vcc, 0, v47
	v_and_b32_e32 v42, 0x7fffffff, v52
	v_mul_f32_e32 v20, v51, v20
	v_cndmask_b32_e32 v56, v43, v57, vcc
	v_and_b32_e32 v43, 0x7fffffff, v53
	v_pk_fma_f32 v[42:43], v[42:43], s[4:5], 1.0 op_sel_hi:[1,0,0]
	v_cmp_gt_f32_e32 vcc, 0, v52
	v_rcp_f32_e32 v42, v42
	v_rcp_f32_e32 v43, v43
	v_and_b32_e32 v25, 0xffff0000, v36
	v_lshlrev_b32_e32 v28, 16, v37
	v_and_b32_e32 v27, 0xffff0000, v38
	v_pk_fma_f32 v[46:47], v[42:43], s[50:51], v[130:131] op_sel_hi:[1,0,0]
	v_lshlrev_b32_e32 v26, 16, v38
	v_pk_fma_f32 v[46:47], v[42:43], v[46:47], s[52:53] op_sel_hi:[1,1,0]
	s_nop 0
	v_pk_fma_f32 v[46:47], v[42:43], v[46:47], s[54:55] op_sel_hi:[1,1,0]
	s_nop 0
	v_pk_fma_f32 v[46:47], v[42:43], v[46:47], s[56:57] op_sel_hi:[1,1,0]
	s_nop 0
	v_pk_mul_f32 v[42:43], v[42:43], v[46:47]
	v_pk_mul_f32 v[46:47], v[54:55], s[58:59] op_sel_hi:[1,0]
	s_nop 0
	v_exp_f32_e32 v46, v46
	v_exp_f32_e32 v47, v47
	s_nop 0
	v_pk_mul_f32 v[42:43], v[46:47], v[42:43]
	s_nop 0
	v_pk_mul_f32 v[46:47], v[42:43], v[52:53]
	v_pk_fma_f32 v[42:43], v[42:43], v[52:53], v[52:53] neg_lo:[1,0,0] neg_hi:[1,0,0]
	s_nop 0
	v_cndmask_b32_e32 v54, v42, v46, vcc
	v_cmp_gt_f32_e32 vcc, 0, v53
	v_and_b32_e32 v42, 0x7fffffff, v48
	v_pk_mul_f32 v[52:53], v[48:49], v[48:49]
	v_cndmask_b32_e32 v55, v43, v47, vcc
	v_and_b32_e32 v43, 0x7fffffff, v49
	v_pk_fma_f32 v[42:43], v[42:43], s[4:5], 1.0 op_sel_hi:[1,0,0]
	v_pk_mul_f32 v[52:53], v[52:53], s[58:59] op_sel_hi:[1,0]
	v_rcp_f32_e32 v42, v42
	v_rcp_f32_e32 v43, v43
	v_exp_f32_e32 v52, v52
	v_exp_f32_e32 v53, v53
	v_cmp_gt_f32_e32 vcc, 0, v48
	v_pk_fma_f32 v[46:47], v[42:43], s[50:51], v[130:131] op_sel_hi:[1,0,0]
	s_nop 0
	v_pk_fma_f32 v[46:47], v[42:43], v[46:47], s[52:53] op_sel_hi:[1,1,0]
	s_nop 0
	v_pk_fma_f32 v[46:47], v[42:43], v[46:47], s[54:55] op_sel_hi:[1,1,0]
	s_nop 0
	v_pk_fma_f32 v[46:47], v[42:43], v[46:47], s[56:57] op_sel_hi:[1,1,0]
	s_nop 0
	v_pk_mul_f32 v[42:43], v[42:43], v[46:47]
	v_pk_mul_f32 v[46:47], v[40:41], v[40:41]
	v_pk_mul_f32 v[42:43], v[52:53], v[42:43]
	v_pk_mul_f32 v[46:47], v[46:47], s[58:59] op_sel_hi:[1,0]
	v_pk_mul_f32 v[52:53], v[42:43], v[48:49]
	v_pk_fma_f32 v[42:43], v[42:43], v[48:49], v[48:49] neg_lo:[1,0,0] neg_hi:[1,0,0]
	v_exp_f32_e32 v46, v46
	v_cndmask_b32_e32 v52, v42, v52, vcc
	v_cmp_gt_f32_e32 vcc, 0, v49
	v_and_b32_e32 v42, 0x7fffffff, v40
	v_exp_f32_e32 v47, v47
	v_cndmask_b32_e32 v53, v43, v53, vcc
	v_and_b32_e32 v43, 0x7fffffff, v41
	v_pk_fma_f32 v[42:43], v[42:43], s[4:5], 1.0 op_sel_hi:[1,0,0]
	v_cmp_gt_f32_e32 vcc, 0, v40
	v_rcp_f32_e32 v42, v42
	v_rcp_f32_e32 v43, v43
	v_mul_f32_e32 v24, v52, v16
	v_fma_f32 v16, v29, v21, v50
	v_mul_f32_e32 v21, v53, v17
	v_pk_fma_f32 v[48:49], v[42:43], s[50:51], v[130:131] op_sel_hi:[1,0,0]
	v_fma_f32 v17, v30, v22, v50
	v_pk_fma_f32 v[48:49], v[42:43], v[48:49], s[52:53] op_sel_hi:[1,1,0]
	v_mul_f32_e32 v16, v56, v16
	v_pk_fma_f32 v[48:49], v[42:43], v[48:49], s[54:55] op_sel_hi:[1,1,0]
	v_mul_f32_e32 v17, v54, v17
	v_pk_fma_f32 v[48:49], v[42:43], v[48:49], s[56:57] op_sel_hi:[1,1,0]
	v_cvt_pk_bf16_f32 v16, v20, v16
	v_and_b32_e32 v29, 0xffff0000, v37
	v_pk_mul_f32 v[42:43], v[42:43], v[48:49]
	v_and_b32_e32 v37, 0x7fffffff, v25
	v_pk_mul_f32 v[42:43], v[46:47], v[42:43]
	v_lshlrev_b32_e32 v30, 16, v39
	v_pk_mul_f32 v[46:47], v[42:43], v[40:41]
	v_pk_fma_f32 v[42:43], v[42:43], v[40:41], v[40:41] neg_lo:[1,0,0] neg_hi:[1,0,0]
	s_nop 0
	v_cndmask_b32_e32 v40, v42, v46, vcc
	v_cmp_gt_f32_e32 vcc, 0, v41
	v_mul_f32_e32 v22, v40, v18
	v_fma_f32 v18, v31, v23, v50
	v_cndmask_b32_e32 v41, v43, v47, vcc
	v_mul_f32_e32 v18, v55, v18
	v_mul_f32_e32 v19, v41, v19
	v_cvt_pk_bf16_f32 v17, v17, v18
	v_cvt_pk_bf16_f32 v18, v24, v21
	v_cvt_pk_bf16_f32 v19, v22, v19
	global_store_dwordx4 v[44:45], v[16:19], off offset:2112 sc1
	global_load_dwordx4 v[16:19], v[96:97], off offset:272
	s_nop 0
	global_load_dwordx4 v[20:23], v[96:97], off offset:256
	v_lshlrev_b32_e32 v24, 16, v36
	v_and_b32_e32 v36, 0x7fffffff, v24
	v_pk_fma_f32 v[36:37], v[36:37], s[4:5], 1.0 op_sel_hi:[1,0,0]
	v_pk_mul_f32 v[40:41], v[24:25], v[24:25]
	v_rcp_f32_e32 v36, v36
	v_rcp_f32_e32 v37, v37
	v_and_b32_e32 v31, 0xffff0000, v39
	v_pk_mul_f32 v[40:41], v[40:41], s[58:59] op_sel_hi:[1,0]
	v_cmp_gt_f32_e32 vcc, 0, v24
	v_pk_fma_f32 v[38:39], v[36:37], s[50:51], v[130:131] op_sel_hi:[1,0,0]
	v_exp_f32_e32 v40, v40
	v_pk_fma_f32 v[38:39], v[36:37], v[38:39], s[52:53] op_sel_hi:[1,1,0]
	v_exp_f32_e32 v41, v41
	v_pk_fma_f32 v[38:39], v[36:37], v[38:39], s[54:55] op_sel_hi:[1,1,0]
	s_waitcnt vmcnt(1)
	v_fma_f32 v8, v16, v8, v50
	v_pk_fma_f32 v[38:39], v[36:37], v[38:39], s[56:57] op_sel_hi:[1,1,0]
	v_fma_f32 v9, v17, v9, v50
	v_pk_mul_f32 v[36:37], v[36:37], v[38:39]
	v_pk_mul_f32 v[38:39], v[28:29], v[28:29]
	v_pk_mul_f32 v[36:37], v[40:41], v[36:37]
	v_fma_f32 v10, v18, v10, v50
	v_pk_mul_f32 v[40:41], v[36:37], v[24:25]
	v_pk_fma_f32 v[36:37], v[36:37], v[24:25], v[24:25] neg_lo:[1,0,0] neg_hi:[1,0,0]
	v_and_b32_e32 v24, 0x7fffffff, v28
	v_cndmask_b32_e32 v40, v36, v40, vcc
	v_cmp_gt_f32_e32 vcc, 0, v25
	v_and_b32_e32 v25, 0x7fffffff, v29
	v_pk_fma_f32 v[24:25], v[24:25], s[4:5], 1.0 op_sel_hi:[1,0,0]
	v_cndmask_b32_e32 v41, v37, v41, vcc
	v_rcp_f32_e32 v24, v24
	v_rcp_f32_e32 v25, v25
	v_cmp_gt_f32_e32 vcc, 0, v28
	v_fma_f32 v11, v19, v11, v50
	s_waitcnt vmcnt(0)
	v_fma_f32 v12, v20, v12, v50
	v_pk_fma_f32 v[36:37], v[24:25], s[50:51], v[130:131] op_sel_hi:[1,0,0]
	v_mul_f32_e32 v12, v40, v12
	v_pk_fma_f32 v[36:37], v[24:25], v[36:37], s[52:53] op_sel_hi:[1,1,0]
	v_lshlrev_b32_e32 v20, 16, v33
	v_pk_fma_f32 v[36:37], v[24:25], v[36:37], s[54:55] op_sel_hi:[1,1,0]
	v_and_b32_e32 v19, 0xffff0000, v34
	v_pk_fma_f32 v[36:37], v[24:25], v[36:37], s[56:57] op_sel_hi:[1,1,0]
	v_lshlrev_b32_e32 v18, 16, v34
	v_pk_mul_f32 v[24:25], v[24:25], v[36:37]
	v_pk_mul_f32 v[36:37], v[38:39], s[58:59] op_sel_hi:[1,0]
	v_and_b32_e32 v17, 0xffff0000, v35
	v_exp_f32_e32 v36, v36
	v_exp_f32_e32 v37, v37
	s_nop 0
	v_pk_mul_f32 v[24:25], v[36:37], v[24:25]
	s_nop 0
	v_pk_mul_f32 v[36:37], v[24:25], v[28:29]
	v_pk_fma_f32 v[24:25], v[24:25], v[28:29], v[28:29] neg_lo:[1,0,0] neg_hi:[1,0,0]
	s_nop 0
	v_cndmask_b32_e32 v38, v24, v36, vcc
	v_cmp_gt_f32_e32 vcc, 0, v29
	v_and_b32_e32 v24, 0x7fffffff, v26
	s_nop 0
	v_cndmask_b32_e32 v39, v25, v37, vcc
	v_and_b32_e32 v25, 0x7fffffff, v27
	v_pk_fma_f32 v[24:25], v[24:25], s[4:5], 1.0 op_sel_hi:[1,0,0]
	v_pk_mul_f32 v[36:37], v[26:27], v[26:27]
	v_rcp_f32_e32 v24, v24
	v_rcp_f32_e32 v25, v25
	v_pk_mul_f32 v[36:37], v[36:37], s[58:59] op_sel_hi:[1,0]
	v_cmp_gt_f32_e32 vcc, 0, v26
	v_exp_f32_e32 v36, v36
	v_pk_fma_f32 v[28:29], v[24:25], s[50:51], v[130:131] op_sel_hi:[1,0,0]
	v_exp_f32_e32 v37, v37
	v_pk_fma_f32 v[28:29], v[24:25], v[28:29], s[52:53] op_sel_hi:[1,1,0]
	s_nop 0
	v_pk_fma_f32 v[28:29], v[24:25], v[28:29], s[54:55] op_sel_hi:[1,1,0]
	s_nop 0
	v_pk_fma_f32 v[28:29], v[24:25], v[28:29], s[56:57] op_sel_hi:[1,1,0]
	s_nop 0
	v_pk_mul_f32 v[24:25], v[24:25], v[28:29]
	v_pk_mul_f32 v[28:29], v[30:31], v[30:31]
	v_pk_mul_f32 v[24:25], v[36:37], v[24:25]
	s_nop 0
	v_pk_mul_f32 v[36:37], v[24:25], v[26:27]
	v_pk_fma_f32 v[24:25], v[24:25], v[26:27], v[26:27] neg_lo:[1,0,0] neg_hi:[1,0,0]
	s_nop 0
	v_cndmask_b32_e32 v36, v24, v36, vcc
	v_cmp_gt_f32_e32 vcc, 0, v27
	v_and_b32_e32 v24, 0x7fffffff, v30
	v_mul_f32_e32 v16, v36, v8
	v_cndmask_b32_e32 v37, v25, v37, vcc
	v_and_b32_e32 v25, 0x7fffffff, v31
	v_pk_fma_f32 v[24:25], v[24:25], s[4:5], 1.0 op_sel_hi:[1,0,0]
	v_cmp_gt_f32_e32 vcc, 0, v30
	v_rcp_f32_e32 v24, v24
	v_rcp_f32_e32 v25, v25
	v_fma_f32 v8, v21, v13, v50
	v_mul_f32_e32 v13, v37, v9
	v_fma_f32 v9, v22, v14, v50
	v_pk_fma_f32 v[26:27], v[24:25], s[50:51], v[130:131] op_sel_hi:[1,0,0]
	v_mul_f32_e32 v8, v41, v8
	v_pk_fma_f32 v[26:27], v[24:25], v[26:27], s[52:53] op_sel_hi:[1,1,0]
	v_mul_f32_e32 v9, v38, v9
	v_pk_fma_f32 v[26:27], v[24:25], v[26:27], s[54:55] op_sel_hi:[1,1,0]
	v_cvt_pk_bf16_f32 v8, v12, v8
	v_lshlrev_b32_e32 v22, 16, v32
	v_pk_fma_f32 v[26:27], v[24:25], v[26:27], s[56:57] op_sel_hi:[1,1,0]
	v_and_b32_e32 v21, 0xffff0000, v33
	v_pk_mul_f32 v[24:25], v[24:25], v[26:27]
	v_pk_mul_f32 v[26:27], v[28:29], s[58:59] op_sel_hi:[1,0]
	s_nop 0
	v_exp_f32_e32 v26, v26
	v_exp_f32_e32 v27, v27
	s_nop 0
	v_pk_mul_f32 v[24:25], v[26:27], v[24:25]
	s_nop 0
	v_pk_mul_f32 v[26:27], v[24:25], v[30:31]
	v_pk_fma_f32 v[24:25], v[24:25], v[30:31], v[30:31] neg_lo:[1,0,0] neg_hi:[1,0,0]
	s_nop 0
	v_cndmask_b32_e32 v24, v24, v26, vcc
	v_cmp_gt_f32_e32 vcc, 0, v31
	v_mul_f32_e32 v14, v24, v10
	v_fma_f32 v10, v23, v15, v50
	v_cndmask_b32_e32 v25, v25, v27, vcc
	v_mul_f32_e32 v10, v39, v10
	v_mul_f32_e32 v11, v25, v11
	v_cvt_pk_bf16_f32 v9, v9, v10
	v_cvt_pk_bf16_f32 v10, v16, v13
	v_cvt_pk_bf16_f32 v11, v14, v11
	global_store_dwordx4 v[44:45], v[8:11], off offset:2176 sc1
	global_load_dwordx4 v[8:11], v[96:97], off offset:400
	s_nop 0
	global_load_dwordx4 v[12:15], v[96:97], off offset:384
	v_and_b32_e32 v23, 0xffff0000, v32
	v_and_b32_e32 v25, 0x7fffffff, v23
	v_and_b32_e32 v24, 0x7fffffff, v22
	v_pk_fma_f32 v[24:25], v[24:25], s[4:5], 1.0 op_sel_hi:[1,0,0]
	v_pk_mul_f32 v[28:29], v[22:23], v[22:23]
	v_rcp_f32_e32 v24, v24
	v_rcp_f32_e32 v25, v25
	v_pk_mul_f32 v[28:29], v[28:29], s[58:59] op_sel_hi:[1,0]
	v_cmp_gt_f32_e32 vcc, 0, v22
	v_exp_f32_e32 v28, v28
	v_pk_fma_f32 v[26:27], v[24:25], s[50:51], v[130:131] op_sel_hi:[1,0,0]
	v_exp_f32_e32 v29, v29
	v_pk_fma_f32 v[26:27], v[24:25], v[26:27], s[52:53] op_sel_hi:[1,1,0]
	v_lshlrev_b32_e32 v16, 16, v35
	v_pk_fma_f32 v[26:27], v[24:25], v[26:27], s[54:55] op_sel_hi:[1,1,0]
	s_waitcnt vmcnt(1)
	v_fma_f32 v0, v8, v0, v50
	v_pk_fma_f32 v[26:27], v[24:25], v[26:27], s[56:57] op_sel_hi:[1,1,0]
	v_fma_f32 v1, v9, v1, v50
	v_pk_mul_f32 v[24:25], v[24:25], v[26:27]
	v_pk_mul_f32 v[26:27], v[20:21], v[20:21]
	v_pk_mul_f32 v[24:25], v[28:29], v[24:25]
	v_fma_f32 v2, v10, v2, v50
	v_pk_mul_f32 v[28:29], v[24:25], v[22:23]
	v_pk_fma_f32 v[24:25], v[24:25], v[22:23], v[22:23] neg_lo:[1,0,0] neg_hi:[1,0,0]
	v_and_b32_e32 v22, 0x7fffffff, v20
	v_cndmask_b32_e32 v28, v24, v28, vcc
	v_cmp_gt_f32_e32 vcc, 0, v23
	v_and_b32_e32 v23, 0x7fffffff, v21
	v_pk_fma_f32 v[22:23], v[22:23], s[4:5], 1.0 op_sel_hi:[1,0,0]
	v_cndmask_b32_e32 v29, v25, v29, vcc
	v_rcp_f32_e32 v22, v22
	v_rcp_f32_e32 v23, v23
	v_cmp_gt_f32_e32 vcc, 0, v20
	s_waitcnt vmcnt(0)
	v_fma_f32 v4, v12, v4, v50
	v_mul_f32_e32 v4, v28, v4
	v_pk_fma_f32 v[24:25], v[22:23], s[50:51], v[130:131] op_sel_hi:[1,0,0]
	s_nop 0
	v_pk_fma_f32 v[24:25], v[22:23], v[24:25], s[52:53] op_sel_hi:[1,1,0]
	s_nop 0
	v_pk_fma_f32 v[24:25], v[22:23], v[24:25], s[54:55] op_sel_hi:[1,1,0]
	s_nop 0
	v_pk_fma_f32 v[24:25], v[22:23], v[24:25], s[56:57] op_sel_hi:[1,1,0]
	s_nop 0
	v_pk_mul_f32 v[22:23], v[22:23], v[24:25]
	v_pk_mul_f32 v[24:25], v[26:27], s[58:59] op_sel_hi:[1,0]
	s_nop 0
	v_exp_f32_e32 v24, v24
	v_exp_f32_e32 v25, v25
	s_nop 0
	v_pk_mul_f32 v[22:23], v[24:25], v[22:23]
	s_nop 0
	v_pk_mul_f32 v[24:25], v[22:23], v[20:21]
	v_pk_fma_f32 v[22:23], v[22:23], v[20:21], v[20:21] neg_lo:[1,0,0] neg_hi:[1,0,0]
	v_and_b32_e32 v20, 0x7fffffff, v18
	v_cndmask_b32_e32 v26, v22, v24, vcc
	v_cmp_gt_f32_e32 vcc, 0, v21
	v_and_b32_e32 v21, 0x7fffffff, v19
	v_pk_fma_f32 v[20:21], v[20:21], s[4:5], 1.0 op_sel_hi:[1,0,0]
	v_cndmask_b32_e32 v27, v23, v25, vcc
	v_rcp_f32_e32 v20, v20
	v_rcp_f32_e32 v21, v21
	v_pk_mul_f32 v[24:25], v[18:19], v[18:19]
	v_cmp_gt_f32_e32 vcc, 0, v18
	v_pk_mul_f32 v[24:25], v[24:25], s[58:59] op_sel_hi:[1,0]
	v_pk_fma_f32 v[22:23], v[20:21], s[50:51], v[130:131] op_sel_hi:[1,0,0]
	v_exp_f32_e32 v24, v24
	v_pk_fma_f32 v[22:23], v[20:21], v[22:23], s[52:53] op_sel_hi:[1,1,0]
	v_exp_f32_e32 v25, v25
	v_pk_fma_f32 v[22:23], v[20:21], v[22:23], s[54:55] op_sel_hi:[1,1,0]
	s_nop 0
	v_pk_fma_f32 v[22:23], v[20:21], v[22:23], s[56:57] op_sel_hi:[1,1,0]
	s_nop 0
	v_pk_mul_f32 v[20:21], v[20:21], v[22:23]
	v_pk_mul_f32 v[22:23], v[16:17], v[16:17]
	v_pk_mul_f32 v[20:21], v[24:25], v[20:21]
	s_nop 0
	v_pk_mul_f32 v[24:25], v[20:21], v[18:19]
	v_pk_fma_f32 v[20:21], v[20:21], v[18:19], v[18:19] neg_lo:[1,0,0] neg_hi:[1,0,0]
	v_and_b32_e32 v18, 0x7fffffff, v16
	v_cndmask_b32_e32 v24, v20, v24, vcc
	v_cmp_gt_f32_e32 vcc, 0, v19
	v_and_b32_e32 v19, 0x7fffffff, v17
	v_pk_fma_f32 v[18:19], v[18:19], s[4:5], 1.0 op_sel_hi:[1,0,0]
	v_cndmask_b32_e32 v25, v21, v25, vcc
	v_rcp_f32_e32 v18, v18
	v_rcp_f32_e32 v19, v19
	v_cmp_gt_f32_e32 vcc, 0, v16
	v_mul_f32_e32 v8, v24, v0
	v_fma_f32 v0, v13, v5, v50
	v_pk_fma_f32 v[20:21], v[18:19], s[50:51], v[130:131] op_sel_hi:[1,0,0]
	v_mul_f32_e32 v5, v25, v1
	v_pk_fma_f32 v[20:21], v[18:19], v[20:21], s[52:53] op_sel_hi:[1,1,0]
	v_fma_f32 v1, v14, v6, v50
	v_pk_fma_f32 v[20:21], v[18:19], v[20:21], s[54:55] op_sel_hi:[1,1,0]
	s_add_i32 s53, s53, s5
	v_pk_fma_f32 v[20:21], v[18:19], v[20:21], s[56:57] op_sel_hi:[1,1,0]
	s_add_i32 s51, s51, s63
	v_pk_mul_f32 v[18:19], v[18:19], v[20:21]
	v_pk_mul_f32 v[20:21], v[22:23], s[58:59] op_sel_hi:[1,0]
	s_add_i32 s59, s59, s62
	v_exp_f32_e32 v20, v20
	v_exp_f32_e32 v21, v21
	v_mul_f32_e32 v0, v29, v0
	v_mul_f32_e32 v1, v26, v1
	s_cmpk_gt_i32 s53, 0x1ff
	v_pk_mul_f32 v[18:19], v[20:21], v[18:19]
	v_cvt_pk_bf16_f32 v0, v4, v0
	s_nop 0
	v_pk_mul_f32 v[20:21], v[18:19], v[16:17]
	v_pk_fma_f32 v[18:19], v[18:19], v[16:17], v[16:17] neg_lo:[1,0,0] neg_hi:[1,0,0]
	s_nop 0
	v_cndmask_b32_e32 v16, v18, v20, vcc
	v_cmp_gt_f32_e32 vcc, 0, v17
	v_mul_f32_e32 v6, v16, v2
	v_fma_f32 v2, v15, v7, v50
	v_cndmask_b32_e32 v17, v19, v21, vcc
	v_fmac_f32_e32 v50, v11, v3
	v_mul_f32_e32 v2, v27, v2
	v_mul_f32_e32 v3, v17, v50
	v_cvt_pk_bf16_f32 v1, v1, v2
	v_cvt_pk_bf16_f32 v2, v8, v5
	v_cvt_pk_bf16_f32 v3, v6, v3
	global_store_dwordx4 v[44:45], v[0:3], off offset:2240 sc1
	s_cbranch_scc0 .LBB0_277

.LBB0_283:
	v_mov_b32_e32 v163, v166
	s_waitcnt vmcnt(14)
	v_cvt_pk_bf16_f32 v120, v120, v124
	s_lshl_b64 s[4:5], s[4:5], 1
	v_lshlrev_b32_e32 v128, 9, v163
	v_ashrrev_i32_e32 v167, 2, v163
	v_and_b32_e32 v128, 0x1e00, v128
	v_and_b32_e32 v167, -4, v167
	v_add3_u32 v167, s25, v128, v167
	v_lshlrev_b32_e32 v128, 4, v163
	v_and_b32_e32 v128, 0x70, v128
	v_add_u32_e32 v168, v167, v128
	ds_write_b32 v168, v120
	v_cvt_pk_bf16_f32 v120, v121, v125
	ds_write_b32 v168, v120 offset:128
	v_cvt_pk_bf16_f32 v120, v122, v126
	ds_write_b32 v168, v120 offset:256
	v_cvt_pk_bf16_f32 v120, v123, v127
	ds_write_b32 v168, v120 offset:384
	v_xad_u32 v120, v128, 16, v167
	s_waitcnt vmcnt(12)
	v_cvt_pk_bf16_f32 v112, v112, v116
	ds_write_b32 v120, v112
	v_cvt_pk_bf16_f32 v112, v113, v117
	ds_write_b32 v120, v112 offset:128
	v_cvt_pk_bf16_f32 v112, v114, v118
	ds_write_b32 v120, v112 offset:256
	v_cvt_pk_bf16_f32 v112, v115, v119
	ds_write_b32 v120, v112 offset:384
	v_xad_u32 v112, v128, 32, v167
	s_waitcnt vmcnt(10)
	v_cvt_pk_bf16_f32 v104, v104, v108
	ds_write_b32 v112, v104
	v_cvt_pk_bf16_f32 v104, v105, v109
	ds_write_b32 v112, v104 offset:128
	v_cvt_pk_bf16_f32 v104, v106, v110
	ds_write_b32 v112, v104 offset:256
	v_cvt_pk_bf16_f32 v104, v107, v111
	ds_write_b32 v112, v104 offset:384
	v_xad_u32 v104, v128, 48, v167
	s_waitcnt vmcnt(8)
	v_cvt_pk_bf16_f32 v96, v96, v100
	ds_write_b32 v104, v96
	v_cvt_pk_bf16_f32 v96, v97, v101
	ds_write_b32 v104, v96 offset:128
	v_cvt_pk_bf16_f32 v96, v98, v102
	ds_write_b32 v104, v96 offset:256
	v_cvt_pk_bf16_f32 v96, v99, v103
	ds_write_b32 v104, v96 offset:384
	v_xad_u32 v96, v128, 64, v167
	s_waitcnt vmcnt(6)
	v_cvt_pk_bf16_f32 v88, v88, v92
	ds_write_b32 v96, v88
	v_cvt_pk_bf16_f32 v88, v89, v93
	ds_write_b32 v96, v88 offset:128
	v_cvt_pk_bf16_f32 v88, v90, v94
	ds_write_b32 v96, v88 offset:256
	v_cvt_pk_bf16_f32 v88, v91, v95
	ds_write_b32 v96, v88 offset:384
	v_xad_u32 v88, v128, s23, v167
	s_waitcnt vmcnt(4)
	v_cvt_pk_bf16_f32 v80, v80, v84
	ds_write_b32 v88, v80
	v_cvt_pk_bf16_f32 v80, v81, v85
	ds_write_b32 v88, v80 offset:128
	v_cvt_pk_bf16_f32 v80, v82, v86
	ds_write_b32 v88, v80 offset:256
	v_cvt_pk_bf16_f32 v80, v83, v87
	ds_write_b32 v88, v80 offset:384
	v_xad_u32 v80, v128, s44, v167
	s_waitcnt vmcnt(2)
	v_cvt_pk_bf16_f32 v72, v72, v76
	ds_write_b32 v80, v72
	v_cvt_pk_bf16_f32 v72, v73, v77
	ds_write_b32 v80, v72 offset:128
	v_cvt_pk_bf16_f32 v72, v74, v78
	ds_write_b32 v80, v72 offset:256
	v_cvt_pk_bf16_f32 v72, v75, v79
	ds_write_b32 v80, v72 offset:384
	v_xad_u32 v72, v128, s22, v167
	s_waitcnt vmcnt(0)
	v_cvt_pk_bf16_f32 v64, v64, v68
	v_ashrrev_i32_e32 v82, 3, v163
	ds_write_b32 v72, v64
	v_cvt_pk_bf16_f32 v64, v65, v69
	v_lshrrev_b32_e32 v65, 2, v82
	ds_write_b32 v72, v64 offset:128
	v_cvt_pk_bf16_f32 v64, v66, v70
	v_xor_b32_e32 v65, v65, v163
	ds_write_b32 v72, v64 offset:256
	v_cvt_pk_bf16_f32 v64, v67, v71
	ds_write_b32 v72, v64 offset:384
	v_lshlrev_b32_e32 v65, 4, v65
	s_waitcnt lgkmcnt(0)
	v_lshlrev_b32_e32 v64, 7, v82
	v_and_b32_e32 v65, 0x70, v65
	v_add3_u32 v70, s25, v64, v65
	ds_read_b128 v[64:67], v70
	v_subrev_u32_e32 v68, s50, v82
	s_add_u32 s4, s68, s4
	v_add_u32_e32 v78, s47, v68
	s_addc_u32 s5, s69, s5
	v_ashrrev_i32_e32 v79, 31, v78
	v_lshl_add_u64 v[76:77], s[4:5], 0, v[128:129]
	v_lshlrev_b64 v[68:69], 12, v[78:79]
	v_lshl_add_u64 v[72:73], v[76:77], 0, v[68:69]
	s_waitcnt lgkmcnt(0)
	global_store_dwordx4 v[72:73], v[64:67], off sc1
	v_add_u32_e32 v72, 8, v78
	v_ashrrev_i32_e32 v73, 31, v72
	v_add_u32_e32 v64, 8, v82
	v_lshlrev_b32_e32 v65, 7, v64
	v_lshrrev_b32_e32 v64, 2, v64
	v_xor_b32_e32 v64, v64, v163
	v_lshlrev_b32_e32 v64, 4, v64
	v_lshlrev_b64 v[72:73], 12, v[72:73]
	v_and_b32_e32 v64, 0x70, v64
	v_lshl_add_u64 v[80:81], v[76:77], 0, v[72:73]
	v_add_u32_e32 v72, 16, v82
	v_add3_u32 v64, s25, v65, v64
	v_lshlrev_b32_e32 v73, 7, v72
	v_lshrrev_b32_e32 v72, 2, v72
	ds_read_b128 v[68:71], v70 offset:4096
	ds_read_b128 v[64:67], v64
	v_xor_b32_e32 v72, v72, v163
	v_lshlrev_b32_e32 v72, 4, v72
	v_and_b32_e32 v72, 0x70, v72
	v_add3_u32 v72, s25, v73, v72
	ds_read_b128 v[72:75], v72
	s_waitcnt lgkmcnt(1)
	global_store_dwordx4 v[80:81], v[64:67], off sc1
	s_andn2_b64 vcc, exec, s[0:1]
	s_nop 0
	v_add_u32_e32 v64, 16, v78
	v_ashrrev_i32_e32 v65, 31, v64
	v_lshlrev_b64 v[64:65], 12, v[64:65]
	v_lshl_add_u64 v[64:65], v[76:77], 0, v[64:65]
	s_waitcnt lgkmcnt(0)
	global_store_dwordx4 v[64:65], v[72:75], off sc1
	v_add_u32_e32 v64, 24, v82
	v_lshlrev_b32_e32 v65, 7, v64
	v_lshrrev_b32_e32 v64, 2, v64
	v_xor_b32_e32 v64, v64, v163
	v_add_u32_e32 v72, 24, v78
	v_lshlrev_b32_e32 v64, 4, v64
	v_ashrrev_i32_e32 v73, 31, v72
	v_and_b32_e32 v64, 0x70, v64
	v_lshlrev_b64 v[72:73], 12, v[72:73]
	v_add3_u32 v64, s25, v65, v64
	v_lshl_add_u64 v[80:81], v[76:77], 0, v[72:73]
	v_add_u32_e32 v72, 40, v82
	ds_read_b128 v[64:67], v64
	v_lshlrev_b32_e32 v73, 7, v72
	v_lshrrev_b32_e32 v72, 2, v72
	v_xor_b32_e32 v72, v72, v163
	v_lshlrev_b32_e32 v72, 4, v72
	v_and_b32_e32 v72, 0x70, v72
	v_add3_u32 v72, s25, v73, v72
	ds_read_b128 v[72:75], v72
	s_waitcnt lgkmcnt(1)
	global_store_dwordx4 v[80:81], v[64:67], off sc1
	s_nop 1
	v_add_u32_e32 v64, 32, v78
	v_ashrrev_i32_e32 v65, 31, v64
	v_lshlrev_b64 v[64:65], 12, v[64:65]
	v_lshl_add_u64 v[64:65], v[76:77], 0, v[64:65]
	global_store_dwordx4 v[64:65], v[68:71], off sc1
	v_add_u32_e32 v64, 40, v78
	v_ashrrev_i32_e32 v65, 31, v64
	v_lshlrev_b64 v[64:65], 12, v[64:65]
	v_lshl_add_u64 v[64:65], v[76:77], 0, v[64:65]
	s_waitcnt lgkmcnt(0)
	global_store_dwordx4 v[64:65], v[72:75], off sc1
	v_add_u32_e32 v64, 48, v82
	v_lshlrev_b32_e32 v65, 7, v64
	v_lshrrev_b32_e32 v64, 2, v64
	v_add_u32_e32 v68, 48, v78
	v_xor_b32_e32 v64, v64, v163
	v_ashrrev_i32_e32 v69, 31, v68
	v_lshlrev_b32_e32 v64, 4, v64
	v_lshlrev_b64 v[68:69], 12, v[68:69]
	v_and_b32_e32 v64, 0x70, v64
	v_lshl_add_u64 v[72:73], v[76:77], 0, v[68:69]
	v_add_u32_e32 v68, 56, v82
	v_add3_u32 v64, s25, v65, v64
	v_lshlrev_b32_e32 v69, 7, v68
	v_lshrrev_b32_e32 v68, 2, v68
	ds_read_b128 v[64:67], v64
	v_xor_b32_e32 v68, v68, v163
	v_lshlrev_b32_e32 v68, 4, v68
	v_and_b32_e32 v68, 0x70, v68
	v_add3_u32 v68, s25, v69, v68
	ds_read_b128 v[68:71], v68
	s_waitcnt lgkmcnt(1)
	global_store_dwordx4 v[72:73], v[64:67], off sc1
	s_nop 1
	v_add_u32_e32 v64, 56, v78
	v_ashrrev_i32_e32 v65, 31, v64
	v_lshlrev_b64 v[64:65], 12, v[64:65]
	v_lshl_add_u64 v[64:65], v[76:77], 0, v[64:65]
	s_waitcnt lgkmcnt(0)
	global_store_dwordx4 v[64:65], v[68:71], off sc1
	s_waitcnt lgkmcnt(0)
	s_cbranch_vccnz .LBB0_280
	v_mov_b32_e32 v82, v166
	v_cvt_pk_bf16_f32 v66, v4, v0
	s_ashr_i32 s0, s46, 31
	v_lshlrev_b32_e32 v64, 9, v82
	v_ashrrev_i32_e32 v65, 2, v82
	v_and_b32_e32 v64, 0x1e00, v64
	v_and_b32_e32 v65, -4, v65
	v_add3_u32 v64, s25, v64, v65
	v_lshlrev_b32_e32 v65, 4, v82
	v_and_b32_e32 v128, 0x70, v65
	v_add_u32_e32 v65, v64, v128
	ds_write_b32 v65, v66
	v_cvt_pk_bf16_f32 v66, v5, v1
	ds_write_b32 v65, v66 offset:128
	v_cvt_pk_bf16_f32 v66, v6, v2
	ds_write_b32 v65, v66 offset:256
	v_cvt_pk_bf16_f32 v66, v7, v3
	ds_write_b32 v65, v66 offset:384
	v_xad_u32 v65, v128, 16, v64
	v_cvt_pk_bf16_f32 v66, v12, v8
	ds_write_b32 v65, v66
	v_cvt_pk_bf16_f32 v66, v13, v9
	ds_write_b32 v65, v66 offset:128
	v_cvt_pk_bf16_f32 v66, v14, v10
	ds_write_b32 v65, v66 offset:256
	v_cvt_pk_bf16_f32 v66, v15, v11
	ds_write_b32 v65, v66 offset:384
	v_xad_u32 v65, v128, 32, v64
	v_cvt_pk_bf16_f32 v66, v20, v16
	ds_write_b32 v65, v66
	v_cvt_pk_bf16_f32 v66, v21, v17
	ds_write_b32 v65, v66 offset:128
	v_cvt_pk_bf16_f32 v66, v22, v18
	ds_write_b32 v65, v66 offset:256
	v_cvt_pk_bf16_f32 v66, v23, v19
	ds_write_b32 v65, v66 offset:384
	v_xad_u32 v65, v128, 48, v64
	v_cvt_pk_bf16_f32 v66, v28, v24
	ds_write_b32 v65, v66
	v_cvt_pk_bf16_f32 v66, v29, v25
	ds_write_b32 v65, v66 offset:128
	v_cvt_pk_bf16_f32 v66, v30, v26
	ds_write_b32 v65, v66 offset:256
	v_cvt_pk_bf16_f32 v66, v31, v27
	ds_write_b32 v65, v66 offset:384
	v_xad_u32 v65, v128, 64, v64
	v_cvt_pk_bf16_f32 v66, v36, v32
	ds_write_b32 v65, v66
	v_cvt_pk_bf16_f32 v66, v37, v33
	ds_write_b32 v65, v66 offset:128
	v_cvt_pk_bf16_f32 v66, v38, v34
	ds_write_b32 v65, v66 offset:256
	v_cvt_pk_bf16_f32 v66, v39, v35
	ds_write_b32 v65, v66 offset:384
	v_xad_u32 v65, v128, s23, v64
	v_cvt_pk_bf16_f32 v66, v44, v40
	ds_write_b32 v65, v66
	v_cvt_pk_bf16_f32 v66, v45, v41
	ds_write_b32 v65, v66 offset:128
	v_cvt_pk_bf16_f32 v66, v46, v42
	ds_write_b32 v65, v66 offset:256
	v_cvt_pk_bf16_f32 v66, v47, v43
	ds_write_b32 v65, v66 offset:384
	v_xad_u32 v65, v128, s44, v64
	v_cvt_pk_bf16_f32 v66, v52, v48
	ds_write_b32 v65, v66
	v_cvt_pk_bf16_f32 v66, v53, v49
	ds_write_b32 v65, v66 offset:128
	v_cvt_pk_bf16_f32 v66, v54, v50
	ds_write_b32 v65, v66 offset:256
	v_cvt_pk_bf16_f32 v66, v55, v51
	ds_write_b32 v65, v66 offset:384
	v_xad_u32 v64, v128, s22, v64
	v_cvt_pk_bf16_f32 v65, v60, v56
	s_lshr_b32 s0, s0, 25
	ds_write_b32 v64, v65
	v_cvt_pk_bf16_f32 v65, v61, v57
	s_add_i32 s46, s46, s0
	ds_write_b32 v64, v65 offset:128
	v_cvt_pk_bf16_f32 v65, v62, v58
	s_ashr_i32 s1, s46, 7
	ds_write_b32 v64, v65 offset:256
	v_cvt_pk_bf16_f32 v65, v63, v59
	v_ashrrev_i32_e32 v83, 3, v82
	s_lshl_b32 s0, s1, 6
	ds_write_b32 v64, v65 offset:384
	v_lshrrev_b32_e32 v65, 2, v83
	s_lshl_b32 s4, s1, 13
	s_ashr_i32 s1, s0, 31
	v_xor_b32_e32 v65, v65, v82
	s_lshl_b64 s[0:1], s[0:1], 1
	v_lshlrev_b32_e32 v65, 4, v65
	s_waitcnt lgkmcnt(0)
	s_add_u32 s0, s68, s0
	v_lshlrev_b32_e32 v64, 7, v83
	v_and_b32_e32 v65, 0x70, v65
	s_addc_u32 s1, s69, s1
	v_add3_u32 v70, s25, v64, v65
	v_lshl_add_u64 v[76:77], s[0:1], 0, v[128:129]
	ds_read_b128 v[64:67], v70
	v_subrev_u32_e32 v68, s4, v83
	s_add_i32 s0, s15, s16
	v_add_u32_e32 v78, s0, v68
	v_ashrrev_i32_e32 v79, 31, v78
	v_lshlrev_b64 v[68:69], 12, v[78:79]
	v_lshl_add_u64 v[72:73], v[76:77], 0, v[68:69]
	s_waitcnt lgkmcnt(0)
	global_store_dwordx4 v[72:73], v[64:67], off sc1
	v_add_u32_e32 v72, 8, v78
	v_ashrrev_i32_e32 v73, 31, v72
	v_add_u32_e32 v64, 8, v83
	v_lshlrev_b32_e32 v65, 7, v64
	v_lshrrev_b32_e32 v64, 2, v64
	v_xor_b32_e32 v64, v64, v82
	v_lshlrev_b32_e32 v64, 4, v64
	v_lshlrev_b64 v[72:73], 12, v[72:73]
	v_and_b32_e32 v64, 0x70, v64
	v_lshl_add_u64 v[80:81], v[76:77], 0, v[72:73]
	v_add_u32_e32 v72, 16, v83
	v_add3_u32 v64, s25, v65, v64
	v_lshlrev_b32_e32 v73, 7, v72
	v_lshrrev_b32_e32 v72, 2, v72
	ds_read_b128 v[68:71], v70 offset:4096
	ds_read_b128 v[64:67], v64
	v_xor_b32_e32 v72, v72, v82
	v_lshlrev_b32_e32 v72, 4, v72
	v_and_b32_e32 v72, 0x70, v72
	v_add3_u32 v72, s25, v73, v72
	ds_read_b128 v[72:75], v72
	s_waitcnt lgkmcnt(1)
	global_store_dwordx4 v[80:81], v[64:67], off sc1
	s_nop 1
	v_add_u32_e32 v64, 16, v78
	v_ashrrev_i32_e32 v65, 31, v64
	v_lshlrev_b64 v[64:65], 12, v[64:65]
	v_lshl_add_u64 v[64:65], v[76:77], 0, v[64:65]
	s_waitcnt lgkmcnt(0)
	global_store_dwordx4 v[64:65], v[72:75], off sc1
	v_add_u32_e32 v64, 24, v83
	v_lshlrev_b32_e32 v65, 7, v64
	v_lshrrev_b32_e32 v64, 2, v64
	v_xor_b32_e32 v64, v64, v82
	v_add_u32_e32 v72, 24, v78
	v_lshlrev_b32_e32 v64, 4, v64
	v_ashrrev_i32_e32 v73, 31, v72
	v_and_b32_e32 v64, 0x70, v64
	v_lshlrev_b64 v[72:73], 12, v[72:73]
	v_add3_u32 v64, s25, v65, v64
	v_lshl_add_u64 v[80:81], v[76:77], 0, v[72:73]
	v_add_u32_e32 v72, 40, v83
	ds_read_b128 v[64:67], v64
	v_lshlrev_b32_e32 v73, 7, v72
	v_lshrrev_b32_e32 v72, 2, v72
	v_xor_b32_e32 v72, v72, v82
	v_lshlrev_b32_e32 v72, 4, v72
	v_and_b32_e32 v72, 0x70, v72
	v_add3_u32 v72, s25, v73, v72
	ds_read_b128 v[72:75], v72
	s_waitcnt lgkmcnt(1)
	global_store_dwordx4 v[80:81], v[64:67], off sc1
	s_nop 1
	v_add_u32_e32 v64, 32, v78
	v_ashrrev_i32_e32 v65, 31, v64
	v_lshlrev_b64 v[64:65], 12, v[64:65]
	v_lshl_add_u64 v[64:65], v[76:77], 0, v[64:65]
	global_store_dwordx4 v[64:65], v[68:71], off sc1
	v_add_u32_e32 v64, 40, v78
	v_ashrrev_i32_e32 v65, 31, v64
	v_lshlrev_b64 v[64:65], 12, v[64:65]
	v_lshl_add_u64 v[64:65], v[76:77], 0, v[64:65]
	s_waitcnt lgkmcnt(0)
	global_store_dwordx4 v[64:65], v[72:75], off sc1
	v_add_u32_e32 v64, 48, v83
	v_lshlrev_b32_e32 v65, 7, v64
	v_lshrrev_b32_e32 v64, 2, v64
	v_add_u32_e32 v68, 48, v78
	v_xor_b32_e32 v64, v64, v82
	v_ashrrev_i32_e32 v69, 31, v68
	v_lshlrev_b32_e32 v64, 4, v64
	v_lshlrev_b64 v[68:69], 12, v[68:69]
	v_and_b32_e32 v64, 0x70, v64
	v_lshl_add_u64 v[72:73], v[76:77], 0, v[68:69]
	v_add_u32_e32 v68, 56, v83
	v_add3_u32 v64, s25, v65, v64
	v_lshlrev_b32_e32 v69, 7, v68
	v_lshrrev_b32_e32 v68, 2, v68
	ds_read_b128 v[64:67], v64
	v_xor_b32_e32 v68, v68, v82
	v_lshlrev_b32_e32 v68, 4, v68
	v_and_b32_e32 v68, 0x70, v68
	v_add3_u32 v68, s25, v69, v68
	ds_read_b128 v[68:71], v68
	s_waitcnt lgkmcnt(1)
	global_store_dwordx4 v[72:73], v[64:67], off sc1
	s_nop 1
	v_add_u32_e32 v64, 56, v78
	v_ashrrev_i32_e32 v65, 31, v64
	v_lshlrev_b64 v[64:65], 12, v[64:65]
	v_lshl_add_u64 v[64:65], v[76:77], 0, v[64:65]
	s_waitcnt lgkmcnt(0)
	global_store_dwordx4 v[64:65], v[68:71], off sc1
	s_waitcnt lgkmcnt(0)
	s_branch .LBB0_280

.LBB0_313:
	s_lshl_b32 s21, s12, 1
	s_lshl_b32 s12, s12, 9
	s_and_b32 s47, s12, 0xfffff800
	s_lshl_b32 s12, s56, 8
	v_mov_b32_e32 v136, v139
	v_mov_b32_e32 v145, v138
	s_and_b32 s12, s12, 0x100
	s_add_i32 s12, s12, s77
	s_and_b32 s21, s21, 6
	v_add_lshl_u32 v145, s12, v145, 1
	s_lshr_b32 s50, s56, 1
	s_or_b32 s13, s21, s13
	v_or_b32_e32 v146, s50, v145
	s_lshl_b32 s13, s13, 7
	v_cvt_pk_bf16_f32 v124, v124, v125
	v_cvt_pk_bf16_f32 v125, v126, v127
	v_cvt_pk_bf16_f32 v126, v120, v121
	v_add_u32_e32 v120, s47, v146
	s_or_b32 s13, s13, s20
	v_ashrrev_i32_e32 v121, 31, v120
	v_lshl_add_u32 v136, v136, 3, s13
	v_lshlrev_b64 v[120:121], 12, v[120:121]
	v_ashrrev_i32_e32 v137, 31, v136
	v_lshl_add_u64 v[120:121], s[48:49], 0, v[120:121]
	s_add_i32 s46, s47, 0x800
	v_lshl_add_u64 v[120:121], v[136:137], 1, v[120:121]
	v_cmp_ne_u32_e32 vcc, 0, v146
	v_cvt_pk_bf16_f32 v127, v122, v123
	global_store_dwordx4 v[120:121], v[124:127], off sc1
	s_and_saveexec_b64 s[12:13], vcc
	s_cbranch_execz .LBB0_315
	v_cvt_pk_bf16_f32 v116, v116, v117
	v_cvt_pk_bf16_f32 v117, v118, v119
	v_cvt_pk_bf16_f32 v118, v112, v113
	v_sub_u32_e32 v112, s46, v146
	v_ashrrev_i32_e32 v113, 31, v112
	v_lshlrev_b64 v[112:113], 12, v[112:113]
	v_lshl_add_u64 v[112:113], s[48:49], 0, v[112:113]
	v_lshl_add_u64 v[112:113], v[136:137], 1, v[112:113]
	v_cvt_pk_bf16_f32 v119, v114, v115
	global_store_dwordx4 v[112:113], v[116:119], off sc1
.LBB0_315:
	s_or_b64 exec, exec, s[12:13]
	v_add3_u32 v112, v145, s50, 32
	v_cvt_pk_bf16_f32 v108, v108, v109
	v_cvt_pk_bf16_f32 v109, v110, v111
	v_cvt_pk_bf16_f32 v110, v104, v105
	v_add_u32_e32 v104, s47, v112
	v_ashrrev_i32_e32 v105, 31, v104
	v_lshlrev_b64 v[104:105], 12, v[104:105]
	v_lshl_add_u64 v[104:105], s[48:49], 0, v[104:105]
	v_lshl_add_u64 v[104:105], v[136:137], 1, v[104:105]
	v_cmp_ne_u32_e32 vcc, 0, v112
	v_cvt_pk_bf16_f32 v111, v106, v107
	global_store_dwordx4 v[104:105], v[108:111], off sc1
	s_and_saveexec_b64 s[12:13], vcc
	s_cbranch_execz .LBB0_317
	v_cvt_pk_bf16_f32 v100, v100, v101
	v_cvt_pk_bf16_f32 v101, v102, v103
	v_cvt_pk_bf16_f32 v102, v96, v97
	v_sub_u32_e32 v96, s46, v112
	v_ashrrev_i32_e32 v97, 31, v96
	v_lshlrev_b64 v[96:97], 12, v[96:97]
	v_lshl_add_u64 v[96:97], s[48:49], 0, v[96:97]
	v_lshl_add_u64 v[96:97], v[136:137], 1, v[96:97]
	v_cvt_pk_bf16_f32 v103, v98, v99
	global_store_dwordx4 v[96:97], v[100:103], off sc1
.LBB0_317:
	s_or_b64 exec, exec, s[12:13]
	v_add3_u32 v96, v145, s50, 64
	v_cvt_pk_bf16_f32 v92, v92, v93
	v_cvt_pk_bf16_f32 v93, v94, v95
	v_cvt_pk_bf16_f32 v94, v88, v89
	v_add_u32_e32 v88, s47, v96
	v_ashrrev_i32_e32 v89, 31, v88
	v_lshlrev_b64 v[88:89], 12, v[88:89]
	v_lshl_add_u64 v[88:89], s[48:49], 0, v[88:89]
	v_lshl_add_u64 v[88:89], v[136:137], 1, v[88:89]
	v_cmp_ne_u32_e32 vcc, 0, v96
	v_cvt_pk_bf16_f32 v95, v90, v91
	global_store_dwordx4 v[88:89], v[92:95], off sc1
	s_and_saveexec_b64 s[12:13], vcc
	s_cbranch_execz .LBB0_319
	v_cvt_pk_bf16_f32 v84, v84, v85
	v_cvt_pk_bf16_f32 v85, v86, v87
	v_cvt_pk_bf16_f32 v86, v80, v81
	v_sub_u32_e32 v80, s46, v96
	v_ashrrev_i32_e32 v81, 31, v80
	v_lshlrev_b64 v[80:81], 12, v[80:81]
	v_lshl_add_u64 v[80:81], s[48:49], 0, v[80:81]
	v_lshl_add_u64 v[80:81], v[136:137], 1, v[80:81]
	v_cvt_pk_bf16_f32 v87, v82, v83
	global_store_dwordx4 v[80:81], v[84:87], off sc1
.LBB0_319:
	s_or_b64 exec, exec, s[12:13]
	v_add_u32_e32 v80, s50, v145
	v_add_u32_e32 v81, 0x60, v80
	v_cvt_pk_bf16_f32 v72, v72, v73
	v_cvt_pk_bf16_f32 v73, v74, v75
	v_cvt_pk_bf16_f32 v74, v64, v65
	v_add_u32_e32 v64, s47, v81
	v_ashrrev_i32_e32 v65, 31, v64
	v_lshlrev_b64 v[64:65], 12, v[64:65]
	v_lshl_add_u64 v[64:65], s[48:49], 0, v[64:65]
	v_lshl_add_u64 v[64:65], v[136:137], 1, v[64:65]
	v_cmp_ne_u32_e32 vcc, 0, v81
	v_cvt_pk_bf16_f32 v75, v66, v67
	global_store_dwordx4 v[64:65], v[72:75], off sc1
	s_and_saveexec_b64 s[12:13], vcc
	s_cbranch_execz .LBB0_321
	v_cvt_pk_bf16_f32 v56, v56, v57
	v_cvt_pk_bf16_f32 v57, v58, v59
	v_cvt_pk_bf16_f32 v58, v48, v49
	v_sub_u32_e32 v48, s46, v81
	v_ashrrev_i32_e32 v49, 31, v48
	v_lshlrev_b64 v[48:49], 12, v[48:49]
	v_lshl_add_u64 v[48:49], s[48:49], 0, v[48:49]
	v_lshl_add_u64 v[48:49], v[136:137], 1, v[48:49]
	v_cvt_pk_bf16_f32 v59, v50, v51
	global_store_dwordx4 v[48:49], v[56:59], off sc1
.LBB0_321:
	s_or_b64 exec, exec, s[12:13]
	v_add_u32_e32 v48, 0x100, v80
	v_add_u32_e32 v50, s47, v48
	v_ashrrev_i32_e32 v51, 31, v50
	v_lshlrev_b64 v[50:51], 12, v[50:51]
	v_lshl_add_u64 v[50:51], s[48:49], 0, v[50:51]
	v_lshl_add_u64 v[50:51], v[136:137], 1, v[50:51]
	v_cmp_ne_u32_e32 vcc, 0, v48
	v_cvt_pk_bf16_f32 v56, v76, v77
	v_cvt_pk_bf16_f32 v57, v78, v79
	v_cvt_pk_bf16_f32 v58, v68, v69
	v_cvt_pk_bf16_f32 v59, v70, v71
	global_store_dwordx4 v[50:51], v[56:59], off sc1
	s_and_saveexec_b64 s[12:13], vcc
	s_cbranch_execz .LBB0_323
	v_sub_u32_e32 v48, s46, v48
	v_ashrrev_i32_e32 v49, 31, v48
	v_lshlrev_b64 v[48:49], 12, v[48:49]
	v_lshl_add_u64 v[48:49], s[48:49], 0, v[48:49]
	v_lshl_add_u64 v[48:49], v[136:137], 1, v[48:49]
	v_cvt_pk_bf16_f32 v50, v60, v61
	v_cvt_pk_bf16_f32 v51, v62, v63
	v_cvt_pk_bf16_f32 v52, v52, v53
	v_cvt_pk_bf16_f32 v53, v54, v55
	global_store_dwordx4 v[48:49], v[50:53], off sc1
.LBB0_323:
	s_or_b64 exec, exec, s[12:13]
	v_add_u32_e32 v48, 0x120, v80
	v_cvt_pk_bf16_f32 v44, v44, v45
	v_cvt_pk_bf16_f32 v45, v46, v47
	v_cvt_pk_bf16_f32 v46, v40, v41
	v_add_u32_e32 v40, s47, v48
	v_ashrrev_i32_e32 v41, 31, v40
	v_lshlrev_b64 v[40:41], 12, v[40:41]
	v_lshl_add_u64 v[40:41], s[48:49], 0, v[40:41]
	v_lshl_add_u64 v[40:41], v[136:137], 1, v[40:41]
	v_cmp_ne_u32_e32 vcc, 0, v48
	v_cvt_pk_bf16_f32 v47, v42, v43
	global_store_dwordx4 v[40:41], v[44:47], off sc1
	s_and_saveexec_b64 s[12:13], vcc
	s_cbranch_execz .LBB0_325
	v_cvt_pk_bf16_f32 v36, v36, v37
	v_cvt_pk_bf16_f32 v37, v38, v39
	v_cvt_pk_bf16_f32 v38, v32, v33
	v_sub_u32_e32 v32, s46, v48
	v_ashrrev_i32_e32 v33, 31, v32
	v_lshlrev_b64 v[32:33], 12, v[32:33]
	v_lshl_add_u64 v[32:33], s[48:49], 0, v[32:33]
	v_lshl_add_u64 v[32:33], v[136:137], 1, v[32:33]
	v_cvt_pk_bf16_f32 v39, v34, v35
	global_store_dwordx4 v[32:33], v[36:39], off sc1
.LBB0_325:
	s_or_b64 exec, exec, s[12:13]
	v_add_u32_e32 v32, 0x140, v80
	v_cvt_pk_bf16_f32 v28, v28, v29
	v_cvt_pk_bf16_f32 v29, v30, v31
	v_cvt_pk_bf16_f32 v30, v24, v25
	v_add_u32_e32 v24, s47, v32
	v_ashrrev_i32_e32 v25, 31, v24
	v_lshlrev_b64 v[24:25], 12, v[24:25]
	v_lshl_add_u64 v[24:25], s[48:49], 0, v[24:25]
	v_lshl_add_u64 v[24:25], v[136:137], 1, v[24:25]
	v_cmp_ne_u32_e32 vcc, 0, v32
	v_cvt_pk_bf16_f32 v31, v26, v27
	global_store_dwordx4 v[24:25], v[28:31], off sc1
	s_and_saveexec_b64 s[12:13], vcc
	s_cbranch_execz .LBB0_327
	v_cvt_pk_bf16_f32 v20, v20, v21
	v_cvt_pk_bf16_f32 v21, v22, v23
	v_cvt_pk_bf16_f32 v22, v16, v17
	v_sub_u32_e32 v16, s46, v32
	v_ashrrev_i32_e32 v17, 31, v16
	v_lshlrev_b64 v[16:17], 12, v[16:17]
	v_lshl_add_u64 v[16:17], s[48:49], 0, v[16:17]
	v_lshl_add_u64 v[16:17], v[136:137], 1, v[16:17]
	v_cvt_pk_bf16_f32 v23, v18, v19
	global_store_dwordx4 v[16:17], v[20:23], off sc1
.LBB0_327:
	s_or_b64 exec, exec, s[12:13]
	v_add_u32_e32 v16, 0x160, v80
	v_cvt_pk_bf16_f32 v12, v12, v13
	v_cvt_pk_bf16_f32 v13, v14, v15
	v_cvt_pk_bf16_f32 v14, v8, v9
	v_add_u32_e32 v8, s47, v16
	v_ashrrev_i32_e32 v9, 31, v8
	v_lshlrev_b64 v[8:9], 12, v[8:9]
	v_lshl_add_u64 v[8:9], s[48:49], 0, v[8:9]
	v_lshl_add_u64 v[8:9], v[136:137], 1, v[8:9]
	v_cmp_ne_u32_e32 vcc, 0, v16
	v_cvt_pk_bf16_f32 v15, v10, v11
	global_store_dwordx4 v[8:9], v[12:15], off sc1
	s_and_saveexec_b64 s[12:13], vcc
	s_cbranch_execz .LBB0_329
	v_cvt_pk_bf16_f32 v4, v4, v5
	v_cvt_pk_bf16_f32 v5, v6, v7
	v_cvt_pk_bf16_f32 v6, v0, v1
	v_sub_u32_e32 v0, s46, v16
	v_ashrrev_i32_e32 v1, 31, v0
	v_lshlrev_b64 v[0:1], 12, v[0:1]
	v_lshl_add_u64 v[0:1], s[48:49], 0, v[0:1]
	v_lshl_add_u64 v[0:1], v[136:137], 1, v[0:1]
	v_cvt_pk_bf16_f32 v7, v2, v3
	global_store_dwordx4 v[0:1], v[4:7], off sc1

.LBB0_338:
	v_mov_b32_e32 v163, v166
	s_waitcnt vmcnt(0)
	v_cvt_pk_bf16_f32 v120, v120, v124
	s_lshl_b64 s[4:5], s[4:5], 1
	v_lshlrev_b32_e32 v128, 9, v163
	v_ashrrev_i32_e32 v167, 2, v163
	v_and_b32_e32 v128, 0x1e00, v128
	v_and_b32_e32 v167, -4, v167
	v_add3_u32 v167, s25, v128, v167
	v_lshlrev_b32_e32 v128, 4, v163
	v_and_b32_e32 v128, 0x70, v128
	v_add_u32_e32 v168, v167, v128
	ds_write_b32 v168, v120
	v_cvt_pk_bf16_f32 v120, v121, v125
	ds_write_b32 v168, v120 offset:128
	v_cvt_pk_bf16_f32 v120, v122, v126
	ds_write_b32 v168, v120 offset:256
	v_cvt_pk_bf16_f32 v120, v123, v127
	ds_write_b32 v168, v120 offset:384
	v_xad_u32 v120, v128, 16, v167
	v_cvt_pk_bf16_f32 v112, v112, v116
	ds_write_b32 v120, v112
	v_cvt_pk_bf16_f32 v112, v113, v117
	ds_write_b32 v120, v112 offset:128
	v_cvt_pk_bf16_f32 v112, v114, v118
	ds_write_b32 v120, v112 offset:256
	v_cvt_pk_bf16_f32 v112, v115, v119
	ds_write_b32 v120, v112 offset:384
	v_xad_u32 v112, v128, 32, v167
	v_cvt_pk_bf16_f32 v104, v104, v108
	ds_write_b32 v112, v104
	v_cvt_pk_bf16_f32 v104, v105, v109
	ds_write_b32 v112, v104 offset:128
	v_cvt_pk_bf16_f32 v104, v106, v110
	ds_write_b32 v112, v104 offset:256
	v_cvt_pk_bf16_f32 v104, v107, v111
	ds_write_b32 v112, v104 offset:384
	v_xad_u32 v104, v128, 48, v167
	v_cvt_pk_bf16_f32 v96, v96, v100
	ds_write_b32 v104, v96
	v_cvt_pk_bf16_f32 v96, v97, v101
	ds_write_b32 v104, v96 offset:128
	v_cvt_pk_bf16_f32 v96, v98, v102
	ds_write_b32 v104, v96 offset:256
	v_cvt_pk_bf16_f32 v96, v99, v103
	ds_write_b32 v104, v96 offset:384
	v_xad_u32 v96, v128, 64, v167
	v_cvt_pk_bf16_f32 v88, v88, v92
	ds_write_b32 v96, v88
	v_cvt_pk_bf16_f32 v88, v89, v93
	ds_write_b32 v96, v88 offset:128
	v_cvt_pk_bf16_f32 v88, v90, v94
	ds_write_b32 v96, v88 offset:256
	v_cvt_pk_bf16_f32 v88, v91, v95
	ds_write_b32 v96, v88 offset:384
	v_xad_u32 v88, v128, s14, v167
	v_cvt_pk_bf16_f32 v80, v80, v84
	ds_write_b32 v88, v80
	v_cvt_pk_bf16_f32 v80, v81, v85
	ds_write_b32 v88, v80 offset:128
	v_cvt_pk_bf16_f32 v80, v82, v86
	ds_write_b32 v88, v80 offset:256
	v_cvt_pk_bf16_f32 v80, v83, v87
	ds_write_b32 v88, v80 offset:384
	v_xad_u32 v80, v128, s15, v167
	v_cvt_pk_bf16_f32 v72, v72, v76
	ds_write_b32 v80, v72
	v_cvt_pk_bf16_f32 v72, v73, v77
	ds_write_b32 v80, v72 offset:128
	v_cvt_pk_bf16_f32 v72, v74, v78
	ds_write_b32 v80, v72 offset:256
	v_cvt_pk_bf16_f32 v72, v75, v79
	ds_write_b32 v80, v72 offset:384
	v_xad_u32 v72, v128, s13, v167
	v_cvt_pk_bf16_f32 v64, v64, v68
	v_ashrrev_i32_e32 v82, 3, v163
	ds_write_b32 v72, v64
	v_cvt_pk_bf16_f32 v64, v65, v69
	v_lshrrev_b32_e32 v65, 2, v82
	ds_write_b32 v72, v64 offset:128
	v_cvt_pk_bf16_f32 v64, v66, v70
	v_xor_b32_e32 v65, v65, v163
	ds_write_b32 v72, v64 offset:256
	v_cvt_pk_bf16_f32 v64, v67, v71
	ds_write_b32 v72, v64 offset:384
	v_lshlrev_b32_e32 v65, 4, v65
	s_waitcnt lgkmcnt(0)
	v_lshlrev_b32_e32 v64, 7, v82
	v_and_b32_e32 v65, 0x70, v65
	v_add3_u32 v70, s25, v64, v65
	ds_read_b128 v[64:67], v70
	v_subrev_u32_e32 v68, s17, v82
	s_add_u32 s4, s72, s4
	v_add_u32_e32 v78, s11, v68
	s_addc_u32 s5, s73, s5
	v_ashrrev_i32_e32 v79, 31, v78
	v_lshl_add_u64 v[76:77], s[4:5], 0, v[128:129]
	v_lshlrev_b64 v[68:69], 14, v[78:79]
	v_lshl_add_u64 v[72:73], v[76:77], 0, v[68:69]
	s_waitcnt lgkmcnt(0)
	global_store_dwordx4 v[72:73], v[64:67], off sc1
	v_add_u32_e32 v72, 8, v78
	v_ashrrev_i32_e32 v73, 31, v72
	v_add_u32_e32 v64, 8, v82
	v_lshlrev_b32_e32 v65, 7, v64
	v_lshrrev_b32_e32 v64, 2, v64
	v_xor_b32_e32 v64, v64, v163
	v_lshlrev_b32_e32 v64, 4, v64
	v_lshlrev_b64 v[72:73], 14, v[72:73]
	v_and_b32_e32 v64, 0x70, v64
	v_lshl_add_u64 v[80:81], v[76:77], 0, v[72:73]
	v_add_u32_e32 v72, 16, v82
	v_add3_u32 v64, s25, v65, v64
	v_lshlrev_b32_e32 v73, 7, v72
	v_lshrrev_b32_e32 v72, 2, v72
	ds_read_b128 v[68:71], v70 offset:4096
	ds_read_b128 v[64:67], v64
	v_xor_b32_e32 v72, v72, v163
	v_lshlrev_b32_e32 v72, 4, v72
	v_and_b32_e32 v72, 0x70, v72
	v_add3_u32 v72, s25, v73, v72
	ds_read_b128 v[72:75], v72
	s_waitcnt lgkmcnt(1)
	global_store_dwordx4 v[80:81], v[64:67], off sc1
	s_andn2_b64 vcc, exec, s[0:1]
	s_nop 0
	v_add_u32_e32 v64, 16, v78
	v_ashrrev_i32_e32 v65, 31, v64
	v_lshlrev_b64 v[64:65], 14, v[64:65]
	v_lshl_add_u64 v[64:65], v[76:77], 0, v[64:65]
	s_waitcnt lgkmcnt(0)
	global_store_dwordx4 v[64:65], v[72:75], off sc1
	v_add_u32_e32 v64, 24, v82
	v_lshlrev_b32_e32 v65, 7, v64
	v_lshrrev_b32_e32 v64, 2, v64
	v_xor_b32_e32 v64, v64, v163
	v_add_u32_e32 v72, 24, v78
	v_lshlrev_b32_e32 v64, 4, v64
	v_ashrrev_i32_e32 v73, 31, v72
	v_and_b32_e32 v64, 0x70, v64
	v_lshlrev_b64 v[72:73], 14, v[72:73]
	v_add3_u32 v64, s25, v65, v64
	v_lshl_add_u64 v[80:81], v[76:77], 0, v[72:73]
	v_add_u32_e32 v72, 40, v82
	ds_read_b128 v[64:67], v64
	v_lshlrev_b32_e32 v73, 7, v72
	v_lshrrev_b32_e32 v72, 2, v72
	v_xor_b32_e32 v72, v72, v163
	v_lshlrev_b32_e32 v72, 4, v72
	v_and_b32_e32 v72, 0x70, v72
	v_add3_u32 v72, s25, v73, v72
	ds_read_b128 v[72:75], v72
	s_waitcnt lgkmcnt(1)
	global_store_dwordx4 v[80:81], v[64:67], off sc1
	s_nop 1
	v_add_u32_e32 v64, 32, v78
	v_ashrrev_i32_e32 v65, 31, v64
	v_lshlrev_b64 v[64:65], 14, v[64:65]
	v_lshl_add_u64 v[64:65], v[76:77], 0, v[64:65]
	global_store_dwordx4 v[64:65], v[68:71], off sc1
	v_add_u32_e32 v64, 40, v78
	v_ashrrev_i32_e32 v65, 31, v64
	v_lshlrev_b64 v[64:65], 14, v[64:65]
	v_lshl_add_u64 v[64:65], v[76:77], 0, v[64:65]
	s_waitcnt lgkmcnt(0)
	global_store_dwordx4 v[64:65], v[72:75], off sc1
	v_add_u32_e32 v64, 48, v82
	v_lshlrev_b32_e32 v65, 7, v64
	v_lshrrev_b32_e32 v64, 2, v64
	v_add_u32_e32 v68, 48, v78
	v_xor_b32_e32 v64, v64, v163
	v_ashrrev_i32_e32 v69, 31, v68
	v_lshlrev_b32_e32 v64, 4, v64
	v_lshlrev_b64 v[68:69], 14, v[68:69]
	v_and_b32_e32 v64, 0x70, v64
	v_lshl_add_u64 v[72:73], v[76:77], 0, v[68:69]
	v_add_u32_e32 v68, 56, v82
	v_add3_u32 v64, s25, v65, v64
	v_lshlrev_b32_e32 v69, 7, v68
	v_lshrrev_b32_e32 v68, 2, v68
	ds_read_b128 v[64:67], v64
	v_xor_b32_e32 v68, v68, v163
	v_lshlrev_b32_e32 v68, 4, v68
	v_and_b32_e32 v68, 0x70, v68
	v_add3_u32 v68, s25, v69, v68
	ds_read_b128 v[68:71], v68
	s_waitcnt lgkmcnt(1)
	global_store_dwordx4 v[72:73], v[64:67], off sc1
	s_nop 1
	v_add_u32_e32 v64, 56, v78
	v_ashrrev_i32_e32 v65, 31, v64
	v_lshlrev_b64 v[64:65], 14, v[64:65]
	v_lshl_add_u64 v[64:65], v[76:77], 0, v[64:65]
	s_waitcnt lgkmcnt(0)
	global_store_dwordx4 v[64:65], v[68:71], off sc1
	s_waitcnt lgkmcnt(0)
	s_cbranch_vccnz .LBB0_335
	v_mov_b32_e32 v82, v166
	v_cvt_pk_bf16_f32 v66, v4, v0
	s_ashr_i32 s0, s16, 31
	v_lshlrev_b32_e32 v64, 9, v82
	v_ashrrev_i32_e32 v65, 2, v82
	v_and_b32_e32 v64, 0x1e00, v64
	v_and_b32_e32 v65, -4, v65
	v_add3_u32 v64, s25, v64, v65
	v_lshlrev_b32_e32 v65, 4, v82
	v_and_b32_e32 v128, 0x70, v65
	v_add_u32_e32 v65, v64, v128
	ds_write_b32 v65, v66
	v_cvt_pk_bf16_f32 v66, v5, v1
	ds_write_b32 v65, v66 offset:128
	v_cvt_pk_bf16_f32 v66, v6, v2
	ds_write_b32 v65, v66 offset:256
	v_cvt_pk_bf16_f32 v66, v7, v3
	ds_write_b32 v65, v66 offset:384
	v_xad_u32 v65, v128, 16, v64
	v_cvt_pk_bf16_f32 v66, v12, v8
	ds_write_b32 v65, v66
	v_cvt_pk_bf16_f32 v66, v13, v9
	ds_write_b32 v65, v66 offset:128
	v_cvt_pk_bf16_f32 v66, v14, v10
	ds_write_b32 v65, v66 offset:256
	v_cvt_pk_bf16_f32 v66, v15, v11
	ds_write_b32 v65, v66 offset:384
	v_xad_u32 v65, v128, 32, v64
	v_cvt_pk_bf16_f32 v66, v20, v16
	ds_write_b32 v65, v66
	v_cvt_pk_bf16_f32 v66, v21, v17
	ds_write_b32 v65, v66 offset:128
	v_cvt_pk_bf16_f32 v66, v22, v18
	ds_write_b32 v65, v66 offset:256
	v_cvt_pk_bf16_f32 v66, v23, v19
	ds_write_b32 v65, v66 offset:384
	v_xad_u32 v65, v128, 48, v64
	v_cvt_pk_bf16_f32 v66, v28, v24
	ds_write_b32 v65, v66
	v_cvt_pk_bf16_f32 v66, v29, v25
	ds_write_b32 v65, v66 offset:128
	v_cvt_pk_bf16_f32 v66, v30, v26
	ds_write_b32 v65, v66 offset:256
	v_cvt_pk_bf16_f32 v66, v31, v27
	ds_write_b32 v65, v66 offset:384
	v_xad_u32 v65, v128, 64, v64
	v_cvt_pk_bf16_f32 v66, v36, v32
	ds_write_b32 v65, v66
	v_cvt_pk_bf16_f32 v66, v37, v33
	ds_write_b32 v65, v66 offset:128
	v_cvt_pk_bf16_f32 v66, v38, v34
	ds_write_b32 v65, v66 offset:256
	v_cvt_pk_bf16_f32 v66, v39, v35
	ds_write_b32 v65, v66 offset:384
	v_xad_u32 v65, v128, s14, v64
	v_cvt_pk_bf16_f32 v66, v44, v40
	ds_write_b32 v65, v66
	v_cvt_pk_bf16_f32 v66, v45, v41
	ds_write_b32 v65, v66 offset:128
	v_cvt_pk_bf16_f32 v66, v46, v42
	ds_write_b32 v65, v66 offset:256
	v_cvt_pk_bf16_f32 v66, v47, v43
	ds_write_b32 v65, v66 offset:384
	v_xad_u32 v65, v128, s15, v64
	v_cvt_pk_bf16_f32 v66, v52, v48
	ds_write_b32 v65, v66
	v_cvt_pk_bf16_f32 v66, v53, v49
	ds_write_b32 v65, v66 offset:128
	v_cvt_pk_bf16_f32 v66, v54, v50
	ds_write_b32 v65, v66 offset:256
	v_cvt_pk_bf16_f32 v66, v55, v51
	ds_write_b32 v65, v66 offset:384
	v_xad_u32 v64, v128, s13, v64
	v_cvt_pk_bf16_f32 v65, v60, v56
	s_lshr_b32 s0, s0, 27
	ds_write_b32 v64, v65
	v_cvt_pk_bf16_f32 v65, v61, v57
	s_add_i32 s16, s16, s0
	ds_write_b32 v64, v65 offset:128
	v_cvt_pk_bf16_f32 v65, v62, v58
	s_ashr_i32 s1, s16, 5
	ds_write_b32 v64, v65 offset:256
	v_cvt_pk_bf16_f32 v65, v63, v59
	v_ashrrev_i32_e32 v83, 3, v82
	s_lshl_b32 s0, s1, 6
	ds_write_b32 v64, v65 offset:384
	v_lshrrev_b32_e32 v65, 2, v83
	s_lshl_b32 s4, s1, 11
	s_ashr_i32 s1, s0, 31
	v_xor_b32_e32 v65, v65, v82
	s_lshl_b64 s[0:1], s[0:1], 1
	v_lshlrev_b32_e32 v65, 4, v65
	s_waitcnt lgkmcnt(0)
	s_add_u32 s0, s72, s0
	v_lshlrev_b32_e32 v64, 7, v83
	v_and_b32_e32 v65, 0x70, v65
	s_addc_u32 s1, s73, s1
	v_add3_u32 v70, s25, v64, v65
	v_lshl_add_u64 v[76:77], s[0:1], 0, v[128:129]
	ds_read_b128 v[64:67], v70
	v_subrev_u32_e32 v68, s4, v83
	s_add_i32 s0, s10, s11
	v_add_u32_e32 v78, s0, v68
	v_ashrrev_i32_e32 v79, 31, v78
	v_lshlrev_b64 v[68:69], 14, v[78:79]
	v_lshl_add_u64 v[72:73], v[76:77], 0, v[68:69]
	s_waitcnt lgkmcnt(0)
	global_store_dwordx4 v[72:73], v[64:67], off sc1
	v_add_u32_e32 v72, 8, v78
	v_ashrrev_i32_e32 v73, 31, v72
	v_add_u32_e32 v64, 8, v83
	v_lshlrev_b32_e32 v65, 7, v64
	v_lshrrev_b32_e32 v64, 2, v64
	v_xor_b32_e32 v64, v64, v82
	v_lshlrev_b32_e32 v64, 4, v64
	v_lshlrev_b64 v[72:73], 14, v[72:73]
	v_and_b32_e32 v64, 0x70, v64
	v_lshl_add_u64 v[80:81], v[76:77], 0, v[72:73]
	v_add_u32_e32 v72, 16, v83
	v_add3_u32 v64, s25, v65, v64
	v_lshlrev_b32_e32 v73, 7, v72
	v_lshrrev_b32_e32 v72, 2, v72
	ds_read_b128 v[68:71], v70 offset:4096
	ds_read_b128 v[64:67], v64
	v_xor_b32_e32 v72, v72, v82
	v_lshlrev_b32_e32 v72, 4, v72
	v_and_b32_e32 v72, 0x70, v72
	v_add3_u32 v72, s25, v73, v72
	ds_read_b128 v[72:75], v72
	s_waitcnt lgkmcnt(1)
	global_store_dwordx4 v[80:81], v[64:67], off sc1
	s_nop 1
	v_add_u32_e32 v64, 16, v78
	v_ashrrev_i32_e32 v65, 31, v64
	v_lshlrev_b64 v[64:65], 14, v[64:65]
	v_lshl_add_u64 v[64:65], v[76:77], 0, v[64:65]
	s_waitcnt lgkmcnt(0)
	global_store_dwordx4 v[64:65], v[72:75], off sc1
	v_add_u32_e32 v64, 24, v83
	v_lshlrev_b32_e32 v65, 7, v64
	v_lshrrev_b32_e32 v64, 2, v64
	v_xor_b32_e32 v64, v64, v82
	v_add_u32_e32 v72, 24, v78
	v_lshlrev_b32_e32 v64, 4, v64
	v_ashrrev_i32_e32 v73, 31, v72
	v_and_b32_e32 v64, 0x70, v64
	v_lshlrev_b64 v[72:73], 14, v[72:73]
	v_add3_u32 v64, s25, v65, v64
	v_lshl_add_u64 v[80:81], v[76:77], 0, v[72:73]
	v_add_u32_e32 v72, 40, v83
	ds_read_b128 v[64:67], v64
	v_lshlrev_b32_e32 v73, 7, v72
	v_lshrrev_b32_e32 v72, 2, v72
	v_xor_b32_e32 v72, v72, v82
	v_lshlrev_b32_e32 v72, 4, v72
	v_and_b32_e32 v72, 0x70, v72
	v_add3_u32 v72, s25, v73, v72
	ds_read_b128 v[72:75], v72
	s_waitcnt lgkmcnt(1)
	global_store_dwordx4 v[80:81], v[64:67], off sc1
	s_nop 1
	v_add_u32_e32 v64, 32, v78
	v_ashrrev_i32_e32 v65, 31, v64
	v_lshlrev_b64 v[64:65], 14, v[64:65]
	v_lshl_add_u64 v[64:65], v[76:77], 0, v[64:65]
	global_store_dwordx4 v[64:65], v[68:71], off sc1
	v_add_u32_e32 v64, 40, v78
	v_ashrrev_i32_e32 v65, 31, v64
	v_lshlrev_b64 v[64:65], 14, v[64:65]
	v_lshl_add_u64 v[64:65], v[76:77], 0, v[64:65]
	s_waitcnt lgkmcnt(0)
	global_store_dwordx4 v[64:65], v[72:75], off sc1
	v_add_u32_e32 v64, 48, v83
	v_lshlrev_b32_e32 v65, 7, v64
	v_lshrrev_b32_e32 v64, 2, v64
	v_add_u32_e32 v68, 48, v78
	v_xor_b32_e32 v64, v64, v82
	v_ashrrev_i32_e32 v69, 31, v68
	v_lshlrev_b32_e32 v64, 4, v64
	v_lshlrev_b64 v[68:69], 14, v[68:69]
	v_and_b32_e32 v64, 0x70, v64
	v_lshl_add_u64 v[72:73], v[76:77], 0, v[68:69]
	v_add_u32_e32 v68, 56, v83
	v_add3_u32 v64, s25, v65, v64
	v_lshlrev_b32_e32 v69, 7, v68
	v_lshrrev_b32_e32 v68, 2, v68
	ds_read_b128 v[64:67], v64
	v_xor_b32_e32 v68, v68, v82
	v_lshlrev_b32_e32 v68, 4, v68
	v_and_b32_e32 v68, 0x70, v68
	v_add3_u32 v68, s25, v69, v68
	ds_read_b128 v[68:71], v68
	s_waitcnt lgkmcnt(1)
	global_store_dwordx4 v[72:73], v[64:67], off sc1
	s_nop 1
	v_add_u32_e32 v64, 56, v78
	v_ashrrev_i32_e32 v65, 31, v64
	v_lshlrev_b64 v[64:65], 14, v[64:65]
	v_lshl_add_u64 v[64:65], v[76:77], 0, v[64:65]
	s_waitcnt lgkmcnt(0)
	global_store_dwordx4 v[64:65], v[68:71], off sc1
	s_waitcnt lgkmcnt(0)
	s_branch .LBB0_335
